# peel + all s_setprio removed from the 7 GEMM K-loops (priority flips were costing issue slots; load segment is co-critical)
# speedup vs baseline: 1.0071x; 1.0071x over previous
.LBB0_296:
	s_ashr_i32 s23, s22, 31
	s_lshl_b64 s[56:57], s[22:23], 21
	s_add_u32 s72, s2, s56
	s_addc_u32 s73, s3, s57
	s_and_b64 s[56:57], s[4:5], exec
	s_cselect_b32 s23, s73, s81
	s_cselect_b32 s56, s72, s80
	s_ashr_i32 s21, s20, 31
	s_lshl_b64 s[60:61], s[20:21], 20
	s_add_u32 s74, s14, s60
	s_addc_u32 s75, s15, s61
	s_and_b64 s[60:61], s[4:5], exec
	s_cselect_b32 s21, s75, s83
	s_cselect_b32 s57, s74, s82
	s_add_u32 s80, s80, 0x100080
	s_addc_u32 s81, s81, 0
	s_add_u32 s60, s82, 0x100
	s_addc_u32 s61, s83, 0
	s_mov_b32 s68, -2
	s_add_u32 s67, s80, 0xfff00080
	s_addc_u32 s69, s81, -1
	s_add_i32 s70, 0, 0x10000
	s_cmp_eq_u32 s68, 28
	s_cselect_b32 s85, s23, s69
	s_cselect_b32 s84, s56, s67
	s_cselect_b32 s83, s21, s61
	s_cselect_b32 s82, s57, s60
	s_add_i32 s67, 0, 0x14000
	v_add_u32_e32 v140, s70, v168
	v_add_u32_e32 v166, s67, v168
	ds_read_b128 v[80:83], v140
	ds_read_b128 v[116:119], v140 offset:1024
	ds_read_b128 v[136:139], v140 offset:2048
	ds_read_b128 v[140:143], v140 offset:3072
	ds_read_b128 v[158:161], v166
	ds_read_b128 v[162:165], v166 offset:1024
	ds_read_b128 v[170:173], v166 offset:2048
	ds_read_b128 v[174:177], v166 offset:3072
	v_lshl_add_u64 v[166:167], s[80:81], 0, v[154:155]
	s_add_i32 m0, s26, 0xc000
	ds_read_b128 v[178:181], v169
	ds_read_b128 v[182:185], v169 offset:1024
	ds_read_b128 v[186:189], v169 offset:2048
	ds_read_b128 v[190:193], v169 offset:3072
	ds_read_b128 v[194:197], v169 offset:4096
	ds_read_b128 v[198:201], v169 offset:5120
	ds_read_b128 v[202:205], v169 offset:6144
	ds_read_b128 v[206:209], v169 offset:7168
	global_load_lds_dwordx4 v[166:167], off
	v_lshl_add_u64 v[166:167], s[80:81], 0, v[156:157]
	s_add_i32 m0, s26, 0xe000
	s_nop 0
	global_load_lds_dwordx4 v[166:167], off
	s_waitcnt vmcnt(8)
	s_waitcnt lgkmcnt(0)
	s_barrier
	s_waitcnt lgkmcnt(0)
	v_mfma_f32_16x16x32_bf16 v[132:135], v[80:83], v[178:181], 0
	v_mfma_f32_16x16x32_bf16 v[128:131], v[136:139], v[178:181], 0
	v_mfma_f32_16x16x32_bf16 v[112:115], v[80:83], v[186:189], 0
	v_mfma_f32_16x16x32_bf16 v[108:111], v[136:139], v[186:189], 0
	v_mfma_f32_16x16x32_bf16 v[96:99], v[80:83], v[194:197], 0
	v_mfma_f32_16x16x32_bf16 v[92:95], v[136:139], v[194:197], 0
	v_mfma_f32_16x16x32_bf16 v[76:79], v[80:83], v[202:205], 0
	v_mfma_f32_16x16x32_bf16 v[72:75], v[136:139], v[202:205], 0
	v_mfma_f32_16x16x32_bf16 v[132:135], v[116:119], v[182:185], v[132:135]
	v_mfma_f32_16x16x32_bf16 v[128:131], v[140:143], v[182:185], v[128:131]
	v_mfma_f32_16x16x32_bf16 v[112:115], v[116:119], v[190:193], v[112:115]
	v_mfma_f32_16x16x32_bf16 v[108:111], v[140:143], v[190:193], v[108:111]
	v_mfma_f32_16x16x32_bf16 v[96:99], v[116:119], v[198:201], v[96:99]
	v_mfma_f32_16x16x32_bf16 v[92:95], v[140:143], v[198:201], v[92:95]
	v_mfma_f32_16x16x32_bf16 v[76:79], v[116:119], v[206:209], v[76:79]
	v_mfma_f32_16x16x32_bf16 v[72:75], v[140:143], v[206:209], v[72:75]
	v_mfma_f32_16x16x32_bf16 v[124:127], v[158:161], v[178:181], 0
	v_mfma_f32_16x16x32_bf16 v[120:123], v[170:173], v[178:181], 0
	v_mfma_f32_16x16x32_bf16 v[104:107], v[158:161], v[186:189], 0
	v_mfma_f32_16x16x32_bf16 v[100:103], v[170:173], v[186:189], 0
	v_mfma_f32_16x16x32_bf16 v[88:91], v[158:161], v[194:197], 0
	v_mfma_f32_16x16x32_bf16 v[84:87], v[170:173], v[194:197], 0
	v_mfma_f32_16x16x32_bf16 v[68:71], v[158:161], v[202:205], 0
	v_mfma_f32_16x16x32_bf16 v[64:67], v[170:173], v[202:205], 0
	v_mfma_f32_16x16x32_bf16 v[124:127], v[162:165], v[182:185], v[124:127]
	v_mfma_f32_16x16x32_bf16 v[120:123], v[174:177], v[182:185], v[120:123]
	v_mfma_f32_16x16x32_bf16 v[104:107], v[162:165], v[190:193], v[104:107]
	v_mfma_f32_16x16x32_bf16 v[100:103], v[174:177], v[190:193], v[100:103]
	v_mfma_f32_16x16x32_bf16 v[88:91], v[162:165], v[198:201], v[88:91]
	v_mfma_f32_16x16x32_bf16 v[84:87], v[174:177], v[198:201], v[84:87]
	v_mfma_f32_16x16x32_bf16 v[68:71], v[162:165], v[206:209], v[68:71]
	v_mfma_f32_16x16x32_bf16 v[64:67], v[174:177], v[206:209], v[64:67]
	s_barrier
	s_add_i32 s69, s70, s24
	v_lshl_add_u64 v[166:167], s[82:83], 0, v[146:147]
	s_mov_b32 m0, s69
	ds_read_b128 v[178:181], v169 offset:16384
	ds_read_b128 v[182:185], v169 offset:17408
	ds_read_b128 v[186:189], v169 offset:18432
	ds_read_b128 v[190:193], v169 offset:19456
	ds_read_b128 v[194:197], v169 offset:20480
	ds_read_b128 v[198:201], v169 offset:21504
	ds_read_b128 v[202:205], v169 offset:22528
	ds_read_b128 v[206:209], v169 offset:23552
	global_load_lds_dwordx4 v[166:167], off
	s_add_i32 m0, s69, 0x2000
	s_add_u32 s70, s82, 0x80000
	v_lshl_add_u64 v[210:211], s[82:83], 0, v[150:151]
	s_addc_u32 s71, s83, 0
	s_add_i32 s67, s67, s24
	global_load_lds_dwordx4 v[210:211], off
	v_lshl_add_u64 v[212:213], s[70:71], 0, v[146:147]
	s_mov_b32 m0, s67
	v_lshl_add_u64 v[214:215], s[84:85], 0, v[148:149]
	global_load_lds_dwordx4 v[212:213], off
	v_lshl_add_u64 v[212:213], s[70:71], 0, v[150:151]
	s_add_i32 m0, s67, 0x2000
	s_nop 0
	global_load_lds_dwordx4 v[212:213], off
	v_lshl_add_u64 v[212:213], s[84:85], 0, v[144:145]
	s_mov_b32 m0, s26
	s_nop 0
	global_load_lds_dwordx4 v[212:213], off
	s_mov_b32 m0, s28
	s_nop 0
	global_load_lds_dwordx4 v[214:215], off
	s_waitcnt vmcnt(8)
	s_waitcnt lgkmcnt(0)
	s_barrier
	s_waitcnt lgkmcnt(0)
	v_mfma_f32_16x16x32_bf16 v[60:63], v[80:83], v[178:181], 0
	v_mfma_f32_16x16x32_bf16 v[56:59], v[136:139], v[178:181], 0
	v_mfma_f32_16x16x32_bf16 v[44:47], v[80:83], v[186:189], 0
	v_mfma_f32_16x16x32_bf16 v[40:43], v[136:139], v[186:189], 0
	v_mfma_f32_16x16x32_bf16 v[28:31], v[80:83], v[194:197], 0
	v_mfma_f32_16x16x32_bf16 v[24:27], v[136:139], v[194:197], 0
	v_mfma_f32_16x16x32_bf16 v[12:15], v[80:83], v[202:205], 0
	v_mfma_f32_16x16x32_bf16 v[8:11], v[136:139], v[202:205], 0
	v_mfma_f32_16x16x32_bf16 v[60:63], v[116:119], v[182:185], v[60:63]
	v_mfma_f32_16x16x32_bf16 v[56:59], v[140:143], v[182:185], v[56:59]
	v_mfma_f32_16x16x32_bf16 v[44:47], v[116:119], v[190:193], v[44:47]
	v_mfma_f32_16x16x32_bf16 v[40:43], v[140:143], v[190:193], v[40:43]
	v_mfma_f32_16x16x32_bf16 v[28:31], v[116:119], v[198:201], v[28:31]
	v_mfma_f32_16x16x32_bf16 v[24:27], v[140:143], v[198:201], v[24:27]
	v_mfma_f32_16x16x32_bf16 v[12:15], v[116:119], v[206:209], v[12:15]
	v_mfma_f32_16x16x32_bf16 v[8:11], v[140:143], v[206:209], v[8:11]
	v_mfma_f32_16x16x32_bf16 v[52:55], v[158:161], v[178:181], 0
	v_mfma_f32_16x16x32_bf16 v[48:51], v[170:173], v[178:181], 0
	v_mfma_f32_16x16x32_bf16 v[36:39], v[158:161], v[186:189], 0
	v_mfma_f32_16x16x32_bf16 v[32:35], v[170:173], v[186:189], 0
	v_mfma_f32_16x16x32_bf16 v[20:23], v[158:161], v[194:197], 0
	v_mfma_f32_16x16x32_bf16 v[16:19], v[170:173], v[194:197], 0
	v_mfma_f32_16x16x32_bf16 v[4:7], v[158:161], v[202:205], 0
	v_mfma_f32_16x16x32_bf16 v[0:3], v[170:173], v[202:205], 0
	v_mfma_f32_16x16x32_bf16 v[52:55], v[162:165], v[182:185], v[52:55]
	v_mfma_f32_16x16x32_bf16 v[48:51], v[174:177], v[182:185], v[48:51]
	v_mfma_f32_16x16x32_bf16 v[36:39], v[162:165], v[190:193], v[36:39]
	v_mfma_f32_16x16x32_bf16 v[32:35], v[174:177], v[190:193], v[32:35]
	v_mfma_f32_16x16x32_bf16 v[20:23], v[162:165], v[198:201], v[20:23]
	v_mfma_f32_16x16x32_bf16 v[16:19], v[174:177], v[198:201], v[16:19]
	v_mfma_f32_16x16x32_bf16 v[4:7], v[162:165], v[206:209], v[4:7]
	v_mfma_f32_16x16x32_bf16 v[0:3], v[174:177], v[206:209], v[0:3]
	s_barrier
	s_add_i32 s67, 0, 0x18000
	s_add_i32 s69, 0, 0x1c000
	v_add_u32_e32 v140, s67, v168
	v_add_u32_e32 v174, s69, v168
	ds_read_b128 v[80:83], v140
	ds_read_b128 v[116:119], v140 offset:1024
	ds_read_b128 v[136:139], v140 offset:2048
	ds_read_b128 v[140:143], v140 offset:3072
	ds_read_b128 v[158:161], v174
	ds_read_b128 v[162:165], v174 offset:1024
	ds_read_b128 v[170:173], v174 offset:2048
	ds_read_b128 v[174:177], v174 offset:3072
	s_add_u32 s70, s84, 0x100000
	s_addc_u32 s71, s85, 0
	s_mov_b32 m0, s29
	v_lshl_add_u64 v[218:219], s[70:71], 0, v[144:145]
	ds_read_b128 v[178:181], v169 offset:32768
	ds_read_b128 v[182:185], v169 offset:33792
	ds_read_b128 v[186:189], v169 offset:34816
	ds_read_b128 v[190:193], v169 offset:35840
	ds_read_b128 v[194:197], v169 offset:36864
	ds_read_b128 v[198:201], v169 offset:37888
	ds_read_b128 v[202:205], v169 offset:38912
	ds_read_b128 v[206:209], v169 offset:39936
	global_load_lds_dwordx4 v[218:219], off
	v_lshl_add_u64 v[218:219], s[70:71], 0, v[148:149]
	s_mov_b32 m0, s34
	s_nop 0
	global_load_lds_dwordx4 v[218:219], off
	s_waitcnt vmcnt(8)
	s_waitcnt lgkmcnt(0)
	s_barrier
	s_waitcnt lgkmcnt(0)
	v_mfma_f32_16x16x32_bf16 v[132:135], v[80:83], v[178:181], v[132:135]
	v_mfma_f32_16x16x32_bf16 v[128:131], v[136:139], v[178:181], v[128:131]
	v_mfma_f32_16x16x32_bf16 v[112:115], v[80:83], v[186:189], v[112:115]
	v_mfma_f32_16x16x32_bf16 v[108:111], v[136:139], v[186:189], v[108:111]
	v_mfma_f32_16x16x32_bf16 v[96:99], v[80:83], v[194:197], v[96:99]
	v_mfma_f32_16x16x32_bf16 v[92:95], v[136:139], v[194:197], v[92:95]
	v_mfma_f32_16x16x32_bf16 v[76:79], v[80:83], v[202:205], v[76:79]
	v_mfma_f32_16x16x32_bf16 v[72:75], v[136:139], v[202:205], v[72:75]
	v_mfma_f32_16x16x32_bf16 v[132:135], v[116:119], v[182:185], v[132:135]
	v_mfma_f32_16x16x32_bf16 v[128:131], v[140:143], v[182:185], v[128:131]
	v_mfma_f32_16x16x32_bf16 v[112:115], v[116:119], v[190:193], v[112:115]
	v_mfma_f32_16x16x32_bf16 v[108:111], v[140:143], v[190:193], v[108:111]
	v_mfma_f32_16x16x32_bf16 v[96:99], v[116:119], v[198:201], v[96:99]
	v_mfma_f32_16x16x32_bf16 v[92:95], v[140:143], v[198:201], v[92:95]
	v_mfma_f32_16x16x32_bf16 v[76:79], v[116:119], v[206:209], v[76:79]
	v_mfma_f32_16x16x32_bf16 v[72:75], v[140:143], v[206:209], v[72:75]
	v_mfma_f32_16x16x32_bf16 v[124:127], v[158:161], v[178:181], v[124:127]
	v_mfma_f32_16x16x32_bf16 v[120:123], v[170:173], v[178:181], v[120:123]
	v_mfma_f32_16x16x32_bf16 v[104:107], v[158:161], v[186:189], v[104:107]
	v_mfma_f32_16x16x32_bf16 v[100:103], v[170:173], v[186:189], v[100:103]
	v_mfma_f32_16x16x32_bf16 v[88:91], v[158:161], v[194:197], v[88:91]
	v_mfma_f32_16x16x32_bf16 v[84:87], v[170:173], v[194:197], v[84:87]
	v_mfma_f32_16x16x32_bf16 v[68:71], v[158:161], v[202:205], v[68:71]
	v_mfma_f32_16x16x32_bf16 v[64:67], v[170:173], v[202:205], v[64:67]
	v_mfma_f32_16x16x32_bf16 v[124:127], v[162:165], v[182:185], v[124:127]
	v_mfma_f32_16x16x32_bf16 v[120:123], v[174:177], v[182:185], v[120:123]
	v_mfma_f32_16x16x32_bf16 v[104:107], v[162:165], v[190:193], v[104:107]
	v_mfma_f32_16x16x32_bf16 v[100:103], v[174:177], v[190:193], v[100:103]
	v_mfma_f32_16x16x32_bf16 v[88:91], v[162:165], v[198:201], v[88:91]
	v_mfma_f32_16x16x32_bf16 v[84:87], v[174:177], v[198:201], v[84:87]
	v_mfma_f32_16x16x32_bf16 v[68:71], v[162:165], v[206:209], v[68:71]
	v_mfma_f32_16x16x32_bf16 v[64:67], v[174:177], v[206:209], v[64:67]
	s_barrier
	s_add_i32 s67, s67, s24
	v_lshl_add_u64 v[166:167], v[166:167], 0, s[30:31]
	s_mov_b32 m0, s67
	ds_read_b128 v[178:181], v169 offset:49152
	ds_read_b128 v[182:185], v169 offset:50176
	ds_read_b128 v[186:189], v169 offset:51200
	ds_read_b128 v[190:193], v169 offset:52224
	ds_read_b128 v[194:197], v169 offset:53248
	ds_read_b128 v[198:201], v169 offset:54272
	ds_read_b128 v[202:205], v169 offset:55296
	ds_read_b128 v[206:209], v169 offset:56320
	global_load_lds_dwordx4 v[166:167], off
	s_add_i32 m0, s67, 0x2000
	s_add_u32 s70, s82, 0x80080
	v_lshl_add_u64 v[166:167], v[210:211], 0, s[30:31]
	s_addc_u32 s71, s83, 0
	s_add_i32 s67, s69, s24
	global_load_lds_dwordx4 v[166:167], off
	v_lshl_add_u64 v[166:167], s[70:71], 0, v[146:147]
	s_mov_b32 m0, s67
	s_nop 0
	global_load_lds_dwordx4 v[166:167], off
	v_lshl_add_u64 v[166:167], s[70:71], 0, v[150:151]
	s_add_i32 m0, s67, 0x2000
	s_nop 0
	global_load_lds_dwordx4 v[166:167], off
	v_lshl_add_u64 v[166:167], v[212:213], 0, s[30:31]
	s_mov_b32 m0, s39
	s_nop 0
	global_load_lds_dwordx4 v[166:167], off
	v_lshl_add_u64 v[166:167], v[214:215], 0, s[30:31]
	s_mov_b32 m0, s40
	s_nop 0
	global_load_lds_dwordx4 v[166:167], off
	s_waitcnt vmcnt(8)
	s_waitcnt lgkmcnt(0)
	s_barrier
	s_waitcnt lgkmcnt(0)
	v_mfma_f32_16x16x32_bf16 v[60:63], v[80:83], v[178:181], v[60:63]
	v_mfma_f32_16x16x32_bf16 v[56:59], v[136:139], v[178:181], v[56:59]
	v_mfma_f32_16x16x32_bf16 v[44:47], v[80:83], v[186:189], v[44:47]
	v_mfma_f32_16x16x32_bf16 v[40:43], v[136:139], v[186:189], v[40:43]
	v_mfma_f32_16x16x32_bf16 v[28:31], v[80:83], v[194:197], v[28:31]
	v_mfma_f32_16x16x32_bf16 v[24:27], v[136:139], v[194:197], v[24:27]
	v_mfma_f32_16x16x32_bf16 v[12:15], v[80:83], v[202:205], v[12:15]
	v_mfma_f32_16x16x32_bf16 v[8:11], v[136:139], v[202:205], v[8:11]
	v_mfma_f32_16x16x32_bf16 v[60:63], v[116:119], v[182:185], v[60:63]
	v_mfma_f32_16x16x32_bf16 v[56:59], v[140:143], v[182:185], v[56:59]
	v_mfma_f32_16x16x32_bf16 v[44:47], v[116:119], v[190:193], v[44:47]
	v_mfma_f32_16x16x32_bf16 v[40:43], v[140:143], v[190:193], v[40:43]
	v_mfma_f32_16x16x32_bf16 v[28:31], v[116:119], v[198:201], v[28:31]
	v_mfma_f32_16x16x32_bf16 v[24:27], v[140:143], v[198:201], v[24:27]
	v_mfma_f32_16x16x32_bf16 v[12:15], v[116:119], v[206:209], v[12:15]
	v_mfma_f32_16x16x32_bf16 v[8:11], v[140:143], v[206:209], v[8:11]
	v_mfma_f32_16x16x32_bf16 v[52:55], v[158:161], v[178:181], v[52:55]
	v_mfma_f32_16x16x32_bf16 v[48:51], v[170:173], v[178:181], v[48:51]
	v_mfma_f32_16x16x32_bf16 v[36:39], v[158:161], v[186:189], v[36:39]
	v_mfma_f32_16x16x32_bf16 v[32:35], v[170:173], v[186:189], v[32:35]
	v_mfma_f32_16x16x32_bf16 v[20:23], v[158:161], v[194:197], v[20:23]
	v_mfma_f32_16x16x32_bf16 v[16:19], v[170:173], v[194:197], v[16:19]
	v_mfma_f32_16x16x32_bf16 v[4:7], v[158:161], v[202:205], v[4:7]
	v_mfma_f32_16x16x32_bf16 v[0:3], v[170:173], v[202:205], v[0:3]
	v_mfma_f32_16x16x32_bf16 v[52:55], v[162:165], v[182:185], v[52:55]
	v_mfma_f32_16x16x32_bf16 v[48:51], v[174:177], v[182:185], v[48:51]
	v_mfma_f32_16x16x32_bf16 v[36:39], v[162:165], v[190:193], v[36:39]
	v_mfma_f32_16x16x32_bf16 v[32:35], v[174:177], v[190:193], v[32:35]
	v_mfma_f32_16x16x32_bf16 v[20:23], v[162:165], v[198:201], v[20:23]
	v_mfma_f32_16x16x32_bf16 v[16:19], v[174:177], v[198:201], v[16:19]
	v_mfma_f32_16x16x32_bf16 v[4:7], v[162:165], v[206:209], v[4:7]
	v_mfma_f32_16x16x32_bf16 v[0:3], v[174:177], v[206:209], v[0:3]
	s_barrier
	s_add_i32 s68, s68, 2
	s_add_u32 s80, s80, 0x100
	s_addc_u32 s81, s81, 0
	s_add_u32 s60, s60, 0x100
	s_addc_u32 s61, s61, 0
.LBB0_297:
	s_add_u32 s67, s80, 0xfff00080
	s_addc_u32 s69, s81, -1
	s_add_i32 s70, 0, 0x10000
	s_cmp_eq_u32 s68, 28
	s_cselect_b32 s85, s23, s69
	s_cselect_b32 s84, s56, s67
	s_cselect_b32 s83, s21, s61
	s_cselect_b32 s82, s57, s60
	s_add_i32 s67, 0, 0x14000
	v_add_u32_e32 v140, s70, v168
	v_add_u32_e32 v166, s67, v168
	ds_read_b128 v[80:83], v140
	ds_read_b128 v[116:119], v140 offset:1024
	ds_read_b128 v[136:139], v140 offset:2048
	ds_read_b128 v[140:143], v140 offset:3072
	ds_read_b128 v[158:161], v166
	ds_read_b128 v[162:165], v166 offset:1024
	ds_read_b128 v[170:173], v166 offset:2048
	ds_read_b128 v[174:177], v166 offset:3072
	v_lshl_add_u64 v[166:167], s[80:81], 0, v[154:155]
	s_add_i32 m0, s26, 0xc000
	ds_read_b128 v[178:181], v169
	ds_read_b128 v[182:185], v169 offset:1024
	ds_read_b128 v[186:189], v169 offset:2048
	ds_read_b128 v[190:193], v169 offset:3072
	ds_read_b128 v[194:197], v169 offset:4096
	ds_read_b128 v[198:201], v169 offset:5120
	ds_read_b128 v[202:205], v169 offset:6144
	ds_read_b128 v[206:209], v169 offset:7168
	global_load_lds_dwordx4 v[166:167], off
	v_lshl_add_u64 v[166:167], s[80:81], 0, v[156:157]
	s_add_i32 m0, s26, 0xe000
	s_nop 0
	global_load_lds_dwordx4 v[166:167], off
	s_waitcnt vmcnt(8)
	s_waitcnt lgkmcnt(0)
	s_barrier
	s_waitcnt lgkmcnt(0)
	v_mfma_f32_16x16x32_bf16 v[132:135], v[80:83], v[178:181], v[132:135]
	v_mfma_f32_16x16x32_bf16 v[128:131], v[136:139], v[178:181], v[128:131]
	v_mfma_f32_16x16x32_bf16 v[112:115], v[80:83], v[186:189], v[112:115]
	v_mfma_f32_16x16x32_bf16 v[108:111], v[136:139], v[186:189], v[108:111]
	v_mfma_f32_16x16x32_bf16 v[96:99], v[80:83], v[194:197], v[96:99]
	v_mfma_f32_16x16x32_bf16 v[92:95], v[136:139], v[194:197], v[92:95]
	v_mfma_f32_16x16x32_bf16 v[76:79], v[80:83], v[202:205], v[76:79]
	v_mfma_f32_16x16x32_bf16 v[72:75], v[136:139], v[202:205], v[72:75]
	v_mfma_f32_16x16x32_bf16 v[132:135], v[116:119], v[182:185], v[132:135]
	v_mfma_f32_16x16x32_bf16 v[128:131], v[140:143], v[182:185], v[128:131]
	v_mfma_f32_16x16x32_bf16 v[112:115], v[116:119], v[190:193], v[112:115]
	v_mfma_f32_16x16x32_bf16 v[108:111], v[140:143], v[190:193], v[108:111]
	v_mfma_f32_16x16x32_bf16 v[96:99], v[116:119], v[198:201], v[96:99]
	v_mfma_f32_16x16x32_bf16 v[92:95], v[140:143], v[198:201], v[92:95]
	v_mfma_f32_16x16x32_bf16 v[76:79], v[116:119], v[206:209], v[76:79]
	v_mfma_f32_16x16x32_bf16 v[72:75], v[140:143], v[206:209], v[72:75]
	v_mfma_f32_16x16x32_bf16 v[124:127], v[158:161], v[178:181], v[124:127]
	v_mfma_f32_16x16x32_bf16 v[120:123], v[170:173], v[178:181], v[120:123]
	v_mfma_f32_16x16x32_bf16 v[104:107], v[158:161], v[186:189], v[104:107]
	v_mfma_f32_16x16x32_bf16 v[100:103], v[170:173], v[186:189], v[100:103]
	v_mfma_f32_16x16x32_bf16 v[88:91], v[158:161], v[194:197], v[88:91]
	v_mfma_f32_16x16x32_bf16 v[84:87], v[170:173], v[194:197], v[84:87]
	v_mfma_f32_16x16x32_bf16 v[68:71], v[158:161], v[202:205], v[68:71]
	v_mfma_f32_16x16x32_bf16 v[64:67], v[170:173], v[202:205], v[64:67]
	v_mfma_f32_16x16x32_bf16 v[124:127], v[162:165], v[182:185], v[124:127]
	v_mfma_f32_16x16x32_bf16 v[120:123], v[174:177], v[182:185], v[120:123]
	v_mfma_f32_16x16x32_bf16 v[104:107], v[162:165], v[190:193], v[104:107]
	v_mfma_f32_16x16x32_bf16 v[100:103], v[174:177], v[190:193], v[100:103]
	v_mfma_f32_16x16x32_bf16 v[88:91], v[162:165], v[198:201], v[88:91]
	v_mfma_f32_16x16x32_bf16 v[84:87], v[174:177], v[198:201], v[84:87]
	v_mfma_f32_16x16x32_bf16 v[68:71], v[162:165], v[206:209], v[68:71]
	v_mfma_f32_16x16x32_bf16 v[64:67], v[174:177], v[206:209], v[64:67]
	s_barrier
	s_add_i32 s69, s70, s24
	v_lshl_add_u64 v[166:167], s[82:83], 0, v[146:147]
	s_mov_b32 m0, s69
	ds_read_b128 v[178:181], v169 offset:16384
	ds_read_b128 v[182:185], v169 offset:17408
	ds_read_b128 v[186:189], v169 offset:18432
	ds_read_b128 v[190:193], v169 offset:19456
	ds_read_b128 v[194:197], v169 offset:20480
	ds_read_b128 v[198:201], v169 offset:21504
	ds_read_b128 v[202:205], v169 offset:22528
	ds_read_b128 v[206:209], v169 offset:23552
	global_load_lds_dwordx4 v[166:167], off
	s_add_i32 m0, s69, 0x2000
	s_add_u32 s70, s82, 0x80000
	v_lshl_add_u64 v[210:211], s[82:83], 0, v[150:151]
	s_addc_u32 s71, s83, 0
	s_add_i32 s67, s67, s24
	global_load_lds_dwordx4 v[210:211], off
	v_lshl_add_u64 v[212:213], s[70:71], 0, v[146:147]
	s_mov_b32 m0, s67
	v_lshl_add_u64 v[214:215], s[84:85], 0, v[148:149]
	global_load_lds_dwordx4 v[212:213], off
	v_lshl_add_u64 v[212:213], s[70:71], 0, v[150:151]
	s_add_i32 m0, s67, 0x2000
	s_nop 0
	global_load_lds_dwordx4 v[212:213], off
	v_lshl_add_u64 v[212:213], s[84:85], 0, v[144:145]
	s_mov_b32 m0, s26
	s_nop 0
	global_load_lds_dwordx4 v[212:213], off
	s_mov_b32 m0, s28
	s_nop 0
	global_load_lds_dwordx4 v[214:215], off
	s_waitcnt vmcnt(8)
	s_waitcnt lgkmcnt(0)
	s_barrier
	s_waitcnt lgkmcnt(0)
	v_mfma_f32_16x16x32_bf16 v[60:63], v[80:83], v[178:181], v[60:63]
	v_mfma_f32_16x16x32_bf16 v[56:59], v[136:139], v[178:181], v[56:59]
	v_mfma_f32_16x16x32_bf16 v[44:47], v[80:83], v[186:189], v[44:47]
	v_mfma_f32_16x16x32_bf16 v[40:43], v[136:139], v[186:189], v[40:43]
	v_mfma_f32_16x16x32_bf16 v[28:31], v[80:83], v[194:197], v[28:31]
	v_mfma_f32_16x16x32_bf16 v[24:27], v[136:139], v[194:197], v[24:27]
	v_mfma_f32_16x16x32_bf16 v[12:15], v[80:83], v[202:205], v[12:15]
	v_mfma_f32_16x16x32_bf16 v[8:11], v[136:139], v[202:205], v[8:11]
	v_mfma_f32_16x16x32_bf16 v[60:63], v[116:119], v[182:185], v[60:63]
	v_mfma_f32_16x16x32_bf16 v[56:59], v[140:143], v[182:185], v[56:59]
	v_mfma_f32_16x16x32_bf16 v[44:47], v[116:119], v[190:193], v[44:47]
	v_mfma_f32_16x16x32_bf16 v[40:43], v[140:143], v[190:193], v[40:43]
	v_mfma_f32_16x16x32_bf16 v[28:31], v[116:119], v[198:201], v[28:31]
	v_mfma_f32_16x16x32_bf16 v[24:27], v[140:143], v[198:201], v[24:27]
	v_mfma_f32_16x16x32_bf16 v[12:15], v[116:119], v[206:209], v[12:15]
	v_mfma_f32_16x16x32_bf16 v[8:11], v[140:143], v[206:209], v[8:11]
	v_mfma_f32_16x16x32_bf16 v[52:55], v[158:161], v[178:181], v[52:55]
	v_mfma_f32_16x16x32_bf16 v[48:51], v[170:173], v[178:181], v[48:51]
	v_mfma_f32_16x16x32_bf16 v[36:39], v[158:161], v[186:189], v[36:39]
	v_mfma_f32_16x16x32_bf16 v[32:35], v[170:173], v[186:189], v[32:35]
	v_mfma_f32_16x16x32_bf16 v[20:23], v[158:161], v[194:197], v[20:23]
	v_mfma_f32_16x16x32_bf16 v[16:19], v[170:173], v[194:197], v[16:19]
	v_mfma_f32_16x16x32_bf16 v[4:7], v[158:161], v[202:205], v[4:7]
	v_mfma_f32_16x16x32_bf16 v[0:3], v[170:173], v[202:205], v[0:3]
	v_mfma_f32_16x16x32_bf16 v[52:55], v[162:165], v[182:185], v[52:55]
	v_mfma_f32_16x16x32_bf16 v[48:51], v[174:177], v[182:185], v[48:51]
	v_mfma_f32_16x16x32_bf16 v[36:39], v[162:165], v[190:193], v[36:39]
	v_mfma_f32_16x16x32_bf16 v[32:35], v[174:177], v[190:193], v[32:35]
	v_mfma_f32_16x16x32_bf16 v[20:23], v[162:165], v[198:201], v[20:23]
	v_mfma_f32_16x16x32_bf16 v[16:19], v[174:177], v[198:201], v[16:19]
	v_mfma_f32_16x16x32_bf16 v[4:7], v[162:165], v[206:209], v[4:7]
	v_mfma_f32_16x16x32_bf16 v[0:3], v[174:177], v[206:209], v[0:3]
	s_barrier
	s_add_i32 s67, 0, 0x18000
	s_add_i32 s69, 0, 0x1c000
	v_add_u32_e32 v140, s67, v168
	v_add_u32_e32 v174, s69, v168
	ds_read_b128 v[80:83], v140
	ds_read_b128 v[116:119], v140 offset:1024
	ds_read_b128 v[136:139], v140 offset:2048
	ds_read_b128 v[140:143], v140 offset:3072
	ds_read_b128 v[158:161], v174
	ds_read_b128 v[162:165], v174 offset:1024
	ds_read_b128 v[170:173], v174 offset:2048
	ds_read_b128 v[174:177], v174 offset:3072
	s_add_u32 s70, s84, 0x100000
	s_addc_u32 s71, s85, 0
	s_mov_b32 m0, s29
	v_lshl_add_u64 v[218:219], s[70:71], 0, v[144:145]
	ds_read_b128 v[178:181], v169 offset:32768
	ds_read_b128 v[182:185], v169 offset:33792
	ds_read_b128 v[186:189], v169 offset:34816
	ds_read_b128 v[190:193], v169 offset:35840
	ds_read_b128 v[194:197], v169 offset:36864
	ds_read_b128 v[198:201], v169 offset:37888
	ds_read_b128 v[202:205], v169 offset:38912
	ds_read_b128 v[206:209], v169 offset:39936
	global_load_lds_dwordx4 v[218:219], off
	v_lshl_add_u64 v[218:219], s[70:71], 0, v[148:149]
	s_mov_b32 m0, s34
	s_nop 0
	global_load_lds_dwordx4 v[218:219], off
	s_waitcnt vmcnt(8)
	s_waitcnt lgkmcnt(0)
	s_barrier
	s_waitcnt lgkmcnt(0)
	v_mfma_f32_16x16x32_bf16 v[132:135], v[80:83], v[178:181], v[132:135]
	v_mfma_f32_16x16x32_bf16 v[128:131], v[136:139], v[178:181], v[128:131]
	v_mfma_f32_16x16x32_bf16 v[112:115], v[80:83], v[186:189], v[112:115]
	v_mfma_f32_16x16x32_bf16 v[108:111], v[136:139], v[186:189], v[108:111]
	v_mfma_f32_16x16x32_bf16 v[96:99], v[80:83], v[194:197], v[96:99]
	v_mfma_f32_16x16x32_bf16 v[92:95], v[136:139], v[194:197], v[92:95]
	v_mfma_f32_16x16x32_bf16 v[76:79], v[80:83], v[202:205], v[76:79]
	v_mfma_f32_16x16x32_bf16 v[72:75], v[136:139], v[202:205], v[72:75]
	v_mfma_f32_16x16x32_bf16 v[132:135], v[116:119], v[182:185], v[132:135]
	v_mfma_f32_16x16x32_bf16 v[128:131], v[140:143], v[182:185], v[128:131]
	v_mfma_f32_16x16x32_bf16 v[112:115], v[116:119], v[190:193], v[112:115]
	v_mfma_f32_16x16x32_bf16 v[108:111], v[140:143], v[190:193], v[108:111]
	v_mfma_f32_16x16x32_bf16 v[96:99], v[116:119], v[198:201], v[96:99]
	v_mfma_f32_16x16x32_bf16 v[92:95], v[140:143], v[198:201], v[92:95]
	v_mfma_f32_16x16x32_bf16 v[76:79], v[116:119], v[206:209], v[76:79]
	v_mfma_f32_16x16x32_bf16 v[72:75], v[140:143], v[206:209], v[72:75]
	v_mfma_f32_16x16x32_bf16 v[124:127], v[158:161], v[178:181], v[124:127]
	v_mfma_f32_16x16x32_bf16 v[120:123], v[170:173], v[178:181], v[120:123]
	v_mfma_f32_16x16x32_bf16 v[104:107], v[158:161], v[186:189], v[104:107]
	v_mfma_f32_16x16x32_bf16 v[100:103], v[170:173], v[186:189], v[100:103]
	v_mfma_f32_16x16x32_bf16 v[88:91], v[158:161], v[194:197], v[88:91]
	v_mfma_f32_16x16x32_bf16 v[84:87], v[170:173], v[194:197], v[84:87]
	v_mfma_f32_16x16x32_bf16 v[68:71], v[158:161], v[202:205], v[68:71]
	v_mfma_f32_16x16x32_bf16 v[64:67], v[170:173], v[202:205], v[64:67]
	v_mfma_f32_16x16x32_bf16 v[124:127], v[162:165], v[182:185], v[124:127]
	v_mfma_f32_16x16x32_bf16 v[120:123], v[174:177], v[182:185], v[120:123]
	v_mfma_f32_16x16x32_bf16 v[104:107], v[162:165], v[190:193], v[104:107]
	v_mfma_f32_16x16x32_bf16 v[100:103], v[174:177], v[190:193], v[100:103]
	v_mfma_f32_16x16x32_bf16 v[88:91], v[162:165], v[198:201], v[88:91]
	v_mfma_f32_16x16x32_bf16 v[84:87], v[174:177], v[198:201], v[84:87]
	v_mfma_f32_16x16x32_bf16 v[68:71], v[162:165], v[206:209], v[68:71]
	v_mfma_f32_16x16x32_bf16 v[64:67], v[174:177], v[206:209], v[64:67]
	s_barrier
	s_add_i32 s67, s67, s24
	v_lshl_add_u64 v[166:167], v[166:167], 0, s[30:31]
	s_mov_b32 m0, s67
	ds_read_b128 v[178:181], v169 offset:49152
	ds_read_b128 v[182:185], v169 offset:50176
	ds_read_b128 v[186:189], v169 offset:51200
	ds_read_b128 v[190:193], v169 offset:52224
	ds_read_b128 v[194:197], v169 offset:53248
	ds_read_b128 v[198:201], v169 offset:54272
	ds_read_b128 v[202:205], v169 offset:55296
	ds_read_b128 v[206:209], v169 offset:56320
	global_load_lds_dwordx4 v[166:167], off
	s_add_i32 m0, s67, 0x2000
	s_add_u32 s70, s82, 0x80080
	v_lshl_add_u64 v[166:167], v[210:211], 0, s[30:31]
	s_addc_u32 s71, s83, 0
	s_add_i32 s67, s69, s24
	global_load_lds_dwordx4 v[166:167], off
	v_lshl_add_u64 v[166:167], s[70:71], 0, v[146:147]
	s_mov_b32 m0, s67
	s_nop 0
	global_load_lds_dwordx4 v[166:167], off
	v_lshl_add_u64 v[166:167], s[70:71], 0, v[150:151]
	s_add_i32 m0, s67, 0x2000
	s_nop 0
	global_load_lds_dwordx4 v[166:167], off
	v_lshl_add_u64 v[166:167], v[212:213], 0, s[30:31]
	s_mov_b32 m0, s39
	s_nop 0
	global_load_lds_dwordx4 v[166:167], off
	v_lshl_add_u64 v[166:167], v[214:215], 0, s[30:31]
	s_mov_b32 m0, s40
	s_nop 0
	global_load_lds_dwordx4 v[166:167], off
	s_waitcnt vmcnt(8)
	s_waitcnt lgkmcnt(0)
	s_barrier
	s_waitcnt lgkmcnt(0)
	v_mfma_f32_16x16x32_bf16 v[60:63], v[80:83], v[178:181], v[60:63]
	v_mfma_f32_16x16x32_bf16 v[56:59], v[136:139], v[178:181], v[56:59]
	v_mfma_f32_16x16x32_bf16 v[44:47], v[80:83], v[186:189], v[44:47]
	v_mfma_f32_16x16x32_bf16 v[40:43], v[136:139], v[186:189], v[40:43]
	v_mfma_f32_16x16x32_bf16 v[28:31], v[80:83], v[194:197], v[28:31]
	v_mfma_f32_16x16x32_bf16 v[24:27], v[136:139], v[194:197], v[24:27]
	v_mfma_f32_16x16x32_bf16 v[12:15], v[80:83], v[202:205], v[12:15]
	v_mfma_f32_16x16x32_bf16 v[8:11], v[136:139], v[202:205], v[8:11]
	v_mfma_f32_16x16x32_bf16 v[60:63], v[116:119], v[182:185], v[60:63]
	v_mfma_f32_16x16x32_bf16 v[56:59], v[140:143], v[182:185], v[56:59]
	v_mfma_f32_16x16x32_bf16 v[44:47], v[116:119], v[190:193], v[44:47]
	v_mfma_f32_16x16x32_bf16 v[40:43], v[140:143], v[190:193], v[40:43]
	v_mfma_f32_16x16x32_bf16 v[28:31], v[116:119], v[198:201], v[28:31]
	v_mfma_f32_16x16x32_bf16 v[24:27], v[140:143], v[198:201], v[24:27]
	v_mfma_f32_16x16x32_bf16 v[12:15], v[116:119], v[206:209], v[12:15]
	v_mfma_f32_16x16x32_bf16 v[8:11], v[140:143], v[206:209], v[8:11]
	v_mfma_f32_16x16x32_bf16 v[52:55], v[158:161], v[178:181], v[52:55]
	v_mfma_f32_16x16x32_bf16 v[48:51], v[170:173], v[178:181], v[48:51]
	v_mfma_f32_16x16x32_bf16 v[36:39], v[158:161], v[186:189], v[36:39]
	v_mfma_f32_16x16x32_bf16 v[32:35], v[170:173], v[186:189], v[32:35]
	v_mfma_f32_16x16x32_bf16 v[20:23], v[158:161], v[194:197], v[20:23]
	v_mfma_f32_16x16x32_bf16 v[16:19], v[170:173], v[194:197], v[16:19]
	v_mfma_f32_16x16x32_bf16 v[4:7], v[158:161], v[202:205], v[4:7]
	v_mfma_f32_16x16x32_bf16 v[0:3], v[170:173], v[202:205], v[0:3]
	v_mfma_f32_16x16x32_bf16 v[52:55], v[162:165], v[182:185], v[52:55]
	v_mfma_f32_16x16x32_bf16 v[48:51], v[174:177], v[182:185], v[48:51]
	v_mfma_f32_16x16x32_bf16 v[36:39], v[162:165], v[190:193], v[36:39]
	v_mfma_f32_16x16x32_bf16 v[32:35], v[174:177], v[190:193], v[32:35]
	v_mfma_f32_16x16x32_bf16 v[20:23], v[162:165], v[198:201], v[20:23]
	v_mfma_f32_16x16x32_bf16 v[16:19], v[174:177], v[198:201], v[16:19]
	v_mfma_f32_16x16x32_bf16 v[4:7], v[162:165], v[206:209], v[4:7]
	v_mfma_f32_16x16x32_bf16 v[0:3], v[174:177], v[206:209], v[0:3]
	s_barrier
	s_add_i32 s68, s68, 2
	s_add_u32 s80, s80, 0x100
	s_addc_u32 s81, s81, 0
	s_add_u32 s60, s60, 0x100
	s_addc_u32 s61, s61, 0
	s_cmp_gt_u32 s68, 29
	s_cbranch_scc0 .LBB0_297
	s_and_b64 vcc, exec, s[18:19]
	s_cbranch_vccz .LBB0_300
	s_barrier

.LBB0_384:
	s_ashr_i32 s73, s72, 31
	s_lshl_b64 s[74:75], s[72:73], 20
	s_add_u32 s74, s2, s74
	s_addc_u32 s75, s3, s75
	s_and_b64 s[76:77], s[4:5], exec
	s_cselect_b32 s73, s75, s81
	s_cselect_b32 s79, s74, s80
	s_ashr_i32 s23, s22, 31
	s_lshl_b64 s[76:77], s[22:23], 20
	s_add_u32 s76, s14, s76
	s_addc_u32 s77, s15, s77
	s_and_b64 s[84:85], s[4:5], exec
	s_cselect_b32 s23, s77, s83
	s_cselect_b32 s86, s76, s82
	s_add_u32 s80, s80, 0x80080
	s_addc_u32 s81, s81, 0
	s_add_u32 s87, s82, 0x100
	s_addc_u32 s88, s83, 0
	s_mov_b32 s89, -2
	s_add_u32 s67, s80, 0xfff80080
	s_addc_u32 s82, s81, -1
	s_add_i32 s90, 0, 0x10000
	s_cmp_eq_u32 s89, 28
	s_cselect_b32 s85, s73, s82
	s_cselect_b32 s84, s79, s67
	s_cselect_b32 s83, s23, s88
	s_cselect_b32 s82, s86, s87
	s_add_i32 s67, 0, 0x14000
	v_add_u32_e32 v140, s90, v186
	v_add_u32_e32 v156, s67, v186
	ds_read_b128 v[128:131], v140
	ds_read_b128 v[132:135], v140 offset:1024
	ds_read_b128 v[136:139], v140 offset:2048
	ds_read_b128 v[140:143], v140 offset:3072
	ds_read_b128 v[144:147], v156
	ds_read_b128 v[148:151], v156 offset:1024
	ds_read_b128 v[152:155], v156 offset:2048
	ds_read_b128 v[156:159], v156 offset:3072
	v_lshl_add_u64 v[208:209], s[80:81], 0, v[178:179]
	s_add_i32 m0, s29, 0xc000
	ds_read_b128 v[160:163], v187
	ds_read_b128 v[164:167], v187 offset:1024
	ds_read_b128 v[182:185], v187 offset:2048
	ds_read_b128 v[188:191], v187 offset:3072
	ds_read_b128 v[192:195], v187 offset:4096
	ds_read_b128 v[196:199], v187 offset:5120
	ds_read_b128 v[200:203], v187 offset:6144
	ds_read_b128 v[204:207], v187 offset:7168
	global_load_lds_dwordx4 v[208:209], off
	v_lshl_add_u64 v[208:209], s[80:81], 0, v[180:181]
	s_add_i32 m0, s29, 0xe000
	s_nop 0
	global_load_lds_dwordx4 v[208:209], off
	s_waitcnt vmcnt(8)
	s_waitcnt lgkmcnt(0)
	s_barrier
	s_waitcnt lgkmcnt(0)
	v_mfma_f32_16x16x32_bf16 v[124:127], v[128:131], v[160:163], 0
	v_mfma_f32_16x16x32_bf16 v[120:123], v[136:139], v[160:163], 0
	v_mfma_f32_16x16x32_bf16 v[108:111], v[128:131], v[182:185], 0
	v_mfma_f32_16x16x32_bf16 v[104:107], v[136:139], v[182:185], 0
	v_mfma_f32_16x16x32_bf16 v[92:95], v[128:131], v[192:195], 0
	v_mfma_f32_16x16x32_bf16 v[88:91], v[136:139], v[192:195], 0
	v_mfma_f32_16x16x32_bf16 v[76:79], v[128:131], v[200:203], 0
	v_mfma_f32_16x16x32_bf16 v[72:75], v[136:139], v[200:203], 0
	v_mfma_f32_16x16x32_bf16 v[124:127], v[132:135], v[164:167], v[124:127]
	v_mfma_f32_16x16x32_bf16 v[120:123], v[140:143], v[164:167], v[120:123]
	v_mfma_f32_16x16x32_bf16 v[108:111], v[132:135], v[188:191], v[108:111]
	v_mfma_f32_16x16x32_bf16 v[104:107], v[140:143], v[188:191], v[104:107]
	v_mfma_f32_16x16x32_bf16 v[92:95], v[132:135], v[196:199], v[92:95]
	v_mfma_f32_16x16x32_bf16 v[88:91], v[140:143], v[196:199], v[88:91]
	v_mfma_f32_16x16x32_bf16 v[76:79], v[132:135], v[204:207], v[76:79]
	v_mfma_f32_16x16x32_bf16 v[72:75], v[140:143], v[204:207], v[72:75]
	v_mfma_f32_16x16x32_bf16 v[116:119], v[144:147], v[160:163], 0
	v_mfma_f32_16x16x32_bf16 v[112:115], v[152:155], v[160:163], 0
	v_mfma_f32_16x16x32_bf16 v[100:103], v[144:147], v[182:185], 0
	v_mfma_f32_16x16x32_bf16 v[96:99], v[152:155], v[182:185], 0
	v_mfma_f32_16x16x32_bf16 v[84:87], v[144:147], v[192:195], 0
	v_mfma_f32_16x16x32_bf16 v[80:83], v[152:155], v[192:195], 0
	v_mfma_f32_16x16x32_bf16 v[68:71], v[144:147], v[200:203], 0
	v_mfma_f32_16x16x32_bf16 v[64:67], v[152:155], v[200:203], 0
	v_mfma_f32_16x16x32_bf16 v[116:119], v[148:151], v[164:167], v[116:119]
	v_mfma_f32_16x16x32_bf16 v[112:115], v[156:159], v[164:167], v[112:115]
	v_mfma_f32_16x16x32_bf16 v[100:103], v[148:151], v[188:191], v[100:103]
	v_mfma_f32_16x16x32_bf16 v[96:99], v[156:159], v[188:191], v[96:99]
	v_mfma_f32_16x16x32_bf16 v[84:87], v[148:151], v[196:199], v[84:87]
	v_mfma_f32_16x16x32_bf16 v[80:83], v[156:159], v[196:199], v[80:83]
	v_mfma_f32_16x16x32_bf16 v[68:71], v[148:151], v[204:207], v[68:71]
	v_mfma_f32_16x16x32_bf16 v[64:67], v[156:159], v[204:207], v[64:67]
	s_barrier
	s_add_i32 s90, s90, s24
	v_lshl_add_u64 v[208:209], s[82:83], 0, v[172:173]
	s_mov_b32 m0, s90
	ds_read_b128 v[160:163], v187 offset:16384
	ds_read_b128 v[164:167], v187 offset:17408
	ds_read_b128 v[182:185], v187 offset:18432
	ds_read_b128 v[188:191], v187 offset:19456
	ds_read_b128 v[192:195], v187 offset:20480
	ds_read_b128 v[196:199], v187 offset:21504
	ds_read_b128 v[200:203], v187 offset:22528
	ds_read_b128 v[204:207], v187 offset:23552
	global_load_lds_dwordx4 v[208:209], off
	s_add_i32 m0, s90, 0x2000
	s_add_u32 s90, s82, 0x80000
	v_lshl_add_u64 v[210:211], s[82:83], 0, v[168:169]
	s_addc_u32 s91, s83, 0
	s_add_i32 s67, s67, s24
	global_load_lds_dwordx4 v[210:211], off
	v_lshl_add_u64 v[212:213], s[90:91], 0, v[172:173]
	s_mov_b32 m0, s67
	v_lshl_add_u64 v[214:215], s[84:85], 0, v[170:171]
	global_load_lds_dwordx4 v[212:213], off
	v_lshl_add_u64 v[212:213], s[90:91], 0, v[168:169]
	s_add_i32 m0, s67, 0x2000
	s_nop 0
	global_load_lds_dwordx4 v[212:213], off
	v_lshl_add_u64 v[212:213], s[84:85], 0, v[174:175]
	s_mov_b32 m0, s29
	s_nop 0
	global_load_lds_dwordx4 v[212:213], off
	s_mov_b32 m0, s34
	s_nop 0
	global_load_lds_dwordx4 v[214:215], off
	s_waitcnt vmcnt(8)
	s_waitcnt lgkmcnt(0)
	s_barrier
	s_waitcnt lgkmcnt(0)
	v_mfma_f32_16x16x32_bf16 v[60:63], v[128:131], v[160:163], 0
	v_mfma_f32_16x16x32_bf16 v[56:59], v[136:139], v[160:163], 0
	v_mfma_f32_16x16x32_bf16 v[44:47], v[128:131], v[182:185], 0
	v_mfma_f32_16x16x32_bf16 v[40:43], v[136:139], v[182:185], 0
	v_mfma_f32_16x16x32_bf16 v[28:31], v[128:131], v[192:195], 0
	v_mfma_f32_16x16x32_bf16 v[24:27], v[136:139], v[192:195], 0
	v_mfma_f32_16x16x32_bf16 v[12:15], v[128:131], v[200:203], 0
	v_mfma_f32_16x16x32_bf16 v[8:11], v[136:139], v[200:203], 0
	v_mfma_f32_16x16x32_bf16 v[60:63], v[132:135], v[164:167], v[60:63]
	v_mfma_f32_16x16x32_bf16 v[56:59], v[140:143], v[164:167], v[56:59]
	v_mfma_f32_16x16x32_bf16 v[44:47], v[132:135], v[188:191], v[44:47]
	v_mfma_f32_16x16x32_bf16 v[40:43], v[140:143], v[188:191], v[40:43]
	v_mfma_f32_16x16x32_bf16 v[28:31], v[132:135], v[196:199], v[28:31]
	v_mfma_f32_16x16x32_bf16 v[24:27], v[140:143], v[196:199], v[24:27]
	v_mfma_f32_16x16x32_bf16 v[12:15], v[132:135], v[204:207], v[12:15]
	v_mfma_f32_16x16x32_bf16 v[8:11], v[140:143], v[204:207], v[8:11]
	v_mfma_f32_16x16x32_bf16 v[52:55], v[144:147], v[160:163], 0
	v_mfma_f32_16x16x32_bf16 v[48:51], v[152:155], v[160:163], 0
	v_mfma_f32_16x16x32_bf16 v[36:39], v[144:147], v[182:185], 0
	v_mfma_f32_16x16x32_bf16 v[32:35], v[152:155], v[182:185], 0
	v_mfma_f32_16x16x32_bf16 v[20:23], v[144:147], v[192:195], 0
	v_mfma_f32_16x16x32_bf16 v[16:19], v[152:155], v[192:195], 0
	v_mfma_f32_16x16x32_bf16 v[4:7], v[144:147], v[200:203], 0
	v_mfma_f32_16x16x32_bf16 v[0:3], v[152:155], v[200:203], 0
	v_mfma_f32_16x16x32_bf16 v[52:55], v[148:151], v[164:167], v[52:55]
	v_mfma_f32_16x16x32_bf16 v[48:51], v[156:159], v[164:167], v[48:51]
	v_mfma_f32_16x16x32_bf16 v[36:39], v[148:151], v[188:191], v[36:39]
	v_mfma_f32_16x16x32_bf16 v[32:35], v[156:159], v[188:191], v[32:35]
	v_mfma_f32_16x16x32_bf16 v[20:23], v[148:151], v[196:199], v[20:23]
	v_mfma_f32_16x16x32_bf16 v[16:19], v[156:159], v[196:199], v[16:19]
	v_mfma_f32_16x16x32_bf16 v[4:7], v[148:151], v[204:207], v[4:7]
	v_mfma_f32_16x16x32_bf16 v[0:3], v[156:159], v[204:207], v[0:3]
	s_barrier
	s_add_i32 s67, 0, 0x18000
	s_add_i32 s90, 0, 0x1c000
	v_add_u32_e32 v140, s67, v186
	v_add_u32_e32 v156, s90, v186
	ds_read_b128 v[128:131], v140
	ds_read_b128 v[132:135], v140 offset:1024
	ds_read_b128 v[136:139], v140 offset:2048
	ds_read_b128 v[140:143], v140 offset:3072
	ds_read_b128 v[144:147], v156
	ds_read_b128 v[148:151], v156 offset:1024
	ds_read_b128 v[152:155], v156 offset:2048
	ds_read_b128 v[156:159], v156 offset:3072
	s_add_u32 s84, s84, 0x80000
	s_addc_u32 s85, s85, 0
	s_mov_b32 m0, s35
	v_lshl_add_u64 v[218:219], s[84:85], 0, v[174:175]
	ds_read_b128 v[160:163], v187 offset:32768
	ds_read_b128 v[164:167], v187 offset:33792
	ds_read_b128 v[182:185], v187 offset:34816
	ds_read_b128 v[188:191], v187 offset:35840
	ds_read_b128 v[192:195], v187 offset:36864
	ds_read_b128 v[196:199], v187 offset:37888
	ds_read_b128 v[200:203], v187 offset:38912
	ds_read_b128 v[204:207], v187 offset:39936
	global_load_lds_dwordx4 v[218:219], off
	v_lshl_add_u64 v[218:219], s[84:85], 0, v[170:171]
	s_mov_b32 m0, s38
	s_nop 0
	global_load_lds_dwordx4 v[218:219], off
	s_waitcnt vmcnt(8)
	s_waitcnt lgkmcnt(0)
	s_barrier
	s_waitcnt lgkmcnt(0)
	v_mfma_f32_16x16x32_bf16 v[124:127], v[128:131], v[160:163], v[124:127]
	v_mfma_f32_16x16x32_bf16 v[120:123], v[136:139], v[160:163], v[120:123]
	v_mfma_f32_16x16x32_bf16 v[108:111], v[128:131], v[182:185], v[108:111]
	v_mfma_f32_16x16x32_bf16 v[104:107], v[136:139], v[182:185], v[104:107]
	v_mfma_f32_16x16x32_bf16 v[92:95], v[128:131], v[192:195], v[92:95]
	v_mfma_f32_16x16x32_bf16 v[88:91], v[136:139], v[192:195], v[88:91]
	v_mfma_f32_16x16x32_bf16 v[76:79], v[128:131], v[200:203], v[76:79]
	v_mfma_f32_16x16x32_bf16 v[72:75], v[136:139], v[200:203], v[72:75]
	v_mfma_f32_16x16x32_bf16 v[124:127], v[132:135], v[164:167], v[124:127]
	v_mfma_f32_16x16x32_bf16 v[120:123], v[140:143], v[164:167], v[120:123]
	v_mfma_f32_16x16x32_bf16 v[108:111], v[132:135], v[188:191], v[108:111]
	v_mfma_f32_16x16x32_bf16 v[104:107], v[140:143], v[188:191], v[104:107]
	v_mfma_f32_16x16x32_bf16 v[92:95], v[132:135], v[196:199], v[92:95]
	v_mfma_f32_16x16x32_bf16 v[88:91], v[140:143], v[196:199], v[88:91]
	v_mfma_f32_16x16x32_bf16 v[76:79], v[132:135], v[204:207], v[76:79]
	v_mfma_f32_16x16x32_bf16 v[72:75], v[140:143], v[204:207], v[72:75]
	v_mfma_f32_16x16x32_bf16 v[116:119], v[144:147], v[160:163], v[116:119]
	v_mfma_f32_16x16x32_bf16 v[112:115], v[152:155], v[160:163], v[112:115]
	v_mfma_f32_16x16x32_bf16 v[100:103], v[144:147], v[182:185], v[100:103]
	v_mfma_f32_16x16x32_bf16 v[96:99], v[152:155], v[182:185], v[96:99]
	v_mfma_f32_16x16x32_bf16 v[84:87], v[144:147], v[192:195], v[84:87]
	v_mfma_f32_16x16x32_bf16 v[80:83], v[152:155], v[192:195], v[80:83]
	v_mfma_f32_16x16x32_bf16 v[68:71], v[144:147], v[200:203], v[68:71]
	v_mfma_f32_16x16x32_bf16 v[64:67], v[152:155], v[200:203], v[64:67]
	v_mfma_f32_16x16x32_bf16 v[116:119], v[148:151], v[164:167], v[116:119]
	v_mfma_f32_16x16x32_bf16 v[112:115], v[156:159], v[164:167], v[112:115]
	v_mfma_f32_16x16x32_bf16 v[100:103], v[148:151], v[188:191], v[100:103]
	v_mfma_f32_16x16x32_bf16 v[96:99], v[156:159], v[188:191], v[96:99]
	v_mfma_f32_16x16x32_bf16 v[84:87], v[148:151], v[196:199], v[84:87]
	v_mfma_f32_16x16x32_bf16 v[80:83], v[156:159], v[196:199], v[80:83]
	v_mfma_f32_16x16x32_bf16 v[68:71], v[148:151], v[204:207], v[68:71]
	v_mfma_f32_16x16x32_bf16 v[64:67], v[156:159], v[204:207], v[64:67]
	s_barrier
	s_add_i32 s67, s67, s24
	v_lshl_add_u64 v[208:209], v[208:209], 0, s[30:31]
	s_mov_b32 m0, s67
	ds_read_b128 v[160:163], v187 offset:49152
	ds_read_b128 v[164:167], v187 offset:50176
	ds_read_b128 v[182:185], v187 offset:51200
	ds_read_b128 v[188:191], v187 offset:52224
	ds_read_b128 v[192:195], v187 offset:53248
	ds_read_b128 v[196:199], v187 offset:54272
	ds_read_b128 v[200:203], v187 offset:55296
	ds_read_b128 v[204:207], v187 offset:56320
	global_load_lds_dwordx4 v[208:209], off
	s_add_i32 m0, s67, 0x2000
	s_add_u32 s82, s82, 0x80080
	v_lshl_add_u64 v[208:209], v[210:211], 0, s[30:31]
	s_addc_u32 s83, s83, 0
	s_add_i32 s67, s90, s24
	global_load_lds_dwordx4 v[208:209], off
	v_lshl_add_u64 v[208:209], s[82:83], 0, v[172:173]
	s_mov_b32 m0, s67
	s_nop 0
	global_load_lds_dwordx4 v[208:209], off
	v_lshl_add_u64 v[208:209], s[82:83], 0, v[168:169]
	s_add_i32 m0, s67, 0x2000
	s_nop 0
	global_load_lds_dwordx4 v[208:209], off
	v_lshl_add_u64 v[208:209], v[212:213], 0, s[30:31]
	s_mov_b32 m0, s54
	s_nop 0
	global_load_lds_dwordx4 v[208:209], off
	v_lshl_add_u64 v[208:209], v[214:215], 0, s[30:31]
	s_mov_b32 m0, s55
	s_nop 0
	global_load_lds_dwordx4 v[208:209], off
	s_waitcnt vmcnt(8)
	s_waitcnt lgkmcnt(0)
	s_barrier
	s_waitcnt lgkmcnt(0)
	v_mfma_f32_16x16x32_bf16 v[60:63], v[128:131], v[160:163], v[60:63]
	v_mfma_f32_16x16x32_bf16 v[56:59], v[136:139], v[160:163], v[56:59]
	v_mfma_f32_16x16x32_bf16 v[44:47], v[128:131], v[182:185], v[44:47]
	v_mfma_f32_16x16x32_bf16 v[40:43], v[136:139], v[182:185], v[40:43]
	v_mfma_f32_16x16x32_bf16 v[28:31], v[128:131], v[192:195], v[28:31]
	v_mfma_f32_16x16x32_bf16 v[24:27], v[136:139], v[192:195], v[24:27]
	v_mfma_f32_16x16x32_bf16 v[12:15], v[128:131], v[200:203], v[12:15]
	v_mfma_f32_16x16x32_bf16 v[8:11], v[136:139], v[200:203], v[8:11]
	v_mfma_f32_16x16x32_bf16 v[60:63], v[132:135], v[164:167], v[60:63]
	v_mfma_f32_16x16x32_bf16 v[56:59], v[140:143], v[164:167], v[56:59]
	v_mfma_f32_16x16x32_bf16 v[44:47], v[132:135], v[188:191], v[44:47]
	v_mfma_f32_16x16x32_bf16 v[40:43], v[140:143], v[188:191], v[40:43]
	v_mfma_f32_16x16x32_bf16 v[28:31], v[132:135], v[196:199], v[28:31]
	v_mfma_f32_16x16x32_bf16 v[24:27], v[140:143], v[196:199], v[24:27]
	v_mfma_f32_16x16x32_bf16 v[12:15], v[132:135], v[204:207], v[12:15]
	v_mfma_f32_16x16x32_bf16 v[8:11], v[140:143], v[204:207], v[8:11]
	v_mfma_f32_16x16x32_bf16 v[52:55], v[144:147], v[160:163], v[52:55]
	v_mfma_f32_16x16x32_bf16 v[48:51], v[152:155], v[160:163], v[48:51]
	v_mfma_f32_16x16x32_bf16 v[36:39], v[144:147], v[182:185], v[36:39]
	v_mfma_f32_16x16x32_bf16 v[32:35], v[152:155], v[182:185], v[32:35]
	v_mfma_f32_16x16x32_bf16 v[20:23], v[144:147], v[192:195], v[20:23]
	v_mfma_f32_16x16x32_bf16 v[16:19], v[152:155], v[192:195], v[16:19]
	v_mfma_f32_16x16x32_bf16 v[4:7], v[144:147], v[200:203], v[4:7]
	v_mfma_f32_16x16x32_bf16 v[0:3], v[152:155], v[200:203], v[0:3]
	v_mfma_f32_16x16x32_bf16 v[52:55], v[148:151], v[164:167], v[52:55]
	v_mfma_f32_16x16x32_bf16 v[48:51], v[156:159], v[164:167], v[48:51]
	v_mfma_f32_16x16x32_bf16 v[36:39], v[148:151], v[188:191], v[36:39]
	v_mfma_f32_16x16x32_bf16 v[32:35], v[156:159], v[188:191], v[32:35]
	v_mfma_f32_16x16x32_bf16 v[20:23], v[148:151], v[196:199], v[20:23]
	v_mfma_f32_16x16x32_bf16 v[16:19], v[156:159], v[196:199], v[16:19]
	v_mfma_f32_16x16x32_bf16 v[4:7], v[148:151], v[204:207], v[4:7]
	v_mfma_f32_16x16x32_bf16 v[0:3], v[156:159], v[204:207], v[0:3]
	s_barrier
	s_add_i32 s89, s89, 2
	s_add_u32 s80, s80, 0x100
	s_addc_u32 s81, s81, 0
	s_add_u32 s87, s87, 0x100
	s_addc_u32 s88, s88, 0
.LBB0_385:
	s_add_u32 s67, s80, 0xfff80080
	s_addc_u32 s82, s81, -1
	s_add_i32 s90, 0, 0x10000
	s_cmp_eq_u32 s89, 28
	s_cselect_b32 s85, s73, s82
	s_cselect_b32 s84, s79, s67
	s_cselect_b32 s83, s23, s88
	s_cselect_b32 s82, s86, s87
	s_add_i32 s67, 0, 0x14000
	v_add_u32_e32 v140, s90, v186
	v_add_u32_e32 v156, s67, v186
	ds_read_b128 v[128:131], v140
	ds_read_b128 v[132:135], v140 offset:1024
	ds_read_b128 v[136:139], v140 offset:2048
	ds_read_b128 v[140:143], v140 offset:3072
	ds_read_b128 v[144:147], v156
	ds_read_b128 v[148:151], v156 offset:1024
	ds_read_b128 v[152:155], v156 offset:2048
	ds_read_b128 v[156:159], v156 offset:3072
	v_lshl_add_u64 v[208:209], s[80:81], 0, v[178:179]
	s_add_i32 m0, s29, 0xc000
	ds_read_b128 v[160:163], v187
	ds_read_b128 v[164:167], v187 offset:1024
	ds_read_b128 v[182:185], v187 offset:2048
	ds_read_b128 v[188:191], v187 offset:3072
	ds_read_b128 v[192:195], v187 offset:4096
	ds_read_b128 v[196:199], v187 offset:5120
	ds_read_b128 v[200:203], v187 offset:6144
	ds_read_b128 v[204:207], v187 offset:7168
	global_load_lds_dwordx4 v[208:209], off
	v_lshl_add_u64 v[208:209], s[80:81], 0, v[180:181]
	s_add_i32 m0, s29, 0xe000
	s_nop 0
	global_load_lds_dwordx4 v[208:209], off
	s_waitcnt vmcnt(8)
	s_waitcnt lgkmcnt(0)
	s_barrier
	s_waitcnt lgkmcnt(0)
	v_mfma_f32_16x16x32_bf16 v[124:127], v[128:131], v[160:163], v[124:127]
	v_mfma_f32_16x16x32_bf16 v[120:123], v[136:139], v[160:163], v[120:123]
	v_mfma_f32_16x16x32_bf16 v[108:111], v[128:131], v[182:185], v[108:111]
	v_mfma_f32_16x16x32_bf16 v[104:107], v[136:139], v[182:185], v[104:107]
	v_mfma_f32_16x16x32_bf16 v[92:95], v[128:131], v[192:195], v[92:95]
	v_mfma_f32_16x16x32_bf16 v[88:91], v[136:139], v[192:195], v[88:91]
	v_mfma_f32_16x16x32_bf16 v[76:79], v[128:131], v[200:203], v[76:79]
	v_mfma_f32_16x16x32_bf16 v[72:75], v[136:139], v[200:203], v[72:75]
	v_mfma_f32_16x16x32_bf16 v[124:127], v[132:135], v[164:167], v[124:127]
	v_mfma_f32_16x16x32_bf16 v[120:123], v[140:143], v[164:167], v[120:123]
	v_mfma_f32_16x16x32_bf16 v[108:111], v[132:135], v[188:191], v[108:111]
	v_mfma_f32_16x16x32_bf16 v[104:107], v[140:143], v[188:191], v[104:107]
	v_mfma_f32_16x16x32_bf16 v[92:95], v[132:135], v[196:199], v[92:95]
	v_mfma_f32_16x16x32_bf16 v[88:91], v[140:143], v[196:199], v[88:91]
	v_mfma_f32_16x16x32_bf16 v[76:79], v[132:135], v[204:207], v[76:79]
	v_mfma_f32_16x16x32_bf16 v[72:75], v[140:143], v[204:207], v[72:75]
	v_mfma_f32_16x16x32_bf16 v[116:119], v[144:147], v[160:163], v[116:119]
	v_mfma_f32_16x16x32_bf16 v[112:115], v[152:155], v[160:163], v[112:115]
	v_mfma_f32_16x16x32_bf16 v[100:103], v[144:147], v[182:185], v[100:103]
	v_mfma_f32_16x16x32_bf16 v[96:99], v[152:155], v[182:185], v[96:99]
	v_mfma_f32_16x16x32_bf16 v[84:87], v[144:147], v[192:195], v[84:87]
	v_mfma_f32_16x16x32_bf16 v[80:83], v[152:155], v[192:195], v[80:83]
	v_mfma_f32_16x16x32_bf16 v[68:71], v[144:147], v[200:203], v[68:71]
	v_mfma_f32_16x16x32_bf16 v[64:67], v[152:155], v[200:203], v[64:67]
	v_mfma_f32_16x16x32_bf16 v[116:119], v[148:151], v[164:167], v[116:119]
	v_mfma_f32_16x16x32_bf16 v[112:115], v[156:159], v[164:167], v[112:115]
	v_mfma_f32_16x16x32_bf16 v[100:103], v[148:151], v[188:191], v[100:103]
	v_mfma_f32_16x16x32_bf16 v[96:99], v[156:159], v[188:191], v[96:99]
	v_mfma_f32_16x16x32_bf16 v[84:87], v[148:151], v[196:199], v[84:87]
	v_mfma_f32_16x16x32_bf16 v[80:83], v[156:159], v[196:199], v[80:83]
	v_mfma_f32_16x16x32_bf16 v[68:71], v[148:151], v[204:207], v[68:71]
	v_mfma_f32_16x16x32_bf16 v[64:67], v[156:159], v[204:207], v[64:67]
	s_barrier
	s_add_i32 s90, s90, s24
	v_lshl_add_u64 v[208:209], s[82:83], 0, v[172:173]
	s_mov_b32 m0, s90
	ds_read_b128 v[160:163], v187 offset:16384
	ds_read_b128 v[164:167], v187 offset:17408
	ds_read_b128 v[182:185], v187 offset:18432
	ds_read_b128 v[188:191], v187 offset:19456
	ds_read_b128 v[192:195], v187 offset:20480
	ds_read_b128 v[196:199], v187 offset:21504
	ds_read_b128 v[200:203], v187 offset:22528
	ds_read_b128 v[204:207], v187 offset:23552
	global_load_lds_dwordx4 v[208:209], off
	s_add_i32 m0, s90, 0x2000
	s_add_u32 s90, s82, 0x80000
	v_lshl_add_u64 v[210:211], s[82:83], 0, v[168:169]
	s_addc_u32 s91, s83, 0
	s_add_i32 s67, s67, s24
	global_load_lds_dwordx4 v[210:211], off
	v_lshl_add_u64 v[212:213], s[90:91], 0, v[172:173]
	s_mov_b32 m0, s67
	v_lshl_add_u64 v[214:215], s[84:85], 0, v[170:171]
	global_load_lds_dwordx4 v[212:213], off
	v_lshl_add_u64 v[212:213], s[90:91], 0, v[168:169]
	s_add_i32 m0, s67, 0x2000
	s_nop 0
	global_load_lds_dwordx4 v[212:213], off
	v_lshl_add_u64 v[212:213], s[84:85], 0, v[174:175]
	s_mov_b32 m0, s29
	s_nop 0
	global_load_lds_dwordx4 v[212:213], off
	s_mov_b32 m0, s34
	s_nop 0
	global_load_lds_dwordx4 v[214:215], off
	s_waitcnt vmcnt(8)
	s_waitcnt lgkmcnt(0)
	s_barrier
	s_waitcnt lgkmcnt(0)
	v_mfma_f32_16x16x32_bf16 v[60:63], v[128:131], v[160:163], v[60:63]
	v_mfma_f32_16x16x32_bf16 v[56:59], v[136:139], v[160:163], v[56:59]
	v_mfma_f32_16x16x32_bf16 v[44:47], v[128:131], v[182:185], v[44:47]
	v_mfma_f32_16x16x32_bf16 v[40:43], v[136:139], v[182:185], v[40:43]
	v_mfma_f32_16x16x32_bf16 v[28:31], v[128:131], v[192:195], v[28:31]
	v_mfma_f32_16x16x32_bf16 v[24:27], v[136:139], v[192:195], v[24:27]
	v_mfma_f32_16x16x32_bf16 v[12:15], v[128:131], v[200:203], v[12:15]
	v_mfma_f32_16x16x32_bf16 v[8:11], v[136:139], v[200:203], v[8:11]
	v_mfma_f32_16x16x32_bf16 v[60:63], v[132:135], v[164:167], v[60:63]
	v_mfma_f32_16x16x32_bf16 v[56:59], v[140:143], v[164:167], v[56:59]
	v_mfma_f32_16x16x32_bf16 v[44:47], v[132:135], v[188:191], v[44:47]
	v_mfma_f32_16x16x32_bf16 v[40:43], v[140:143], v[188:191], v[40:43]
	v_mfma_f32_16x16x32_bf16 v[28:31], v[132:135], v[196:199], v[28:31]
	v_mfma_f32_16x16x32_bf16 v[24:27], v[140:143], v[196:199], v[24:27]
	v_mfma_f32_16x16x32_bf16 v[12:15], v[132:135], v[204:207], v[12:15]
	v_mfma_f32_16x16x32_bf16 v[8:11], v[140:143], v[204:207], v[8:11]
	v_mfma_f32_16x16x32_bf16 v[52:55], v[144:147], v[160:163], v[52:55]
	v_mfma_f32_16x16x32_bf16 v[48:51], v[152:155], v[160:163], v[48:51]
	v_mfma_f32_16x16x32_bf16 v[36:39], v[144:147], v[182:185], v[36:39]
	v_mfma_f32_16x16x32_bf16 v[32:35], v[152:155], v[182:185], v[32:35]
	v_mfma_f32_16x16x32_bf16 v[20:23], v[144:147], v[192:195], v[20:23]
	v_mfma_f32_16x16x32_bf16 v[16:19], v[152:155], v[192:195], v[16:19]
	v_mfma_f32_16x16x32_bf16 v[4:7], v[144:147], v[200:203], v[4:7]
	v_mfma_f32_16x16x32_bf16 v[0:3], v[152:155], v[200:203], v[0:3]
	v_mfma_f32_16x16x32_bf16 v[52:55], v[148:151], v[164:167], v[52:55]
	v_mfma_f32_16x16x32_bf16 v[48:51], v[156:159], v[164:167], v[48:51]
	v_mfma_f32_16x16x32_bf16 v[36:39], v[148:151], v[188:191], v[36:39]
	v_mfma_f32_16x16x32_bf16 v[32:35], v[156:159], v[188:191], v[32:35]
	v_mfma_f32_16x16x32_bf16 v[20:23], v[148:151], v[196:199], v[20:23]
	v_mfma_f32_16x16x32_bf16 v[16:19], v[156:159], v[196:199], v[16:19]
	v_mfma_f32_16x16x32_bf16 v[4:7], v[148:151], v[204:207], v[4:7]
	v_mfma_f32_16x16x32_bf16 v[0:3], v[156:159], v[204:207], v[0:3]
	s_barrier
	s_add_i32 s67, 0, 0x18000
	s_add_i32 s90, 0, 0x1c000
	v_add_u32_e32 v140, s67, v186
	v_add_u32_e32 v156, s90, v186
	ds_read_b128 v[128:131], v140
	ds_read_b128 v[132:135], v140 offset:1024
	ds_read_b128 v[136:139], v140 offset:2048
	ds_read_b128 v[140:143], v140 offset:3072
	ds_read_b128 v[144:147], v156
	ds_read_b128 v[148:151], v156 offset:1024
	ds_read_b128 v[152:155], v156 offset:2048
	ds_read_b128 v[156:159], v156 offset:3072
	s_add_u32 s84, s84, 0x80000
	s_addc_u32 s85, s85, 0
	s_mov_b32 m0, s35
	v_lshl_add_u64 v[218:219], s[84:85], 0, v[174:175]
	ds_read_b128 v[160:163], v187 offset:32768
	ds_read_b128 v[164:167], v187 offset:33792
	ds_read_b128 v[182:185], v187 offset:34816
	ds_read_b128 v[188:191], v187 offset:35840
	ds_read_b128 v[192:195], v187 offset:36864
	ds_read_b128 v[196:199], v187 offset:37888
	ds_read_b128 v[200:203], v187 offset:38912
	ds_read_b128 v[204:207], v187 offset:39936
	global_load_lds_dwordx4 v[218:219], off
	v_lshl_add_u64 v[218:219], s[84:85], 0, v[170:171]
	s_mov_b32 m0, s38
	s_nop 0
	global_load_lds_dwordx4 v[218:219], off
	s_waitcnt vmcnt(8)
	s_waitcnt lgkmcnt(0)
	s_barrier
	s_waitcnt lgkmcnt(0)
	v_mfma_f32_16x16x32_bf16 v[124:127], v[128:131], v[160:163], v[124:127]
	v_mfma_f32_16x16x32_bf16 v[120:123], v[136:139], v[160:163], v[120:123]
	v_mfma_f32_16x16x32_bf16 v[108:111], v[128:131], v[182:185], v[108:111]
	v_mfma_f32_16x16x32_bf16 v[104:107], v[136:139], v[182:185], v[104:107]
	v_mfma_f32_16x16x32_bf16 v[92:95], v[128:131], v[192:195], v[92:95]
	v_mfma_f32_16x16x32_bf16 v[88:91], v[136:139], v[192:195], v[88:91]
	v_mfma_f32_16x16x32_bf16 v[76:79], v[128:131], v[200:203], v[76:79]
	v_mfma_f32_16x16x32_bf16 v[72:75], v[136:139], v[200:203], v[72:75]
	v_mfma_f32_16x16x32_bf16 v[124:127], v[132:135], v[164:167], v[124:127]
	v_mfma_f32_16x16x32_bf16 v[120:123], v[140:143], v[164:167], v[120:123]
	v_mfma_f32_16x16x32_bf16 v[108:111], v[132:135], v[188:191], v[108:111]
	v_mfma_f32_16x16x32_bf16 v[104:107], v[140:143], v[188:191], v[104:107]
	v_mfma_f32_16x16x32_bf16 v[92:95], v[132:135], v[196:199], v[92:95]
	v_mfma_f32_16x16x32_bf16 v[88:91], v[140:143], v[196:199], v[88:91]
	v_mfma_f32_16x16x32_bf16 v[76:79], v[132:135], v[204:207], v[76:79]
	v_mfma_f32_16x16x32_bf16 v[72:75], v[140:143], v[204:207], v[72:75]
	v_mfma_f32_16x16x32_bf16 v[116:119], v[144:147], v[160:163], v[116:119]
	v_mfma_f32_16x16x32_bf16 v[112:115], v[152:155], v[160:163], v[112:115]
	v_mfma_f32_16x16x32_bf16 v[100:103], v[144:147], v[182:185], v[100:103]
	v_mfma_f32_16x16x32_bf16 v[96:99], v[152:155], v[182:185], v[96:99]
	v_mfma_f32_16x16x32_bf16 v[84:87], v[144:147], v[192:195], v[84:87]
	v_mfma_f32_16x16x32_bf16 v[80:83], v[152:155], v[192:195], v[80:83]
	v_mfma_f32_16x16x32_bf16 v[68:71], v[144:147], v[200:203], v[68:71]
	v_mfma_f32_16x16x32_bf16 v[64:67], v[152:155], v[200:203], v[64:67]
	v_mfma_f32_16x16x32_bf16 v[116:119], v[148:151], v[164:167], v[116:119]
	v_mfma_f32_16x16x32_bf16 v[112:115], v[156:159], v[164:167], v[112:115]
	v_mfma_f32_16x16x32_bf16 v[100:103], v[148:151], v[188:191], v[100:103]
	v_mfma_f32_16x16x32_bf16 v[96:99], v[156:159], v[188:191], v[96:99]
	v_mfma_f32_16x16x32_bf16 v[84:87], v[148:151], v[196:199], v[84:87]
	v_mfma_f32_16x16x32_bf16 v[80:83], v[156:159], v[196:199], v[80:83]
	v_mfma_f32_16x16x32_bf16 v[68:71], v[148:151], v[204:207], v[68:71]
	v_mfma_f32_16x16x32_bf16 v[64:67], v[156:159], v[204:207], v[64:67]
	s_barrier
	s_add_i32 s67, s67, s24
	v_lshl_add_u64 v[208:209], v[208:209], 0, s[30:31]
	s_mov_b32 m0, s67
	ds_read_b128 v[160:163], v187 offset:49152
	ds_read_b128 v[164:167], v187 offset:50176
	ds_read_b128 v[182:185], v187 offset:51200
	ds_read_b128 v[188:191], v187 offset:52224
	ds_read_b128 v[192:195], v187 offset:53248
	ds_read_b128 v[196:199], v187 offset:54272
	ds_read_b128 v[200:203], v187 offset:55296
	ds_read_b128 v[204:207], v187 offset:56320
	global_load_lds_dwordx4 v[208:209], off
	s_add_i32 m0, s67, 0x2000
	s_add_u32 s82, s82, 0x80080
	v_lshl_add_u64 v[208:209], v[210:211], 0, s[30:31]
	s_addc_u32 s83, s83, 0
	s_add_i32 s67, s90, s24
	global_load_lds_dwordx4 v[208:209], off
	v_lshl_add_u64 v[208:209], s[82:83], 0, v[172:173]
	s_mov_b32 m0, s67
	s_nop 0
	global_load_lds_dwordx4 v[208:209], off
	v_lshl_add_u64 v[208:209], s[82:83], 0, v[168:169]
	s_add_i32 m0, s67, 0x2000
	s_nop 0
	global_load_lds_dwordx4 v[208:209], off
	v_lshl_add_u64 v[208:209], v[212:213], 0, s[30:31]
	s_mov_b32 m0, s54
	s_nop 0
	global_load_lds_dwordx4 v[208:209], off
	v_lshl_add_u64 v[208:209], v[214:215], 0, s[30:31]
	s_mov_b32 m0, s55
	s_nop 0
	global_load_lds_dwordx4 v[208:209], off
	s_waitcnt vmcnt(8)
	s_waitcnt lgkmcnt(0)
	s_barrier
	s_waitcnt lgkmcnt(0)
	v_mfma_f32_16x16x32_bf16 v[60:63], v[128:131], v[160:163], v[60:63]
	v_mfma_f32_16x16x32_bf16 v[56:59], v[136:139], v[160:163], v[56:59]
	v_mfma_f32_16x16x32_bf16 v[44:47], v[128:131], v[182:185], v[44:47]
	v_mfma_f32_16x16x32_bf16 v[40:43], v[136:139], v[182:185], v[40:43]
	v_mfma_f32_16x16x32_bf16 v[28:31], v[128:131], v[192:195], v[28:31]
	v_mfma_f32_16x16x32_bf16 v[24:27], v[136:139], v[192:195], v[24:27]
	v_mfma_f32_16x16x32_bf16 v[12:15], v[128:131], v[200:203], v[12:15]
	v_mfma_f32_16x16x32_bf16 v[8:11], v[136:139], v[200:203], v[8:11]
	v_mfma_f32_16x16x32_bf16 v[60:63], v[132:135], v[164:167], v[60:63]
	v_mfma_f32_16x16x32_bf16 v[56:59], v[140:143], v[164:167], v[56:59]
	v_mfma_f32_16x16x32_bf16 v[44:47], v[132:135], v[188:191], v[44:47]
	v_mfma_f32_16x16x32_bf16 v[40:43], v[140:143], v[188:191], v[40:43]
	v_mfma_f32_16x16x32_bf16 v[28:31], v[132:135], v[196:199], v[28:31]
	v_mfma_f32_16x16x32_bf16 v[24:27], v[140:143], v[196:199], v[24:27]
	v_mfma_f32_16x16x32_bf16 v[12:15], v[132:135], v[204:207], v[12:15]
	v_mfma_f32_16x16x32_bf16 v[8:11], v[140:143], v[204:207], v[8:11]
	v_mfma_f32_16x16x32_bf16 v[52:55], v[144:147], v[160:163], v[52:55]
	v_mfma_f32_16x16x32_bf16 v[48:51], v[152:155], v[160:163], v[48:51]
	v_mfma_f32_16x16x32_bf16 v[36:39], v[144:147], v[182:185], v[36:39]
	v_mfma_f32_16x16x32_bf16 v[32:35], v[152:155], v[182:185], v[32:35]
	v_mfma_f32_16x16x32_bf16 v[20:23], v[144:147], v[192:195], v[20:23]
	v_mfma_f32_16x16x32_bf16 v[16:19], v[152:155], v[192:195], v[16:19]
	v_mfma_f32_16x16x32_bf16 v[4:7], v[144:147], v[200:203], v[4:7]
	v_mfma_f32_16x16x32_bf16 v[0:3], v[152:155], v[200:203], v[0:3]
	v_mfma_f32_16x16x32_bf16 v[52:55], v[148:151], v[164:167], v[52:55]
	v_mfma_f32_16x16x32_bf16 v[48:51], v[156:159], v[164:167], v[48:51]
	v_mfma_f32_16x16x32_bf16 v[36:39], v[148:151], v[188:191], v[36:39]
	v_mfma_f32_16x16x32_bf16 v[32:35], v[156:159], v[188:191], v[32:35]
	v_mfma_f32_16x16x32_bf16 v[20:23], v[148:151], v[196:199], v[20:23]
	v_mfma_f32_16x16x32_bf16 v[16:19], v[156:159], v[196:199], v[16:19]
	v_mfma_f32_16x16x32_bf16 v[4:7], v[148:151], v[204:207], v[4:7]
	v_mfma_f32_16x16x32_bf16 v[0:3], v[156:159], v[204:207], v[0:3]
	s_barrier
	s_add_i32 s89, s89, 2
	s_add_u32 s80, s80, 0x100
	s_addc_u32 s81, s81, 0
	s_add_u32 s87, s87, 0x100
	s_addc_u32 s88, s88, 0
	s_cmp_gt_u32 s89, 29
	s_cbranch_scc0 .LBB0_385
	s_and_b64 vcc, exec, s[18:19]
	s_cbranch_vccz .LBB0_388
	s_barrier

.LBB0_594:
	s_ashr_i32 s81, s80, 31
	s_lshl_b64 s[84:85], s[80:81], 20
	s_add_u32 s84, s29, s84
	s_addc_u32 s85, s34, s85
	s_and_b64 s[86:87], s[82:83], exec
	s_cselect_b32 s81, s85, s95
	s_cselect_b32 vcc_lo, s84, s94
	s_ashr_i32 s79, s78, 31
	s_lshl_b64 s[86:87], s[78:79], 20
	s_add_u32 s86, s35, s86
	s_addc_u32 s87, s38, s87
	s_and_b64 s[2:3], s[82:83], exec
	s_cselect_b32 s79, s87, s93
	s_cselect_b32 vcc_hi, s86, s92
	s_lshl_b32 s88, s88, 8
	s_ashr_i32 s89, s88, 31
	s_lshl_b64 s[2:3], s[88:89], 2
	s_add_u32 s2, s90, s2
	s_addc_u32 s3, s91, s3
	s_add_i32 m0, s14, s41
	s_add_u32 s90, s94, 0x80080
	global_load_lds_dwordx4 v239, s[2:3]
	s_addc_u32 s91, s95, 0
	s_add_u32 s89, s92, 0x100
	s_addc_u32 s14, s93, 0
	s_mov_b32 s20, -2
	s_waitcnt vmcnt(0)
	s_add_u32 s2, s90, 0xfff80080
	s_addc_u32 s3, s91, -1
	s_add_i32 s67, 0, 0x10000
	s_cmp_eq_u32 s20, 28
	s_cselect_b32 s95, s81, s3
	s_cselect_b32 s94, vcc_lo, s2
	s_cselect_b32 s93, s79, s14
	s_cselect_b32 s92, vcc_hi, s89
	s_add_i32 s76, 0, 0x14000
	v_add_u32_e32 v96, s67, v238
	v_add_u32_e32 v140, s76, v238
	ds_read_b128 v[64:67], v96
	ds_read_b128 v[72:75], v96 offset:1024
	ds_read_b128 v[88:91], v96 offset:2048
	ds_read_b128 v[96:99], v96 offset:3072
	ds_read_b128 v[108:111], v140
	ds_read_b128 v[116:119], v140 offset:1024
	ds_read_b128 v[128:131], v140 offset:2048
	ds_read_b128 v[140:143], v140 offset:3072
	v_lshl_add_u64 v[192:193], s[90:91], 0, v[230:231]
	s_add_i32 m0, s39, 0xc000
	ds_read_b128 v[152:155], v240
	ds_read_b128 v[156:159], v240 offset:1024
	ds_read_b128 v[160:163], v240 offset:2048
	ds_read_b128 v[164:167], v240 offset:3072
	ds_read_b128 v[168:171], v240 offset:4096
	ds_read_b128 v[180:183], v240 offset:5120
	ds_read_b128 v[184:187], v240 offset:6144
	ds_read_b128 v[188:191], v240 offset:7168
	global_load_lds_dwordx4 v[192:193], off
	v_lshl_add_u64 v[192:193], s[90:91], 0, v[232:233]
	s_add_i32 m0, s39, 0xe000
	s_nop 0
	global_load_lds_dwordx4 v[192:193], off
	s_waitcnt vmcnt(8)
	s_waitcnt lgkmcnt(0)
	s_barrier
	s_waitcnt lgkmcnt(0)
	v_mfma_f32_16x16x32_bf16 v[176:179], v[64:67], v[152:155], 0
	v_mfma_f32_16x16x32_bf16 v[172:175], v[88:91], v[152:155], 0
	v_mfma_f32_16x16x32_bf16 v[136:139], v[64:67], v[160:163], 0
	v_mfma_f32_16x16x32_bf16 v[132:135], v[88:91], v[160:163], 0
	v_mfma_f32_16x16x32_bf16 v[112:115], v[64:67], v[168:171], 0
	v_mfma_f32_16x16x32_bf16 v[104:107], v[88:91], v[168:171], 0
	v_mfma_f32_16x16x32_bf16 v[84:87], v[64:67], v[184:187], 0
	v_mfma_f32_16x16x32_bf16 v[80:83], v[88:91], v[184:187], 0
	v_mfma_f32_16x16x32_bf16 v[176:179], v[72:75], v[156:159], v[176:179]
	v_mfma_f32_16x16x32_bf16 v[172:175], v[96:99], v[156:159], v[172:175]
	v_mfma_f32_16x16x32_bf16 v[136:139], v[72:75], v[164:167], v[136:139]
	v_mfma_f32_16x16x32_bf16 v[132:135], v[96:99], v[164:167], v[132:135]
	v_mfma_f32_16x16x32_bf16 v[112:115], v[72:75], v[180:183], v[112:115]
	v_mfma_f32_16x16x32_bf16 v[104:107], v[96:99], v[180:183], v[104:107]
	v_mfma_f32_16x16x32_bf16 v[84:87], v[72:75], v[188:191], v[84:87]
	v_mfma_f32_16x16x32_bf16 v[80:83], v[96:99], v[188:191], v[80:83]
	v_mfma_f32_16x16x32_bf16 v[148:151], v[108:111], v[152:155], 0
	v_mfma_f32_16x16x32_bf16 v[144:147], v[128:131], v[152:155], 0
	v_mfma_f32_16x16x32_bf16 v[124:127], v[108:111], v[160:163], 0
	v_mfma_f32_16x16x32_bf16 v[120:123], v[128:131], v[160:163], 0
	v_mfma_f32_16x16x32_bf16 v[100:103], v[108:111], v[168:171], 0
	v_mfma_f32_16x16x32_bf16 v[92:95], v[128:131], v[168:171], 0
	v_mfma_f32_16x16x32_bf16 v[76:79], v[108:111], v[184:187], 0
	v_mfma_f32_16x16x32_bf16 v[68:71], v[128:131], v[184:187], 0
	v_mfma_f32_16x16x32_bf16 v[148:151], v[116:119], v[156:159], v[148:151]
	v_mfma_f32_16x16x32_bf16 v[144:147], v[140:143], v[156:159], v[144:147]
	v_mfma_f32_16x16x32_bf16 v[124:127], v[116:119], v[164:167], v[124:127]
	v_mfma_f32_16x16x32_bf16 v[120:123], v[140:143], v[164:167], v[120:123]
	v_mfma_f32_16x16x32_bf16 v[100:103], v[116:119], v[180:183], v[100:103]
	v_mfma_f32_16x16x32_bf16 v[92:95], v[140:143], v[180:183], v[92:95]
	v_mfma_f32_16x16x32_bf16 v[76:79], v[116:119], v[188:191], v[76:79]
	v_mfma_f32_16x16x32_bf16 v[68:71], v[140:143], v[188:191], v[68:71]
	s_barrier
	s_add_i32 s2, s67, s28
	v_lshl_add_u64 v[192:193], s[92:93], 0, v[216:217]
	s_mov_b32 m0, s2
	ds_read_b128 v[152:155], v240 offset:16384
	ds_read_b128 v[156:159], v240 offset:17408
	ds_read_b128 v[160:163], v240 offset:18432
	ds_read_b128 v[164:167], v240 offset:19456
	ds_read_b128 v[168:171], v240 offset:20480
	ds_read_b128 v[180:183], v240 offset:21504
	ds_read_b128 v[184:187], v240 offset:22528
	ds_read_b128 v[188:191], v240 offset:23552
	global_load_lds_dwordx4 v[192:193], off
	s_add_i32 m0, s2, 0x2000
	s_add_u32 s2, s92, 0x80000
	v_lshl_add_u64 v[194:195], s[92:93], 0, v[228:229]
	s_addc_u32 s3, s93, 0
	s_add_i32 s67, s76, s28
	global_load_lds_dwordx4 v[194:195], off
	v_lshl_add_u64 v[196:197], s[2:3], 0, v[216:217]
	s_mov_b32 m0, s67
	v_lshl_add_u64 v[198:199], s[94:95], 0, v[226:227]
	global_load_lds_dwordx4 v[196:197], off
	v_lshl_add_u64 v[196:197], s[2:3], 0, v[228:229]
	s_add_i32 m0, s67, 0x2000
	s_nop 0
	global_load_lds_dwordx4 v[196:197], off
	v_lshl_add_u64 v[196:197], s[94:95], 0, v[224:225]
	s_mov_b32 m0, s39
	s_nop 0
	global_load_lds_dwordx4 v[196:197], off
	s_mov_b32 m0, s53
	s_nop 0
	global_load_lds_dwordx4 v[198:199], off
	s_waitcnt vmcnt(8)
	s_waitcnt lgkmcnt(0)
	s_barrier
	s_waitcnt lgkmcnt(0)
	v_mfma_f32_16x16x32_bf16 v[60:63], v[64:67], v[152:155], 0
	v_mfma_f32_16x16x32_bf16 v[56:59], v[88:91], v[152:155], 0
	v_mfma_f32_16x16x32_bf16 v[44:47], v[64:67], v[160:163], 0
	v_mfma_f32_16x16x32_bf16 v[40:43], v[88:91], v[160:163], 0
	v_mfma_f32_16x16x32_bf16 v[28:31], v[64:67], v[168:171], 0
	v_mfma_f32_16x16x32_bf16 v[24:27], v[88:91], v[168:171], 0
	v_mfma_f32_16x16x32_bf16 v[12:15], v[64:67], v[184:187], 0
	v_mfma_f32_16x16x32_bf16 v[8:11], v[88:91], v[184:187], 0
	v_mfma_f32_16x16x32_bf16 v[60:63], v[72:75], v[156:159], v[60:63]
	v_mfma_f32_16x16x32_bf16 v[56:59], v[96:99], v[156:159], v[56:59]
	v_mfma_f32_16x16x32_bf16 v[44:47], v[72:75], v[164:167], v[44:47]
	v_mfma_f32_16x16x32_bf16 v[40:43], v[96:99], v[164:167], v[40:43]
	v_mfma_f32_16x16x32_bf16 v[28:31], v[72:75], v[180:183], v[28:31]
	v_mfma_f32_16x16x32_bf16 v[24:27], v[96:99], v[180:183], v[24:27]
	v_mfma_f32_16x16x32_bf16 v[12:15], v[72:75], v[188:191], v[12:15]
	v_mfma_f32_16x16x32_bf16 v[8:11], v[96:99], v[188:191], v[8:11]
	v_mfma_f32_16x16x32_bf16 v[52:55], v[108:111], v[152:155], 0
	v_mfma_f32_16x16x32_bf16 v[48:51], v[128:131], v[152:155], 0
	v_mfma_f32_16x16x32_bf16 v[36:39], v[108:111], v[160:163], 0
	v_mfma_f32_16x16x32_bf16 v[32:35], v[128:131], v[160:163], 0
	v_mfma_f32_16x16x32_bf16 v[20:23], v[108:111], v[168:171], 0
	v_mfma_f32_16x16x32_bf16 v[16:19], v[128:131], v[168:171], 0
	v_mfma_f32_16x16x32_bf16 v[4:7], v[108:111], v[184:187], 0
	v_mfma_f32_16x16x32_bf16 v[0:3], v[128:131], v[184:187], 0
	v_mfma_f32_16x16x32_bf16 v[52:55], v[116:119], v[156:159], v[52:55]
	v_mfma_f32_16x16x32_bf16 v[48:51], v[140:143], v[156:159], v[48:51]
	v_mfma_f32_16x16x32_bf16 v[36:39], v[116:119], v[164:167], v[36:39]
	v_mfma_f32_16x16x32_bf16 v[32:35], v[140:143], v[164:167], v[32:35]
	v_mfma_f32_16x16x32_bf16 v[20:23], v[116:119], v[180:183], v[20:23]
	v_mfma_f32_16x16x32_bf16 v[16:19], v[140:143], v[180:183], v[16:19]
	v_mfma_f32_16x16x32_bf16 v[4:7], v[116:119], v[188:191], v[4:7]
	v_mfma_f32_16x16x32_bf16 v[0:3], v[140:143], v[188:191], v[0:3]
	s_barrier
	s_add_i32 s67, 0, 0x18000
	s_add_i32 s76, 0, 0x1c000
	v_add_u32_e32 v96, s67, v238
	v_add_u32_e32 v140, s76, v238
	ds_read_b128 v[64:67], v96
	ds_read_b128 v[72:75], v96 offset:1024
	ds_read_b128 v[88:91], v96 offset:2048
	ds_read_b128 v[96:99], v96 offset:3072
	ds_read_b128 v[108:111], v140
	ds_read_b128 v[116:119], v140 offset:1024
	ds_read_b128 v[128:131], v140 offset:2048
	ds_read_b128 v[140:143], v140 offset:3072
	s_add_u32 s2, s94, 0x80000
	s_addc_u32 s3, s95, 0
	s_mov_b32 m0, s55
	v_lshl_add_u64 v[200:201], s[2:3], 0, v[224:225]
	ds_read_b128 v[152:155], v240 offset:32768
	ds_read_b128 v[156:159], v240 offset:33792
	ds_read_b128 v[160:163], v240 offset:34816
	ds_read_b128 v[164:167], v240 offset:35840
	ds_read_b128 v[168:171], v240 offset:36864
	ds_read_b128 v[180:183], v240 offset:37888
	ds_read_b128 v[184:187], v240 offset:38912
	ds_read_b128 v[188:191], v240 offset:39936
	global_load_lds_dwordx4 v[200:201], off
	v_lshl_add_u64 v[200:201], s[2:3], 0, v[226:227]
	s_mov_b32 m0, s56
	s_nop 0
	global_load_lds_dwordx4 v[200:201], off
	s_waitcnt vmcnt(8)
	s_waitcnt lgkmcnt(0)
	s_barrier
	s_waitcnt lgkmcnt(0)
	v_mfma_f32_16x16x32_bf16 v[176:179], v[64:67], v[152:155], v[176:179]
	v_mfma_f32_16x16x32_bf16 v[172:175], v[88:91], v[152:155], v[172:175]
	v_mfma_f32_16x16x32_bf16 v[136:139], v[64:67], v[160:163], v[136:139]
	v_mfma_f32_16x16x32_bf16 v[132:135], v[88:91], v[160:163], v[132:135]
	v_mfma_f32_16x16x32_bf16 v[112:115], v[64:67], v[168:171], v[112:115]
	v_mfma_f32_16x16x32_bf16 v[104:107], v[88:91], v[168:171], v[104:107]
	v_mfma_f32_16x16x32_bf16 v[84:87], v[64:67], v[184:187], v[84:87]
	v_mfma_f32_16x16x32_bf16 v[80:83], v[88:91], v[184:187], v[80:83]
	v_mfma_f32_16x16x32_bf16 v[176:179], v[72:75], v[156:159], v[176:179]
	v_mfma_f32_16x16x32_bf16 v[172:175], v[96:99], v[156:159], v[172:175]
	v_mfma_f32_16x16x32_bf16 v[136:139], v[72:75], v[164:167], v[136:139]
	v_mfma_f32_16x16x32_bf16 v[132:135], v[96:99], v[164:167], v[132:135]
	v_mfma_f32_16x16x32_bf16 v[112:115], v[72:75], v[180:183], v[112:115]
	v_mfma_f32_16x16x32_bf16 v[104:107], v[96:99], v[180:183], v[104:107]
	v_mfma_f32_16x16x32_bf16 v[84:87], v[72:75], v[188:191], v[84:87]
	v_mfma_f32_16x16x32_bf16 v[80:83], v[96:99], v[188:191], v[80:83]
	v_mfma_f32_16x16x32_bf16 v[148:151], v[108:111], v[152:155], v[148:151]
	v_mfma_f32_16x16x32_bf16 v[144:147], v[128:131], v[152:155], v[144:147]
	v_mfma_f32_16x16x32_bf16 v[124:127], v[108:111], v[160:163], v[124:127]
	v_mfma_f32_16x16x32_bf16 v[120:123], v[128:131], v[160:163], v[120:123]
	v_mfma_f32_16x16x32_bf16 v[100:103], v[108:111], v[168:171], v[100:103]
	v_mfma_f32_16x16x32_bf16 v[92:95], v[128:131], v[168:171], v[92:95]
	v_mfma_f32_16x16x32_bf16 v[76:79], v[108:111], v[184:187], v[76:79]
	v_mfma_f32_16x16x32_bf16 v[68:71], v[128:131], v[184:187], v[68:71]
	v_mfma_f32_16x16x32_bf16 v[148:151], v[116:119], v[156:159], v[148:151]
	v_mfma_f32_16x16x32_bf16 v[144:147], v[140:143], v[156:159], v[144:147]
	v_mfma_f32_16x16x32_bf16 v[124:127], v[116:119], v[164:167], v[124:127]
	v_mfma_f32_16x16x32_bf16 v[120:123], v[140:143], v[164:167], v[120:123]
	v_mfma_f32_16x16x32_bf16 v[100:103], v[116:119], v[180:183], v[100:103]
	v_mfma_f32_16x16x32_bf16 v[92:95], v[140:143], v[180:183], v[92:95]
	v_mfma_f32_16x16x32_bf16 v[76:79], v[116:119], v[188:191], v[76:79]
	v_mfma_f32_16x16x32_bf16 v[68:71], v[140:143], v[188:191], v[68:71]
	s_barrier
	s_add_i32 s2, s67, s28
	v_lshl_add_u64 v[192:193], v[192:193], 0, s[30:31]
	s_mov_b32 m0, s2
	ds_read_b128 v[152:155], v240 offset:49152
	ds_read_b128 v[156:159], v240 offset:50176
	ds_read_b128 v[160:163], v240 offset:51200
	ds_read_b128 v[164:167], v240 offset:52224
	ds_read_b128 v[168:171], v240 offset:53248
	ds_read_b128 v[180:183], v240 offset:54272
	ds_read_b128 v[184:187], v240 offset:55296
	ds_read_b128 v[188:191], v240 offset:56320
	global_load_lds_dwordx4 v[192:193], off
	s_add_i32 m0, s2, 0x2000
	s_add_u32 s2, s92, 0x80080
	v_lshl_add_u64 v[192:193], v[194:195], 0, s[30:31]
	s_addc_u32 s3, s93, 0
	s_add_i32 s67, s76, s28
	global_load_lds_dwordx4 v[192:193], off
	v_lshl_add_u64 v[192:193], s[2:3], 0, v[216:217]
	s_mov_b32 m0, s67
	s_nop 0
	global_load_lds_dwordx4 v[192:193], off
	v_lshl_add_u64 v[192:193], s[2:3], 0, v[228:229]
	s_add_i32 m0, s67, 0x2000
	s_nop 0
	global_load_lds_dwordx4 v[192:193], off
	v_lshl_add_u64 v[192:193], v[196:197], 0, s[30:31]
	s_mov_b32 m0, s70
	s_nop 0
	global_load_lds_dwordx4 v[192:193], off
	v_lshl_add_u64 v[192:193], v[198:199], 0, s[30:31]
	s_mov_b32 m0, s71
	s_nop 0
	global_load_lds_dwordx4 v[192:193], off
	s_waitcnt vmcnt(8)
	s_waitcnt lgkmcnt(0)
	s_barrier
	s_waitcnt lgkmcnt(0)
	v_mfma_f32_16x16x32_bf16 v[60:63], v[64:67], v[152:155], v[60:63]
	v_mfma_f32_16x16x32_bf16 v[56:59], v[88:91], v[152:155], v[56:59]
	v_mfma_f32_16x16x32_bf16 v[44:47], v[64:67], v[160:163], v[44:47]
	v_mfma_f32_16x16x32_bf16 v[40:43], v[88:91], v[160:163], v[40:43]
	v_mfma_f32_16x16x32_bf16 v[28:31], v[64:67], v[168:171], v[28:31]
	v_mfma_f32_16x16x32_bf16 v[24:27], v[88:91], v[168:171], v[24:27]
	v_mfma_f32_16x16x32_bf16 v[12:15], v[64:67], v[184:187], v[12:15]
	v_mfma_f32_16x16x32_bf16 v[8:11], v[88:91], v[184:187], v[8:11]
	v_mfma_f32_16x16x32_bf16 v[60:63], v[72:75], v[156:159], v[60:63]
	v_mfma_f32_16x16x32_bf16 v[56:59], v[96:99], v[156:159], v[56:59]
	v_mfma_f32_16x16x32_bf16 v[44:47], v[72:75], v[164:167], v[44:47]
	v_mfma_f32_16x16x32_bf16 v[40:43], v[96:99], v[164:167], v[40:43]
	v_mfma_f32_16x16x32_bf16 v[28:31], v[72:75], v[180:183], v[28:31]
	v_mfma_f32_16x16x32_bf16 v[24:27], v[96:99], v[180:183], v[24:27]
	v_mfma_f32_16x16x32_bf16 v[12:15], v[72:75], v[188:191], v[12:15]
	v_mfma_f32_16x16x32_bf16 v[8:11], v[96:99], v[188:191], v[8:11]
	v_mfma_f32_16x16x32_bf16 v[52:55], v[108:111], v[152:155], v[52:55]
	v_mfma_f32_16x16x32_bf16 v[48:51], v[128:131], v[152:155], v[48:51]
	v_mfma_f32_16x16x32_bf16 v[36:39], v[108:111], v[160:163], v[36:39]
	v_mfma_f32_16x16x32_bf16 v[32:35], v[128:131], v[160:163], v[32:35]
	v_mfma_f32_16x16x32_bf16 v[20:23], v[108:111], v[168:171], v[20:23]
	v_mfma_f32_16x16x32_bf16 v[16:19], v[128:131], v[168:171], v[16:19]
	v_mfma_f32_16x16x32_bf16 v[4:7], v[108:111], v[184:187], v[4:7]
	v_mfma_f32_16x16x32_bf16 v[0:3], v[128:131], v[184:187], v[0:3]
	v_mfma_f32_16x16x32_bf16 v[52:55], v[116:119], v[156:159], v[52:55]
	v_mfma_f32_16x16x32_bf16 v[48:51], v[140:143], v[156:159], v[48:51]
	v_mfma_f32_16x16x32_bf16 v[36:39], v[116:119], v[164:167], v[36:39]
	v_mfma_f32_16x16x32_bf16 v[32:35], v[140:143], v[164:167], v[32:35]
	v_mfma_f32_16x16x32_bf16 v[20:23], v[116:119], v[180:183], v[20:23]
	v_mfma_f32_16x16x32_bf16 v[16:19], v[140:143], v[180:183], v[16:19]
	v_mfma_f32_16x16x32_bf16 v[4:7], v[116:119], v[188:191], v[4:7]
	v_mfma_f32_16x16x32_bf16 v[0:3], v[140:143], v[188:191], v[0:3]
	s_barrier
	s_add_i32 s20, s20, 2
	s_add_u32 s90, s90, 0x100
	s_addc_u32 s91, s91, 0
	s_add_u32 s89, s89, 0x100
	s_addc_u32 s14, s14, 0
.LBB0_595:
	s_add_u32 s2, s90, 0xfff80080
	s_addc_u32 s3, s91, -1
	s_add_i32 s67, 0, 0x10000
	s_cmp_eq_u32 s20, 28
	s_cselect_b32 s95, s81, s3
	s_cselect_b32 s94, vcc_lo, s2
	s_cselect_b32 s93, s79, s14
	s_cselect_b32 s92, vcc_hi, s89
	s_add_i32 s76, 0, 0x14000
	v_add_u32_e32 v96, s67, v238
	v_add_u32_e32 v140, s76, v238
	ds_read_b128 v[64:67], v96
	ds_read_b128 v[72:75], v96 offset:1024
	ds_read_b128 v[88:91], v96 offset:2048
	ds_read_b128 v[96:99], v96 offset:3072
	ds_read_b128 v[108:111], v140
	ds_read_b128 v[116:119], v140 offset:1024
	ds_read_b128 v[128:131], v140 offset:2048
	ds_read_b128 v[140:143], v140 offset:3072
	v_lshl_add_u64 v[192:193], s[90:91], 0, v[230:231]
	s_add_i32 m0, s39, 0xc000
	ds_read_b128 v[152:155], v240
	ds_read_b128 v[156:159], v240 offset:1024
	ds_read_b128 v[160:163], v240 offset:2048
	ds_read_b128 v[164:167], v240 offset:3072
	ds_read_b128 v[168:171], v240 offset:4096
	ds_read_b128 v[180:183], v240 offset:5120
	ds_read_b128 v[184:187], v240 offset:6144
	ds_read_b128 v[188:191], v240 offset:7168
	global_load_lds_dwordx4 v[192:193], off
	v_lshl_add_u64 v[192:193], s[90:91], 0, v[232:233]
	s_add_i32 m0, s39, 0xe000
	s_nop 0
	global_load_lds_dwordx4 v[192:193], off
	s_waitcnt vmcnt(8)
	s_waitcnt lgkmcnt(0)
	s_barrier
	s_waitcnt lgkmcnt(0)
	v_mfma_f32_16x16x32_bf16 v[176:179], v[64:67], v[152:155], v[176:179]
	v_mfma_f32_16x16x32_bf16 v[172:175], v[88:91], v[152:155], v[172:175]
	v_mfma_f32_16x16x32_bf16 v[136:139], v[64:67], v[160:163], v[136:139]
	v_mfma_f32_16x16x32_bf16 v[132:135], v[88:91], v[160:163], v[132:135]
	v_mfma_f32_16x16x32_bf16 v[112:115], v[64:67], v[168:171], v[112:115]
	v_mfma_f32_16x16x32_bf16 v[104:107], v[88:91], v[168:171], v[104:107]
	v_mfma_f32_16x16x32_bf16 v[84:87], v[64:67], v[184:187], v[84:87]
	v_mfma_f32_16x16x32_bf16 v[80:83], v[88:91], v[184:187], v[80:83]
	v_mfma_f32_16x16x32_bf16 v[176:179], v[72:75], v[156:159], v[176:179]
	v_mfma_f32_16x16x32_bf16 v[172:175], v[96:99], v[156:159], v[172:175]
	v_mfma_f32_16x16x32_bf16 v[136:139], v[72:75], v[164:167], v[136:139]
	v_mfma_f32_16x16x32_bf16 v[132:135], v[96:99], v[164:167], v[132:135]
	v_mfma_f32_16x16x32_bf16 v[112:115], v[72:75], v[180:183], v[112:115]
	v_mfma_f32_16x16x32_bf16 v[104:107], v[96:99], v[180:183], v[104:107]
	v_mfma_f32_16x16x32_bf16 v[84:87], v[72:75], v[188:191], v[84:87]
	v_mfma_f32_16x16x32_bf16 v[80:83], v[96:99], v[188:191], v[80:83]
	v_mfma_f32_16x16x32_bf16 v[148:151], v[108:111], v[152:155], v[148:151]
	v_mfma_f32_16x16x32_bf16 v[144:147], v[128:131], v[152:155], v[144:147]
	v_mfma_f32_16x16x32_bf16 v[124:127], v[108:111], v[160:163], v[124:127]
	v_mfma_f32_16x16x32_bf16 v[120:123], v[128:131], v[160:163], v[120:123]
	v_mfma_f32_16x16x32_bf16 v[100:103], v[108:111], v[168:171], v[100:103]
	v_mfma_f32_16x16x32_bf16 v[92:95], v[128:131], v[168:171], v[92:95]
	v_mfma_f32_16x16x32_bf16 v[76:79], v[108:111], v[184:187], v[76:79]
	v_mfma_f32_16x16x32_bf16 v[68:71], v[128:131], v[184:187], v[68:71]
	v_mfma_f32_16x16x32_bf16 v[148:151], v[116:119], v[156:159], v[148:151]
	v_mfma_f32_16x16x32_bf16 v[144:147], v[140:143], v[156:159], v[144:147]
	v_mfma_f32_16x16x32_bf16 v[124:127], v[116:119], v[164:167], v[124:127]
	v_mfma_f32_16x16x32_bf16 v[120:123], v[140:143], v[164:167], v[120:123]
	v_mfma_f32_16x16x32_bf16 v[100:103], v[116:119], v[180:183], v[100:103]
	v_mfma_f32_16x16x32_bf16 v[92:95], v[140:143], v[180:183], v[92:95]
	v_mfma_f32_16x16x32_bf16 v[76:79], v[116:119], v[188:191], v[76:79]
	v_mfma_f32_16x16x32_bf16 v[68:71], v[140:143], v[188:191], v[68:71]
	s_barrier
	s_add_i32 s2, s67, s28
	v_lshl_add_u64 v[192:193], s[92:93], 0, v[216:217]
	s_mov_b32 m0, s2
	ds_read_b128 v[152:155], v240 offset:16384
	ds_read_b128 v[156:159], v240 offset:17408
	ds_read_b128 v[160:163], v240 offset:18432
	ds_read_b128 v[164:167], v240 offset:19456
	ds_read_b128 v[168:171], v240 offset:20480
	ds_read_b128 v[180:183], v240 offset:21504
	ds_read_b128 v[184:187], v240 offset:22528
	ds_read_b128 v[188:191], v240 offset:23552
	global_load_lds_dwordx4 v[192:193], off
	s_add_i32 m0, s2, 0x2000
	s_add_u32 s2, s92, 0x80000
	v_lshl_add_u64 v[194:195], s[92:93], 0, v[228:229]
	s_addc_u32 s3, s93, 0
	s_add_i32 s67, s76, s28
	global_load_lds_dwordx4 v[194:195], off
	v_lshl_add_u64 v[196:197], s[2:3], 0, v[216:217]
	s_mov_b32 m0, s67
	v_lshl_add_u64 v[198:199], s[94:95], 0, v[226:227]
	global_load_lds_dwordx4 v[196:197], off
	v_lshl_add_u64 v[196:197], s[2:3], 0, v[228:229]
	s_add_i32 m0, s67, 0x2000
	s_nop 0
	global_load_lds_dwordx4 v[196:197], off
	v_lshl_add_u64 v[196:197], s[94:95], 0, v[224:225]
	s_mov_b32 m0, s39
	s_nop 0
	global_load_lds_dwordx4 v[196:197], off
	s_mov_b32 m0, s53
	s_nop 0
	global_load_lds_dwordx4 v[198:199], off
	s_waitcnt vmcnt(8)
	s_waitcnt lgkmcnt(0)
	s_barrier
	s_waitcnt lgkmcnt(0)
	v_mfma_f32_16x16x32_bf16 v[60:63], v[64:67], v[152:155], v[60:63]
	v_mfma_f32_16x16x32_bf16 v[56:59], v[88:91], v[152:155], v[56:59]
	v_mfma_f32_16x16x32_bf16 v[44:47], v[64:67], v[160:163], v[44:47]
	v_mfma_f32_16x16x32_bf16 v[40:43], v[88:91], v[160:163], v[40:43]
	v_mfma_f32_16x16x32_bf16 v[28:31], v[64:67], v[168:171], v[28:31]
	v_mfma_f32_16x16x32_bf16 v[24:27], v[88:91], v[168:171], v[24:27]
	v_mfma_f32_16x16x32_bf16 v[12:15], v[64:67], v[184:187], v[12:15]
	v_mfma_f32_16x16x32_bf16 v[8:11], v[88:91], v[184:187], v[8:11]
	v_mfma_f32_16x16x32_bf16 v[60:63], v[72:75], v[156:159], v[60:63]
	v_mfma_f32_16x16x32_bf16 v[56:59], v[96:99], v[156:159], v[56:59]
	v_mfma_f32_16x16x32_bf16 v[44:47], v[72:75], v[164:167], v[44:47]
	v_mfma_f32_16x16x32_bf16 v[40:43], v[96:99], v[164:167], v[40:43]
	v_mfma_f32_16x16x32_bf16 v[28:31], v[72:75], v[180:183], v[28:31]
	v_mfma_f32_16x16x32_bf16 v[24:27], v[96:99], v[180:183], v[24:27]
	v_mfma_f32_16x16x32_bf16 v[12:15], v[72:75], v[188:191], v[12:15]
	v_mfma_f32_16x16x32_bf16 v[8:11], v[96:99], v[188:191], v[8:11]
	v_mfma_f32_16x16x32_bf16 v[52:55], v[108:111], v[152:155], v[52:55]
	v_mfma_f32_16x16x32_bf16 v[48:51], v[128:131], v[152:155], v[48:51]
	v_mfma_f32_16x16x32_bf16 v[36:39], v[108:111], v[160:163], v[36:39]
	v_mfma_f32_16x16x32_bf16 v[32:35], v[128:131], v[160:163], v[32:35]
	v_mfma_f32_16x16x32_bf16 v[20:23], v[108:111], v[168:171], v[20:23]
	v_mfma_f32_16x16x32_bf16 v[16:19], v[128:131], v[168:171], v[16:19]
	v_mfma_f32_16x16x32_bf16 v[4:7], v[108:111], v[184:187], v[4:7]
	v_mfma_f32_16x16x32_bf16 v[0:3], v[128:131], v[184:187], v[0:3]
	v_mfma_f32_16x16x32_bf16 v[52:55], v[116:119], v[156:159], v[52:55]
	v_mfma_f32_16x16x32_bf16 v[48:51], v[140:143], v[156:159], v[48:51]
	v_mfma_f32_16x16x32_bf16 v[36:39], v[116:119], v[164:167], v[36:39]
	v_mfma_f32_16x16x32_bf16 v[32:35], v[140:143], v[164:167], v[32:35]
	v_mfma_f32_16x16x32_bf16 v[20:23], v[116:119], v[180:183], v[20:23]
	v_mfma_f32_16x16x32_bf16 v[16:19], v[140:143], v[180:183], v[16:19]
	v_mfma_f32_16x16x32_bf16 v[4:7], v[116:119], v[188:191], v[4:7]
	v_mfma_f32_16x16x32_bf16 v[0:3], v[140:143], v[188:191], v[0:3]
	s_barrier
	s_add_i32 s67, 0, 0x18000
	s_add_i32 s76, 0, 0x1c000
	v_add_u32_e32 v96, s67, v238
	v_add_u32_e32 v140, s76, v238
	ds_read_b128 v[64:67], v96
	ds_read_b128 v[72:75], v96 offset:1024
	ds_read_b128 v[88:91], v96 offset:2048
	ds_read_b128 v[96:99], v96 offset:3072
	ds_read_b128 v[108:111], v140
	ds_read_b128 v[116:119], v140 offset:1024
	ds_read_b128 v[128:131], v140 offset:2048
	ds_read_b128 v[140:143], v140 offset:3072
	s_add_u32 s2, s94, 0x80000
	s_addc_u32 s3, s95, 0
	s_mov_b32 m0, s55
	v_lshl_add_u64 v[200:201], s[2:3], 0, v[224:225]
	ds_read_b128 v[152:155], v240 offset:32768
	ds_read_b128 v[156:159], v240 offset:33792
	ds_read_b128 v[160:163], v240 offset:34816
	ds_read_b128 v[164:167], v240 offset:35840
	ds_read_b128 v[168:171], v240 offset:36864
	ds_read_b128 v[180:183], v240 offset:37888
	ds_read_b128 v[184:187], v240 offset:38912
	ds_read_b128 v[188:191], v240 offset:39936
	global_load_lds_dwordx4 v[200:201], off
	v_lshl_add_u64 v[200:201], s[2:3], 0, v[226:227]
	s_mov_b32 m0, s56
	s_nop 0
	global_load_lds_dwordx4 v[200:201], off
	s_waitcnt vmcnt(8)
	s_waitcnt lgkmcnt(0)
	s_barrier
	s_waitcnt lgkmcnt(0)
	v_mfma_f32_16x16x32_bf16 v[176:179], v[64:67], v[152:155], v[176:179]
	v_mfma_f32_16x16x32_bf16 v[172:175], v[88:91], v[152:155], v[172:175]
	v_mfma_f32_16x16x32_bf16 v[136:139], v[64:67], v[160:163], v[136:139]
	v_mfma_f32_16x16x32_bf16 v[132:135], v[88:91], v[160:163], v[132:135]
	v_mfma_f32_16x16x32_bf16 v[112:115], v[64:67], v[168:171], v[112:115]
	v_mfma_f32_16x16x32_bf16 v[104:107], v[88:91], v[168:171], v[104:107]
	v_mfma_f32_16x16x32_bf16 v[84:87], v[64:67], v[184:187], v[84:87]
	v_mfma_f32_16x16x32_bf16 v[80:83], v[88:91], v[184:187], v[80:83]
	v_mfma_f32_16x16x32_bf16 v[176:179], v[72:75], v[156:159], v[176:179]
	v_mfma_f32_16x16x32_bf16 v[172:175], v[96:99], v[156:159], v[172:175]
	v_mfma_f32_16x16x32_bf16 v[136:139], v[72:75], v[164:167], v[136:139]
	v_mfma_f32_16x16x32_bf16 v[132:135], v[96:99], v[164:167], v[132:135]
	v_mfma_f32_16x16x32_bf16 v[112:115], v[72:75], v[180:183], v[112:115]
	v_mfma_f32_16x16x32_bf16 v[104:107], v[96:99], v[180:183], v[104:107]
	v_mfma_f32_16x16x32_bf16 v[84:87], v[72:75], v[188:191], v[84:87]
	v_mfma_f32_16x16x32_bf16 v[80:83], v[96:99], v[188:191], v[80:83]
	v_mfma_f32_16x16x32_bf16 v[148:151], v[108:111], v[152:155], v[148:151]
	v_mfma_f32_16x16x32_bf16 v[144:147], v[128:131], v[152:155], v[144:147]
	v_mfma_f32_16x16x32_bf16 v[124:127], v[108:111], v[160:163], v[124:127]
	v_mfma_f32_16x16x32_bf16 v[120:123], v[128:131], v[160:163], v[120:123]
	v_mfma_f32_16x16x32_bf16 v[100:103], v[108:111], v[168:171], v[100:103]
	v_mfma_f32_16x16x32_bf16 v[92:95], v[128:131], v[168:171], v[92:95]
	v_mfma_f32_16x16x32_bf16 v[76:79], v[108:111], v[184:187], v[76:79]
	v_mfma_f32_16x16x32_bf16 v[68:71], v[128:131], v[184:187], v[68:71]
	v_mfma_f32_16x16x32_bf16 v[148:151], v[116:119], v[156:159], v[148:151]
	v_mfma_f32_16x16x32_bf16 v[144:147], v[140:143], v[156:159], v[144:147]
	v_mfma_f32_16x16x32_bf16 v[124:127], v[116:119], v[164:167], v[124:127]
	v_mfma_f32_16x16x32_bf16 v[120:123], v[140:143], v[164:167], v[120:123]
	v_mfma_f32_16x16x32_bf16 v[100:103], v[116:119], v[180:183], v[100:103]
	v_mfma_f32_16x16x32_bf16 v[92:95], v[140:143], v[180:183], v[92:95]
	v_mfma_f32_16x16x32_bf16 v[76:79], v[116:119], v[188:191], v[76:79]
	v_mfma_f32_16x16x32_bf16 v[68:71], v[140:143], v[188:191], v[68:71]
	s_barrier
	s_add_i32 s2, s67, s28
	v_lshl_add_u64 v[192:193], v[192:193], 0, s[30:31]
	s_mov_b32 m0, s2
	ds_read_b128 v[152:155], v240 offset:49152
	ds_read_b128 v[156:159], v240 offset:50176
	ds_read_b128 v[160:163], v240 offset:51200
	ds_read_b128 v[164:167], v240 offset:52224
	ds_read_b128 v[168:171], v240 offset:53248
	ds_read_b128 v[180:183], v240 offset:54272
	ds_read_b128 v[184:187], v240 offset:55296
	ds_read_b128 v[188:191], v240 offset:56320
	global_load_lds_dwordx4 v[192:193], off
	s_add_i32 m0, s2, 0x2000
	s_add_u32 s2, s92, 0x80080
	v_lshl_add_u64 v[192:193], v[194:195], 0, s[30:31]
	s_addc_u32 s3, s93, 0
	s_add_i32 s67, s76, s28
	global_load_lds_dwordx4 v[192:193], off
	v_lshl_add_u64 v[192:193], s[2:3], 0, v[216:217]
	s_mov_b32 m0, s67
	s_nop 0
	global_load_lds_dwordx4 v[192:193], off
	v_lshl_add_u64 v[192:193], s[2:3], 0, v[228:229]
	s_add_i32 m0, s67, 0x2000
	s_nop 0
	global_load_lds_dwordx4 v[192:193], off
	v_lshl_add_u64 v[192:193], v[196:197], 0, s[30:31]
	s_mov_b32 m0, s70
	s_nop 0
	global_load_lds_dwordx4 v[192:193], off
	v_lshl_add_u64 v[192:193], v[198:199], 0, s[30:31]
	s_mov_b32 m0, s71
	s_nop 0
	global_load_lds_dwordx4 v[192:193], off
	s_waitcnt vmcnt(8)
	s_waitcnt lgkmcnt(0)
	s_barrier
	s_waitcnt lgkmcnt(0)
	v_mfma_f32_16x16x32_bf16 v[60:63], v[64:67], v[152:155], v[60:63]
	v_mfma_f32_16x16x32_bf16 v[56:59], v[88:91], v[152:155], v[56:59]
	v_mfma_f32_16x16x32_bf16 v[44:47], v[64:67], v[160:163], v[44:47]
	v_mfma_f32_16x16x32_bf16 v[40:43], v[88:91], v[160:163], v[40:43]
	v_mfma_f32_16x16x32_bf16 v[28:31], v[64:67], v[168:171], v[28:31]
	v_mfma_f32_16x16x32_bf16 v[24:27], v[88:91], v[168:171], v[24:27]
	v_mfma_f32_16x16x32_bf16 v[12:15], v[64:67], v[184:187], v[12:15]
	v_mfma_f32_16x16x32_bf16 v[8:11], v[88:91], v[184:187], v[8:11]
	v_mfma_f32_16x16x32_bf16 v[60:63], v[72:75], v[156:159], v[60:63]
	v_mfma_f32_16x16x32_bf16 v[56:59], v[96:99], v[156:159], v[56:59]
	v_mfma_f32_16x16x32_bf16 v[44:47], v[72:75], v[164:167], v[44:47]
	v_mfma_f32_16x16x32_bf16 v[40:43], v[96:99], v[164:167], v[40:43]
	v_mfma_f32_16x16x32_bf16 v[28:31], v[72:75], v[180:183], v[28:31]
	v_mfma_f32_16x16x32_bf16 v[24:27], v[96:99], v[180:183], v[24:27]
	v_mfma_f32_16x16x32_bf16 v[12:15], v[72:75], v[188:191], v[12:15]
	v_mfma_f32_16x16x32_bf16 v[8:11], v[96:99], v[188:191], v[8:11]
	v_mfma_f32_16x16x32_bf16 v[52:55], v[108:111], v[152:155], v[52:55]
	v_mfma_f32_16x16x32_bf16 v[48:51], v[128:131], v[152:155], v[48:51]
	v_mfma_f32_16x16x32_bf16 v[36:39], v[108:111], v[160:163], v[36:39]
	v_mfma_f32_16x16x32_bf16 v[32:35], v[128:131], v[160:163], v[32:35]
	v_mfma_f32_16x16x32_bf16 v[20:23], v[108:111], v[168:171], v[20:23]
	v_mfma_f32_16x16x32_bf16 v[16:19], v[128:131], v[168:171], v[16:19]
	v_mfma_f32_16x16x32_bf16 v[4:7], v[108:111], v[184:187], v[4:7]
	v_mfma_f32_16x16x32_bf16 v[0:3], v[128:131], v[184:187], v[0:3]
	v_mfma_f32_16x16x32_bf16 v[52:55], v[116:119], v[156:159], v[52:55]
	v_mfma_f32_16x16x32_bf16 v[48:51], v[140:143], v[156:159], v[48:51]
	v_mfma_f32_16x16x32_bf16 v[36:39], v[116:119], v[164:167], v[36:39]
	v_mfma_f32_16x16x32_bf16 v[32:35], v[140:143], v[164:167], v[32:35]
	v_mfma_f32_16x16x32_bf16 v[20:23], v[116:119], v[180:183], v[20:23]
	v_mfma_f32_16x16x32_bf16 v[16:19], v[140:143], v[180:183], v[16:19]
	v_mfma_f32_16x16x32_bf16 v[4:7], v[116:119], v[188:191], v[4:7]
	v_mfma_f32_16x16x32_bf16 v[0:3], v[140:143], v[188:191], v[0:3]
	s_barrier
	s_add_i32 s20, s20, 2
	s_add_u32 s90, s90, 0x100
	s_addc_u32 s91, s91, 0
	s_add_u32 s89, s89, 0x100
	s_addc_u32 s14, s14, 0
	s_cmp_gt_u32 s20, 29
	s_cbranch_scc0 .LBB0_595
	s_and_b64 vcc, exec, s[74:75]
	s_cbranch_vccz .LBB0_598
	s_barrier

.LBB0_638:
	s_ashr_i32 s87, s86, 31
	s_lshl_b64 s[40:41], s[86:87], 20
	s_add_u32 s88, s14, s40
	s_addc_u32 s89, s15, s41
	s_and_b64 s[40:41], s[4:5], exec
	s_cselect_b32 s7, s89, s11
	s_cselect_b32 s9, s88, s10
	s_ashr_i32 s85, s84, 31
	s_lshl_b64 s[40:41], s[84:85], 20
	s_add_u32 s90, s24, s40
	s_addc_u32 s91, s26, s41
	s_and_b64 s[40:41], s[4:5], exec
	s_cselect_b32 s40, s91, s93
	s_cselect_b32 s41, s90, s92
	s_add_u32 s10, s10, 0x80080
	s_addc_u32 s11, s11, 0
	s_add_u32 s54, s92, 0x100
	s_addc_u32 s55, s93, 0
	s_mov_b32 s85, -2
	s_add_u32 s67, s10, 0xfff80080
	s_addc_u32 s87, s11, -1
	s_add_i32 s96, 0, 0x10000
	s_cmp_eq_u32 s85, 28
	s_cselect_b32 s95, s7, s87
	s_cselect_b32 s94, s9, s67
	s_cselect_b32 s93, s40, s55
	s_cselect_b32 s92, s41, s54
	s_add_i32 s67, 0, 0x14000
	v_add_u32_e32 v52, s96, v194
	v_add_u32_e32 v124, s67, v194
	ds_read_b128 v[40:43], v52
	ds_read_b128 v[44:47], v52 offset:1024
	ds_read_b128 v[48:51], v52 offset:2048
	ds_read_b128 v[52:55], v52 offset:3072
	ds_read_b128 v[64:67], v124
	ds_read_b128 v[100:103], v124 offset:1024
	ds_read_b128 v[120:123], v124 offset:2048
	ds_read_b128 v[124:127], v124 offset:3072
	v_lshl_add_u64 v[208:209], s[10:11], 0, v[186:187]
	s_add_i32 m0, s57, 0xc000
	ds_read_b128 v[136:139], v195
	ds_read_b128 v[140:143], v195 offset:1024
	ds_read_b128 v[144:147], v195 offset:2048
	ds_read_b128 v[172:175], v195 offset:3072
	ds_read_b128 v[190:193], v195 offset:4096
	ds_read_b128 v[196:199], v195 offset:5120
	ds_read_b128 v[200:203], v195 offset:6144
	ds_read_b128 v[204:207], v195 offset:7168
	global_load_lds_dwordx4 v[208:209], off
	v_lshl_add_u64 v[208:209], s[10:11], 0, v[188:189]
	s_add_i32 m0, s57, 0xe000
	s_nop 0
	global_load_lds_dwordx4 v[208:209], off
	s_waitcnt vmcnt(8)
	s_waitcnt lgkmcnt(0)
	s_barrier
	s_waitcnt lgkmcnt(0)
	v_mfma_f32_16x16x32_bf16 v[168:171], v[40:43], v[136:139], 0
	v_mfma_f32_16x16x32_bf16 v[164:167], v[48:51], v[136:139], 0
	v_mfma_f32_16x16x32_bf16 v[152:155], v[40:43], v[144:147], 0
	v_mfma_f32_16x16x32_bf16 v[148:151], v[48:51], v[144:147], 0
	v_mfma_f32_16x16x32_bf16 v[116:119], v[40:43], v[190:193], 0
	v_mfma_f32_16x16x32_bf16 v[112:115], v[48:51], v[190:193], 0
	v_mfma_f32_16x16x32_bf16 v[96:99], v[40:43], v[200:203], 0
	v_mfma_f32_16x16x32_bf16 v[92:95], v[48:51], v[200:203], 0
	v_mfma_f32_16x16x32_bf16 v[168:171], v[44:47], v[140:143], v[168:171]
	v_mfma_f32_16x16x32_bf16 v[164:167], v[52:55], v[140:143], v[164:167]
	v_mfma_f32_16x16x32_bf16 v[152:155], v[44:47], v[172:175], v[152:155]
	v_mfma_f32_16x16x32_bf16 v[148:151], v[52:55], v[172:175], v[148:151]
	v_mfma_f32_16x16x32_bf16 v[116:119], v[44:47], v[196:199], v[116:119]
	v_mfma_f32_16x16x32_bf16 v[112:115], v[52:55], v[196:199], v[112:115]
	v_mfma_f32_16x16x32_bf16 v[96:99], v[44:47], v[204:207], v[96:99]
	v_mfma_f32_16x16x32_bf16 v[92:95], v[52:55], v[204:207], v[92:95]
	v_mfma_f32_16x16x32_bf16 v[160:163], v[64:67], v[136:139], 0
	v_mfma_f32_16x16x32_bf16 v[132:135], v[64:67], v[144:147], 0
	v_mfma_f32_16x16x32_bf16 v[128:131], v[120:123], v[144:147], 0
	v_mfma_f32_16x16x32_bf16 v[108:111], v[64:67], v[190:193], 0
	v_mfma_f32_16x16x32_bf16 v[104:107], v[120:123], v[190:193], 0
	v_mfma_f32_16x16x32_bf16 v[88:91], v[64:67], v[200:203], 0
	v_mfma_f32_16x16x32_bf16 v[84:87], v[120:123], v[200:203], 0
	v_mfma_f32_16x16x32_bf16 v[160:163], v[100:103], v[140:143], v[160:163]
	v_mfma_f32_16x16x32_bf16 v[136:139], v[120:123], v[136:139], 0
	v_mfma_f32_16x16x32_bf16 v[132:135], v[100:103], v[172:175], v[132:135]
	v_mfma_f32_16x16x32_bf16 v[128:131], v[124:127], v[172:175], v[128:131]
	v_mfma_f32_16x16x32_bf16 v[108:111], v[100:103], v[196:199], v[108:111]
	v_mfma_f32_16x16x32_bf16 v[104:107], v[124:127], v[196:199], v[104:107]
	v_mfma_f32_16x16x32_bf16 v[88:91], v[100:103], v[204:207], v[88:91]
	v_mfma_f32_16x16x32_bf16 v[84:87], v[124:127], v[204:207], v[84:87]
	v_mfma_f32_16x16x32_bf16 v[136:139], v[124:127], v[140:143], v[136:139]
	s_barrier
	s_add_i32 s87, s96, s56
	v_lshl_add_u64 v[212:213], s[92:93], 0, v[178:179]
	s_mov_b32 m0, s87
	ds_read_b128 v[140:143], v195 offset:16384
	ds_read_b128 v[144:147], v195 offset:17408
	ds_read_b128 v[156:159], v195 offset:18432
	ds_read_b128 v[172:175], v195 offset:19456
	ds_read_b128 v[190:193], v195 offset:20480
	ds_read_b128 v[196:199], v195 offset:21504
	ds_read_b128 v[200:203], v195 offset:22528
	ds_read_b128 v[204:207], v195 offset:23552
	global_load_lds_dwordx4 v[212:213], off
	s_add_i32 m0, s87, 0x2000
	s_add_u32 vcc_lo, s92, 0x80000
	v_lshl_add_u64 v[214:215], s[92:93], 0, v[182:183]
	s_addc_u32 vcc_hi, s93, 0
	s_add_i32 s67, s67, s56
	global_load_lds_dwordx4 v[214:215], off
	v_lshl_add_u64 v[208:209], vcc, 0, v[178:179]
	s_mov_b32 m0, s67
	v_lshl_add_u64 v[224:225], s[94:95], 0, v[176:177]
	global_load_lds_dwordx4 v[208:209], off
	v_lshl_add_u64 v[208:209], vcc, 0, v[182:183]
	s_add_i32 m0, s67, 0x2000
	v_lshl_add_u64 v[226:227], s[94:95], 0, v[180:181]
	global_load_lds_dwordx4 v[208:209], off
	s_mov_b32 m0, s57
	s_nop 0
	global_load_lds_dwordx4 v[224:225], off
	s_mov_b32 m0, s61
	s_nop 0
	global_load_lds_dwordx4 v[226:227], off
	s_waitcnt vmcnt(8)
	s_waitcnt lgkmcnt(0)
	s_barrier
	s_waitcnt lgkmcnt(0)
	v_mfma_f32_16x16x32_bf16 v[80:83], v[40:43], v[140:143], 0
	v_mfma_f32_16x16x32_bf16 v[76:79], v[48:51], v[140:143], 0
	v_mfma_f32_16x16x32_bf16 v[60:63], v[40:43], v[156:159], 0
	v_mfma_f32_16x16x32_bf16 v[56:59], v[48:51], v[156:159], 0
	v_mfma_f32_16x16x32_bf16 v[28:31], v[40:43], v[190:193], 0
	v_mfma_f32_16x16x32_bf16 v[24:27], v[48:51], v[190:193], 0
	v_mfma_f32_16x16x32_bf16 v[12:15], v[40:43], v[200:203], 0
	v_mfma_f32_16x16x32_bf16 v[8:11], v[48:51], v[200:203], 0
	v_mfma_f32_16x16x32_bf16 v[80:83], v[44:47], v[144:147], v[80:83]
	v_mfma_f32_16x16x32_bf16 v[76:79], v[52:55], v[144:147], v[76:79]
	v_mfma_f32_16x16x32_bf16 v[60:63], v[44:47], v[172:175], v[60:63]
	v_mfma_f32_16x16x32_bf16 v[56:59], v[52:55], v[172:175], v[56:59]
	v_mfma_f32_16x16x32_bf16 v[28:31], v[44:47], v[196:199], v[28:31]
	v_mfma_f32_16x16x32_bf16 v[24:27], v[52:55], v[196:199], v[24:27]
	v_mfma_f32_16x16x32_bf16 v[12:15], v[44:47], v[204:207], v[12:15]
	v_mfma_f32_16x16x32_bf16 v[8:11], v[52:55], v[204:207], v[8:11]
	v_mfma_f32_16x16x32_bf16 v[36:39], v[64:67], v[156:159], 0
	v_mfma_f32_16x16x32_bf16 v[32:35], v[120:123], v[156:159], 0
	v_mfma_f32_16x16x32_bf16 v[20:23], v[64:67], v[190:193], 0
	v_mfma_f32_16x16x32_bf16 v[16:19], v[120:123], v[190:193], 0
	v_mfma_f32_16x16x32_bf16 v[4:7], v[64:67], v[200:203], 0
	v_mfma_f32_16x16x32_bf16 v[0:3], v[120:123], v[200:203], 0
	v_mfma_f32_16x16x32_bf16 v[40:43], v[64:67], v[140:143], 0
	v_mfma_f32_16x16x32_bf16 v[44:47], v[120:123], v[140:143], 0
	v_mfma_f32_16x16x32_bf16 v[36:39], v[100:103], v[172:175], v[36:39]
	v_mfma_f32_16x16x32_bf16 v[32:35], v[124:127], v[172:175], v[32:35]
	v_mfma_f32_16x16x32_bf16 v[20:23], v[100:103], v[196:199], v[20:23]
	v_mfma_f32_16x16x32_bf16 v[16:19], v[124:127], v[196:199], v[16:19]
	v_mfma_f32_16x16x32_bf16 v[4:7], v[100:103], v[204:207], v[4:7]
	v_mfma_f32_16x16x32_bf16 v[0:3], v[124:127], v[204:207], v[0:3]
	v_mfma_f32_16x16x32_bf16 v[40:43], v[100:103], v[144:147], v[40:43]
	v_mfma_f32_16x16x32_bf16 v[44:47], v[124:127], v[144:147], v[44:47]
	s_barrier
	s_add_i32 s67, 0, 0x18000
	s_add_i32 s87, 0, 0x1c000
	v_add_u32_e32 v68, s67, v194
	v_add_u32_e32 v72, s87, v194
	ds_read_b128 v[48:51], v68
	ds_read_b128 v[52:55], v68 offset:1024
	ds_read_b128 v[64:67], v68 offset:2048
	ds_read_b128 v[68:71], v68 offset:3072
	ds_read_b128 v[100:103], v72
	ds_read_b128 v[120:123], v72 offset:1024
	ds_read_b128 v[124:127], v72 offset:2048
	ds_read_b128 v[140:143], v72 offset:3072
	s_add_u32 s94, s94, 0x80000
	s_addc_u32 s95, s95, 0
	s_mov_b32 m0, s68
	v_lshl_add_u64 v[156:157], s[94:95], 0, v[176:177]
	ds_read_b128 v[72:75], v195 offset:32768
	ds_read_b128 v[144:147], v195 offset:33792
	ds_read_b128 v[172:175], v195 offset:34816
	ds_read_b128 v[190:193], v195 offset:35840
	ds_read_b128 v[196:199], v195 offset:36864
	ds_read_b128 v[200:203], v195 offset:37888
	ds_read_b128 v[204:207], v195 offset:38912
	ds_read_b128 v[208:211], v195 offset:39936
	global_load_lds_dwordx4 v[156:157], off
	v_lshl_add_u64 v[156:157], s[94:95], 0, v[180:181]
	s_mov_b32 m0, s69
	s_nop 0
	global_load_lds_dwordx4 v[156:157], off
	s_waitcnt vmcnt(8)
	s_waitcnt lgkmcnt(0)
	s_barrier
	s_waitcnt lgkmcnt(0)
	v_mfma_f32_16x16x32_bf16 v[156:159], v[48:51], v[72:75], v[168:171]
	v_mfma_f32_16x16x32_bf16 v[168:171], v[52:55], v[144:147], v[156:159]
	v_mfma_f32_16x16x32_bf16 v[156:159], v[64:67], v[72:75], v[164:167]
	v_mfma_f32_16x16x32_bf16 v[152:155], v[48:51], v[172:175], v[152:155]
	v_mfma_f32_16x16x32_bf16 v[148:151], v[64:67], v[172:175], v[148:151]
	v_mfma_f32_16x16x32_bf16 v[116:119], v[48:51], v[196:199], v[116:119]
	v_mfma_f32_16x16x32_bf16 v[112:115], v[64:67], v[196:199], v[112:115]
	v_mfma_f32_16x16x32_bf16 v[96:99], v[48:51], v[204:207], v[96:99]
	v_mfma_f32_16x16x32_bf16 v[92:95], v[64:67], v[204:207], v[92:95]
	v_mfma_f32_16x16x32_bf16 v[164:167], v[68:71], v[144:147], v[156:159]
	v_mfma_f32_16x16x32_bf16 v[152:155], v[52:55], v[190:193], v[152:155]
	v_mfma_f32_16x16x32_bf16 v[148:151], v[68:71], v[190:193], v[148:151]
	v_mfma_f32_16x16x32_bf16 v[116:119], v[52:55], v[200:203], v[116:119]
	v_mfma_f32_16x16x32_bf16 v[112:115], v[68:71], v[200:203], v[112:115]
	v_mfma_f32_16x16x32_bf16 v[96:99], v[52:55], v[208:211], v[96:99]
	v_mfma_f32_16x16x32_bf16 v[92:95], v[68:71], v[208:211], v[92:95]
	v_mfma_f32_16x16x32_bf16 v[156:159], v[100:103], v[72:75], v[160:163]
	v_mfma_f32_16x16x32_bf16 v[72:75], v[124:127], v[72:75], v[136:139]
	v_mfma_f32_16x16x32_bf16 v[160:163], v[120:123], v[144:147], v[156:159]
	v_mfma_f32_16x16x32_bf16 v[156:159], v[140:143], v[144:147], v[72:75]
	v_mfma_f32_16x16x32_bf16 v[72:75], v[100:103], v[172:175], v[132:135]
	v_mfma_f32_16x16x32_bf16 v[132:135], v[120:123], v[190:193], v[72:75]
	v_mfma_f32_16x16x32_bf16 v[72:75], v[124:127], v[172:175], v[128:131]
	v_mfma_f32_16x16x32_bf16 v[128:131], v[140:143], v[190:193], v[72:75]
	v_mfma_f32_16x16x32_bf16 v[72:75], v[100:103], v[196:199], v[108:111]
	v_mfma_f32_16x16x32_bf16 v[108:111], v[120:123], v[200:203], v[72:75]
	v_mfma_f32_16x16x32_bf16 v[72:75], v[124:127], v[196:199], v[104:107]
	v_mfma_f32_16x16x32_bf16 v[104:107], v[140:143], v[200:203], v[72:75]
	v_mfma_f32_16x16x32_bf16 v[72:75], v[100:103], v[204:207], v[88:91]
	v_mfma_f32_16x16x32_bf16 v[88:91], v[120:123], v[208:211], v[72:75]
	v_mfma_f32_16x16x32_bf16 v[72:75], v[124:127], v[204:207], v[84:87]
	v_mfma_f32_16x16x32_bf16 v[84:87], v[140:143], v[208:211], v[72:75]
	s_barrier
	s_add_i32 s67, s67, s56
	s_nop 3
	v_lshl_add_u64 v[72:73], v[212:213], 0, s[30:31]
	s_mov_b32 m0, s67
	ds_read_b128 v[136:139], v195 offset:49152
	ds_read_b128 v[144:147], v195 offset:50176
	ds_read_b128 v[172:175], v195 offset:51200
	ds_read_b128 v[190:193], v195 offset:52224
	ds_read_b128 v[196:199], v195 offset:53248
	ds_read_b128 v[200:203], v195 offset:54272
	ds_read_b128 v[204:207], v195 offset:55296
	ds_read_b128 v[208:211], v195 offset:56320
	global_load_lds_dwordx4 v[72:73], off
	s_add_i32 m0, s67, 0x2000
	s_add_u32 s92, s92, 0x80080
	v_lshl_add_u64 v[72:73], v[214:215], 0, s[30:31]
	s_addc_u32 s93, s93, 0
	s_add_i32 s67, s87, s56
	global_load_lds_dwordx4 v[72:73], off
	v_lshl_add_u64 v[72:73], s[92:93], 0, v[178:179]
	s_mov_b32 m0, s67
	s_nop 0
	global_load_lds_dwordx4 v[72:73], off
	v_lshl_add_u64 v[72:73], s[92:93], 0, v[182:183]
	s_add_i32 m0, s67, 0x2000
	s_nop 0
	global_load_lds_dwordx4 v[72:73], off
	v_lshl_add_u64 v[72:73], v[224:225], 0, s[30:31]
	s_mov_b32 m0, s2
	s_nop 0
	global_load_lds_dwordx4 v[72:73], off
	v_lshl_add_u64 v[72:73], v[226:227], 0, s[30:31]
	s_mov_b32 m0, s28
	s_nop 0
	global_load_lds_dwordx4 v[72:73], off
	s_waitcnt vmcnt(8)
	s_waitcnt lgkmcnt(0)
	s_barrier
	s_waitcnt lgkmcnt(0)
	v_mfma_f32_16x16x32_bf16 v[72:75], v[48:51], v[136:139], v[80:83]
	v_mfma_f32_16x16x32_bf16 v[80:83], v[52:55], v[144:147], v[72:75]
	v_mfma_f32_16x16x32_bf16 v[72:75], v[64:67], v[136:139], v[76:79]
	v_mfma_f32_16x16x32_bf16 v[60:63], v[48:51], v[172:175], v[60:63]
	v_mfma_f32_16x16x32_bf16 v[56:59], v[64:67], v[172:175], v[56:59]
	v_mfma_f32_16x16x32_bf16 v[28:31], v[48:51], v[196:199], v[28:31]
	v_mfma_f32_16x16x32_bf16 v[24:27], v[64:67], v[196:199], v[24:27]
	v_mfma_f32_16x16x32_bf16 v[12:15], v[48:51], v[204:207], v[12:15]
	v_mfma_f32_16x16x32_bf16 v[8:11], v[64:67], v[204:207], v[8:11]
	v_mfma_f32_16x16x32_bf16 v[76:79], v[68:71], v[144:147], v[72:75]
	v_mfma_f32_16x16x32_bf16 v[60:63], v[52:55], v[190:193], v[60:63]
	v_mfma_f32_16x16x32_bf16 v[56:59], v[68:71], v[190:193], v[56:59]
	v_mfma_f32_16x16x32_bf16 v[28:31], v[52:55], v[200:203], v[28:31]
	v_mfma_f32_16x16x32_bf16 v[24:27], v[68:71], v[200:203], v[24:27]
	v_mfma_f32_16x16x32_bf16 v[12:15], v[52:55], v[208:211], v[12:15]
	v_mfma_f32_16x16x32_bf16 v[8:11], v[68:71], v[208:211], v[8:11]
	v_mfma_f32_16x16x32_bf16 v[40:43], v[100:103], v[136:139], v[40:43]
	v_mfma_f32_16x16x32_bf16 v[72:75], v[120:123], v[144:147], v[40:43]
	v_mfma_f32_16x16x32_bf16 v[40:43], v[124:127], v[136:139], v[44:47]
	v_mfma_f32_16x16x32_bf16 v[36:39], v[100:103], v[172:175], v[36:39]
	v_mfma_f32_16x16x32_bf16 v[32:35], v[124:127], v[172:175], v[32:35]
	v_mfma_f32_16x16x32_bf16 v[20:23], v[100:103], v[196:199], v[20:23]
	v_mfma_f32_16x16x32_bf16 v[16:19], v[124:127], v[196:199], v[16:19]
	v_mfma_f32_16x16x32_bf16 v[4:7], v[100:103], v[204:207], v[4:7]
	v_mfma_f32_16x16x32_bf16 v[0:3], v[124:127], v[204:207], v[0:3]
	v_mfma_f32_16x16x32_bf16 v[68:71], v[140:143], v[144:147], v[40:43]
	v_mfma_f32_16x16x32_bf16 v[36:39], v[120:123], v[190:193], v[36:39]
	v_mfma_f32_16x16x32_bf16 v[32:35], v[140:143], v[190:193], v[32:35]
	v_mfma_f32_16x16x32_bf16 v[20:23], v[120:123], v[200:203], v[20:23]
	v_mfma_f32_16x16x32_bf16 v[16:19], v[140:143], v[200:203], v[16:19]
	v_mfma_f32_16x16x32_bf16 v[4:7], v[120:123], v[208:211], v[4:7]
	v_mfma_f32_16x16x32_bf16 v[0:3], v[140:143], v[208:211], v[0:3]
	s_barrier
	s_add_i32 s85, s85, 2
	s_add_u32 s10, s10, 0x100
	s_addc_u32 s11, s11, 0
	s_add_u32 s54, s54, 0x100
	s_addc_u32 s55, s55, 0
.LBB0_639:
	s_add_u32 s67, s10, 0xfff80080
	s_addc_u32 s87, s11, -1
	s_add_i32 s96, 0, 0x10000
	s_cmp_eq_u32 s85, 28
	s_cselect_b32 s95, s7, s87
	s_cselect_b32 s94, s9, s67
	s_cselect_b32 s93, s40, s55
	s_cselect_b32 s92, s41, s54
	s_add_i32 s67, 0, 0x14000
	v_add_u32_e32 v52, s96, v194
	v_add_u32_e32 v124, s67, v194
	ds_read_b128 v[40:43], v52
	ds_read_b128 v[44:47], v52 offset:1024
	ds_read_b128 v[48:51], v52 offset:2048
	ds_read_b128 v[52:55], v52 offset:3072
	ds_read_b128 v[64:67], v124
	ds_read_b128 v[100:103], v124 offset:1024
	ds_read_b128 v[120:123], v124 offset:2048
	ds_read_b128 v[124:127], v124 offset:3072
	v_lshl_add_u64 v[208:209], s[10:11], 0, v[186:187]
	s_add_i32 m0, s57, 0xc000
	ds_read_b128 v[136:139], v195
	ds_read_b128 v[140:143], v195 offset:1024
	ds_read_b128 v[144:147], v195 offset:2048
	ds_read_b128 v[172:175], v195 offset:3072
	ds_read_b128 v[190:193], v195 offset:4096
	ds_read_b128 v[196:199], v195 offset:5120
	ds_read_b128 v[200:203], v195 offset:6144
	ds_read_b128 v[204:207], v195 offset:7168
	global_load_lds_dwordx4 v[208:209], off
	v_lshl_add_u64 v[208:209], s[10:11], 0, v[188:189]
	s_add_i32 m0, s57, 0xe000
	s_nop 0
	global_load_lds_dwordx4 v[208:209], off
	s_waitcnt vmcnt(8)
	s_waitcnt lgkmcnt(0)
	s_barrier
	s_waitcnt lgkmcnt(0)
	v_mfma_f32_16x16x32_bf16 v[168:171], v[40:43], v[136:139], v[168:171]
	v_mfma_f32_16x16x32_bf16 v[164:167], v[48:51], v[136:139], v[164:167]
	v_mfma_f32_16x16x32_bf16 v[152:155], v[40:43], v[144:147], v[152:155]
	v_mfma_f32_16x16x32_bf16 v[148:151], v[48:51], v[144:147], v[148:151]
	v_mfma_f32_16x16x32_bf16 v[116:119], v[40:43], v[190:193], v[116:119]
	v_mfma_f32_16x16x32_bf16 v[112:115], v[48:51], v[190:193], v[112:115]
	v_mfma_f32_16x16x32_bf16 v[96:99], v[40:43], v[200:203], v[96:99]
	v_mfma_f32_16x16x32_bf16 v[92:95], v[48:51], v[200:203], v[92:95]
	v_mfma_f32_16x16x32_bf16 v[168:171], v[44:47], v[140:143], v[168:171]
	v_mfma_f32_16x16x32_bf16 v[164:167], v[52:55], v[140:143], v[164:167]
	v_mfma_f32_16x16x32_bf16 v[152:155], v[44:47], v[172:175], v[152:155]
	v_mfma_f32_16x16x32_bf16 v[148:151], v[52:55], v[172:175], v[148:151]
	v_mfma_f32_16x16x32_bf16 v[116:119], v[44:47], v[196:199], v[116:119]
	v_mfma_f32_16x16x32_bf16 v[112:115], v[52:55], v[196:199], v[112:115]
	v_mfma_f32_16x16x32_bf16 v[96:99], v[44:47], v[204:207], v[96:99]
	v_mfma_f32_16x16x32_bf16 v[92:95], v[52:55], v[204:207], v[92:95]
	v_mfma_f32_16x16x32_bf16 v[160:163], v[64:67], v[136:139], v[160:163]
	v_mfma_f32_16x16x32_bf16 v[132:135], v[64:67], v[144:147], v[132:135]
	v_mfma_f32_16x16x32_bf16 v[128:131], v[120:123], v[144:147], v[128:131]
	v_mfma_f32_16x16x32_bf16 v[108:111], v[64:67], v[190:193], v[108:111]
	v_mfma_f32_16x16x32_bf16 v[104:107], v[120:123], v[190:193], v[104:107]
	v_mfma_f32_16x16x32_bf16 v[88:91], v[64:67], v[200:203], v[88:91]
	v_mfma_f32_16x16x32_bf16 v[84:87], v[120:123], v[200:203], v[84:87]
	v_mfma_f32_16x16x32_bf16 v[160:163], v[100:103], v[140:143], v[160:163]
	v_mfma_f32_16x16x32_bf16 v[136:139], v[120:123], v[136:139], v[156:159]
	v_mfma_f32_16x16x32_bf16 v[132:135], v[100:103], v[172:175], v[132:135]
	v_mfma_f32_16x16x32_bf16 v[128:131], v[124:127], v[172:175], v[128:131]
	v_mfma_f32_16x16x32_bf16 v[108:111], v[100:103], v[196:199], v[108:111]
	v_mfma_f32_16x16x32_bf16 v[104:107], v[124:127], v[196:199], v[104:107]
	v_mfma_f32_16x16x32_bf16 v[88:91], v[100:103], v[204:207], v[88:91]
	v_mfma_f32_16x16x32_bf16 v[84:87], v[124:127], v[204:207], v[84:87]
	v_mfma_f32_16x16x32_bf16 v[136:139], v[124:127], v[140:143], v[136:139]
	s_barrier
	s_add_i32 s87, s96, s56
	v_lshl_add_u64 v[212:213], s[92:93], 0, v[178:179]
	s_mov_b32 m0, s87
	ds_read_b128 v[140:143], v195 offset:16384
	ds_read_b128 v[144:147], v195 offset:17408
	ds_read_b128 v[156:159], v195 offset:18432
	ds_read_b128 v[172:175], v195 offset:19456
	ds_read_b128 v[190:193], v195 offset:20480
	ds_read_b128 v[196:199], v195 offset:21504
	ds_read_b128 v[200:203], v195 offset:22528
	ds_read_b128 v[204:207], v195 offset:23552
	global_load_lds_dwordx4 v[212:213], off
	s_add_i32 m0, s87, 0x2000
	s_add_u32 vcc_lo, s92, 0x80000
	v_lshl_add_u64 v[214:215], s[92:93], 0, v[182:183]
	s_addc_u32 vcc_hi, s93, 0
	s_add_i32 s67, s67, s56
	global_load_lds_dwordx4 v[214:215], off
	v_lshl_add_u64 v[208:209], vcc, 0, v[178:179]
	s_mov_b32 m0, s67
	v_lshl_add_u64 v[224:225], s[94:95], 0, v[176:177]
	global_load_lds_dwordx4 v[208:209], off
	v_lshl_add_u64 v[208:209], vcc, 0, v[182:183]
	s_add_i32 m0, s67, 0x2000
	v_lshl_add_u64 v[226:227], s[94:95], 0, v[180:181]
	global_load_lds_dwordx4 v[208:209], off
	s_mov_b32 m0, s57
	s_nop 0
	global_load_lds_dwordx4 v[224:225], off
	s_mov_b32 m0, s61
	s_nop 0
	global_load_lds_dwordx4 v[226:227], off
	s_waitcnt vmcnt(8)
	s_waitcnt lgkmcnt(0)
	s_barrier
	s_waitcnt lgkmcnt(0)
	v_mfma_f32_16x16x32_bf16 v[80:83], v[40:43], v[140:143], v[80:83]
	v_mfma_f32_16x16x32_bf16 v[76:79], v[48:51], v[140:143], v[76:79]
	v_mfma_f32_16x16x32_bf16 v[60:63], v[40:43], v[156:159], v[60:63]
	v_mfma_f32_16x16x32_bf16 v[56:59], v[48:51], v[156:159], v[56:59]
	v_mfma_f32_16x16x32_bf16 v[28:31], v[40:43], v[190:193], v[28:31]
	v_mfma_f32_16x16x32_bf16 v[24:27], v[48:51], v[190:193], v[24:27]
	v_mfma_f32_16x16x32_bf16 v[12:15], v[40:43], v[200:203], v[12:15]
	v_mfma_f32_16x16x32_bf16 v[8:11], v[48:51], v[200:203], v[8:11]
	v_mfma_f32_16x16x32_bf16 v[80:83], v[44:47], v[144:147], v[80:83]
	v_mfma_f32_16x16x32_bf16 v[76:79], v[52:55], v[144:147], v[76:79]
	v_mfma_f32_16x16x32_bf16 v[60:63], v[44:47], v[172:175], v[60:63]
	v_mfma_f32_16x16x32_bf16 v[56:59], v[52:55], v[172:175], v[56:59]
	v_mfma_f32_16x16x32_bf16 v[28:31], v[44:47], v[196:199], v[28:31]
	v_mfma_f32_16x16x32_bf16 v[24:27], v[52:55], v[196:199], v[24:27]
	v_mfma_f32_16x16x32_bf16 v[12:15], v[44:47], v[204:207], v[12:15]
	v_mfma_f32_16x16x32_bf16 v[8:11], v[52:55], v[204:207], v[8:11]
	v_mfma_f32_16x16x32_bf16 v[36:39], v[64:67], v[156:159], v[36:39]
	v_mfma_f32_16x16x32_bf16 v[32:35], v[120:123], v[156:159], v[32:35]
	v_mfma_f32_16x16x32_bf16 v[20:23], v[64:67], v[190:193], v[20:23]
	v_mfma_f32_16x16x32_bf16 v[16:19], v[120:123], v[190:193], v[16:19]
	v_mfma_f32_16x16x32_bf16 v[4:7], v[64:67], v[200:203], v[4:7]
	v_mfma_f32_16x16x32_bf16 v[0:3], v[120:123], v[200:203], v[0:3]
	v_mfma_f32_16x16x32_bf16 v[40:43], v[64:67], v[140:143], v[72:75]
	v_mfma_f32_16x16x32_bf16 v[44:47], v[120:123], v[140:143], v[68:71]
	v_mfma_f32_16x16x32_bf16 v[36:39], v[100:103], v[172:175], v[36:39]
	v_mfma_f32_16x16x32_bf16 v[32:35], v[124:127], v[172:175], v[32:35]
	v_mfma_f32_16x16x32_bf16 v[20:23], v[100:103], v[196:199], v[20:23]
	v_mfma_f32_16x16x32_bf16 v[16:19], v[124:127], v[196:199], v[16:19]
	v_mfma_f32_16x16x32_bf16 v[4:7], v[100:103], v[204:207], v[4:7]
	v_mfma_f32_16x16x32_bf16 v[0:3], v[124:127], v[204:207], v[0:3]
	v_mfma_f32_16x16x32_bf16 v[40:43], v[100:103], v[144:147], v[40:43]
	v_mfma_f32_16x16x32_bf16 v[44:47], v[124:127], v[144:147], v[44:47]
	s_barrier
	s_add_i32 s67, 0, 0x18000
	s_add_i32 s87, 0, 0x1c000
	v_add_u32_e32 v68, s67, v194
	v_add_u32_e32 v72, s87, v194
	ds_read_b128 v[48:51], v68
	ds_read_b128 v[52:55], v68 offset:1024
	ds_read_b128 v[64:67], v68 offset:2048
	ds_read_b128 v[68:71], v68 offset:3072
	ds_read_b128 v[100:103], v72
	ds_read_b128 v[120:123], v72 offset:1024
	ds_read_b128 v[124:127], v72 offset:2048
	ds_read_b128 v[140:143], v72 offset:3072
	s_add_u32 s94, s94, 0x80000
	s_addc_u32 s95, s95, 0
	s_mov_b32 m0, s68
	v_lshl_add_u64 v[156:157], s[94:95], 0, v[176:177]
	ds_read_b128 v[72:75], v195 offset:32768
	ds_read_b128 v[144:147], v195 offset:33792
	ds_read_b128 v[172:175], v195 offset:34816
	ds_read_b128 v[190:193], v195 offset:35840
	ds_read_b128 v[196:199], v195 offset:36864
	ds_read_b128 v[200:203], v195 offset:37888
	ds_read_b128 v[204:207], v195 offset:38912
	ds_read_b128 v[208:211], v195 offset:39936
	global_load_lds_dwordx4 v[156:157], off
	v_lshl_add_u64 v[156:157], s[94:95], 0, v[180:181]
	s_mov_b32 m0, s69
	s_nop 0
	global_load_lds_dwordx4 v[156:157], off
	s_waitcnt vmcnt(8)
	s_waitcnt lgkmcnt(0)
	s_barrier
	s_waitcnt lgkmcnt(0)
	v_mfma_f32_16x16x32_bf16 v[156:159], v[48:51], v[72:75], v[168:171]
	v_mfma_f32_16x16x32_bf16 v[168:171], v[52:55], v[144:147], v[156:159]
	v_mfma_f32_16x16x32_bf16 v[156:159], v[64:67], v[72:75], v[164:167]
	v_mfma_f32_16x16x32_bf16 v[152:155], v[48:51], v[172:175], v[152:155]
	v_mfma_f32_16x16x32_bf16 v[148:151], v[64:67], v[172:175], v[148:151]
	v_mfma_f32_16x16x32_bf16 v[116:119], v[48:51], v[196:199], v[116:119]
	v_mfma_f32_16x16x32_bf16 v[112:115], v[64:67], v[196:199], v[112:115]
	v_mfma_f32_16x16x32_bf16 v[96:99], v[48:51], v[204:207], v[96:99]
	v_mfma_f32_16x16x32_bf16 v[92:95], v[64:67], v[204:207], v[92:95]
	v_mfma_f32_16x16x32_bf16 v[164:167], v[68:71], v[144:147], v[156:159]
	v_mfma_f32_16x16x32_bf16 v[152:155], v[52:55], v[190:193], v[152:155]
	v_mfma_f32_16x16x32_bf16 v[148:151], v[68:71], v[190:193], v[148:151]
	v_mfma_f32_16x16x32_bf16 v[116:119], v[52:55], v[200:203], v[116:119]
	v_mfma_f32_16x16x32_bf16 v[112:115], v[68:71], v[200:203], v[112:115]
	v_mfma_f32_16x16x32_bf16 v[96:99], v[52:55], v[208:211], v[96:99]
	v_mfma_f32_16x16x32_bf16 v[92:95], v[68:71], v[208:211], v[92:95]
	v_mfma_f32_16x16x32_bf16 v[156:159], v[100:103], v[72:75], v[160:163]
	v_mfma_f32_16x16x32_bf16 v[72:75], v[124:127], v[72:75], v[136:139]
	v_mfma_f32_16x16x32_bf16 v[160:163], v[120:123], v[144:147], v[156:159]
	v_mfma_f32_16x16x32_bf16 v[156:159], v[140:143], v[144:147], v[72:75]
	v_mfma_f32_16x16x32_bf16 v[72:75], v[100:103], v[172:175], v[132:135]
	v_mfma_f32_16x16x32_bf16 v[132:135], v[120:123], v[190:193], v[72:75]
	v_mfma_f32_16x16x32_bf16 v[72:75], v[124:127], v[172:175], v[128:131]
	v_mfma_f32_16x16x32_bf16 v[128:131], v[140:143], v[190:193], v[72:75]
	v_mfma_f32_16x16x32_bf16 v[72:75], v[100:103], v[196:199], v[108:111]
	v_mfma_f32_16x16x32_bf16 v[108:111], v[120:123], v[200:203], v[72:75]
	v_mfma_f32_16x16x32_bf16 v[72:75], v[124:127], v[196:199], v[104:107]
	v_mfma_f32_16x16x32_bf16 v[104:107], v[140:143], v[200:203], v[72:75]
	v_mfma_f32_16x16x32_bf16 v[72:75], v[100:103], v[204:207], v[88:91]
	v_mfma_f32_16x16x32_bf16 v[88:91], v[120:123], v[208:211], v[72:75]
	v_mfma_f32_16x16x32_bf16 v[72:75], v[124:127], v[204:207], v[84:87]
	v_mfma_f32_16x16x32_bf16 v[84:87], v[140:143], v[208:211], v[72:75]
	s_barrier
	s_add_i32 s67, s67, s56
	s_nop 3
	v_lshl_add_u64 v[72:73], v[212:213], 0, s[30:31]
	s_mov_b32 m0, s67
	ds_read_b128 v[136:139], v195 offset:49152
	ds_read_b128 v[144:147], v195 offset:50176
	ds_read_b128 v[172:175], v195 offset:51200
	ds_read_b128 v[190:193], v195 offset:52224
	ds_read_b128 v[196:199], v195 offset:53248
	ds_read_b128 v[200:203], v195 offset:54272
	ds_read_b128 v[204:207], v195 offset:55296
	ds_read_b128 v[208:211], v195 offset:56320
	global_load_lds_dwordx4 v[72:73], off
	s_add_i32 m0, s67, 0x2000
	s_add_u32 s92, s92, 0x80080
	v_lshl_add_u64 v[72:73], v[214:215], 0, s[30:31]
	s_addc_u32 s93, s93, 0
	s_add_i32 s67, s87, s56
	global_load_lds_dwordx4 v[72:73], off
	v_lshl_add_u64 v[72:73], s[92:93], 0, v[178:179]
	s_mov_b32 m0, s67
	s_nop 0
	global_load_lds_dwordx4 v[72:73], off
	v_lshl_add_u64 v[72:73], s[92:93], 0, v[182:183]
	s_add_i32 m0, s67, 0x2000
	s_nop 0
	global_load_lds_dwordx4 v[72:73], off
	v_lshl_add_u64 v[72:73], v[224:225], 0, s[30:31]
	s_mov_b32 m0, s2
	s_nop 0
	global_load_lds_dwordx4 v[72:73], off
	v_lshl_add_u64 v[72:73], v[226:227], 0, s[30:31]
	s_mov_b32 m0, s28
	s_nop 0
	global_load_lds_dwordx4 v[72:73], off
	s_waitcnt vmcnt(8)
	s_waitcnt lgkmcnt(0)
	s_barrier
	s_waitcnt lgkmcnt(0)
	v_mfma_f32_16x16x32_bf16 v[72:75], v[48:51], v[136:139], v[80:83]
	v_mfma_f32_16x16x32_bf16 v[80:83], v[52:55], v[144:147], v[72:75]
	v_mfma_f32_16x16x32_bf16 v[72:75], v[64:67], v[136:139], v[76:79]
	v_mfma_f32_16x16x32_bf16 v[60:63], v[48:51], v[172:175], v[60:63]
	v_mfma_f32_16x16x32_bf16 v[56:59], v[64:67], v[172:175], v[56:59]
	v_mfma_f32_16x16x32_bf16 v[28:31], v[48:51], v[196:199], v[28:31]
	v_mfma_f32_16x16x32_bf16 v[24:27], v[64:67], v[196:199], v[24:27]
	v_mfma_f32_16x16x32_bf16 v[12:15], v[48:51], v[204:207], v[12:15]
	v_mfma_f32_16x16x32_bf16 v[8:11], v[64:67], v[204:207], v[8:11]
	v_mfma_f32_16x16x32_bf16 v[76:79], v[68:71], v[144:147], v[72:75]
	v_mfma_f32_16x16x32_bf16 v[60:63], v[52:55], v[190:193], v[60:63]
	v_mfma_f32_16x16x32_bf16 v[56:59], v[68:71], v[190:193], v[56:59]
	v_mfma_f32_16x16x32_bf16 v[28:31], v[52:55], v[200:203], v[28:31]
	v_mfma_f32_16x16x32_bf16 v[24:27], v[68:71], v[200:203], v[24:27]
	v_mfma_f32_16x16x32_bf16 v[12:15], v[52:55], v[208:211], v[12:15]
	v_mfma_f32_16x16x32_bf16 v[8:11], v[68:71], v[208:211], v[8:11]
	v_mfma_f32_16x16x32_bf16 v[40:43], v[100:103], v[136:139], v[40:43]
	v_mfma_f32_16x16x32_bf16 v[72:75], v[120:123], v[144:147], v[40:43]
	v_mfma_f32_16x16x32_bf16 v[40:43], v[124:127], v[136:139], v[44:47]
	v_mfma_f32_16x16x32_bf16 v[36:39], v[100:103], v[172:175], v[36:39]
	v_mfma_f32_16x16x32_bf16 v[32:35], v[124:127], v[172:175], v[32:35]
	v_mfma_f32_16x16x32_bf16 v[20:23], v[100:103], v[196:199], v[20:23]
	v_mfma_f32_16x16x32_bf16 v[16:19], v[124:127], v[196:199], v[16:19]
	v_mfma_f32_16x16x32_bf16 v[4:7], v[100:103], v[204:207], v[4:7]
	v_mfma_f32_16x16x32_bf16 v[0:3], v[124:127], v[204:207], v[0:3]
	v_mfma_f32_16x16x32_bf16 v[68:71], v[140:143], v[144:147], v[40:43]
	v_mfma_f32_16x16x32_bf16 v[36:39], v[120:123], v[190:193], v[36:39]
	v_mfma_f32_16x16x32_bf16 v[32:35], v[140:143], v[190:193], v[32:35]
	v_mfma_f32_16x16x32_bf16 v[20:23], v[120:123], v[200:203], v[20:23]
	v_mfma_f32_16x16x32_bf16 v[16:19], v[140:143], v[200:203], v[16:19]
	v_mfma_f32_16x16x32_bf16 v[4:7], v[120:123], v[208:211], v[4:7]
	v_mfma_f32_16x16x32_bf16 v[0:3], v[140:143], v[208:211], v[0:3]
	s_barrier
	s_add_i32 s85, s85, 2
	s_add_u32 s10, s10, 0x100
	s_addc_u32 s11, s11, 0
	s_add_u32 s54, s54, 0x100
	s_addc_u32 s55, s55, 0
	s_cmp_gt_u32 s85, 29
	s_cbranch_scc0 .LBB0_639
	s_and_b64 vcc, exec, s[80:81]
	s_cbranch_vccz .LBB0_642
	s_barrier

.LBB0_964:
	s_ashr_i32 s79, s78, 31
	s_lshl_b64 s[82:83], s[78:79], 20
	s_add_u32 s82, s14, s82
	s_addc_u32 s83, s15, s83
	s_and_b64 s[84:85], s[80:81], exec
	s_cselect_b32 s79, s83, s93
	s_cselect_b32 s96, s82, s92
	s_ashr_i32 s77, s76, 31
	s_lshl_b64 s[84:85], s[76:77], 20
	s_add_u32 s84, s24, s84
	s_addc_u32 s85, s26, s85
	s_and_b64 vcc, s[80:81], exec
	s_cselect_b32 s77, s85, s91
	s_cselect_b32 vcc_lo, s84, s90
	s_lshl_b32 s86, s86, 8
	s_ashr_i32 s87, s86, 31
	s_lshl_b64 s[74:75], s[86:87], 2
	s_add_u32 s74, s88, s74
	s_addc_u32 s75, s89, s75
	s_add_i32 m0, s71, s40
	s_add_u32 s88, s92, 0x80080
	global_load_lds_dwordx4 v239, s[74:75]
	s_addc_u32 s89, s93, 0
	s_add_u32 s87, s90, 0x100
	s_addc_u32 vcc_hi, s91, 0
	s_mov_b32 s71, -2
	s_waitcnt vmcnt(0)
	s_add_u32 s67, s88, 0xfff80080
	s_addc_u32 s74, s89, -1
	s_add_i32 s75, 0, 0x10000
	s_cmp_eq_u32 s71, 28
	s_cselect_b32 s93, s79, s74
	s_cselect_b32 s92, s96, s67
	s_cselect_b32 s91, s77, vcc_hi
	s_cselect_b32 s90, vcc_lo, s87
	s_add_i32 s67, 0, 0x14000
	v_add_u32_e32 v96, s75, v238
	v_add_u32_e32 v140, s67, v238
	ds_read_b128 v[64:67], v96
	ds_read_b128 v[72:75], v96 offset:1024
	ds_read_b128 v[88:91], v96 offset:2048
	ds_read_b128 v[96:99], v96 offset:3072
	ds_read_b128 v[108:111], v140
	ds_read_b128 v[116:119], v140 offset:1024
	ds_read_b128 v[128:131], v140 offset:2048
	ds_read_b128 v[140:143], v140 offset:3072
	v_lshl_add_u64 v[192:193], s[88:89], 0, v[230:231]
	s_add_i32 m0, s28, 0xc000
	ds_read_b128 v[152:155], v240
	ds_read_b128 v[156:159], v240 offset:1024
	ds_read_b128 v[160:163], v240 offset:2048
	ds_read_b128 v[164:167], v240 offset:3072
	ds_read_b128 v[168:171], v240 offset:4096
	ds_read_b128 v[180:183], v240 offset:5120
	ds_read_b128 v[184:187], v240 offset:6144
	ds_read_b128 v[188:191], v240 offset:7168
	global_load_lds_dwordx4 v[192:193], off
	v_lshl_add_u64 v[192:193], s[88:89], 0, v[232:233]
	s_add_i32 m0, s28, 0xe000
	s_nop 0
	global_load_lds_dwordx4 v[192:193], off
	s_waitcnt vmcnt(8)
	s_waitcnt lgkmcnt(0)
	s_barrier
	s_waitcnt lgkmcnt(0)
	v_mfma_f32_16x16x32_bf16 v[176:179], v[64:67], v[152:155], 0
	v_mfma_f32_16x16x32_bf16 v[172:175], v[88:91], v[152:155], 0
	v_mfma_f32_16x16x32_bf16 v[136:139], v[64:67], v[160:163], 0
	v_mfma_f32_16x16x32_bf16 v[132:135], v[88:91], v[160:163], 0
	v_mfma_f32_16x16x32_bf16 v[112:115], v[64:67], v[168:171], 0
	v_mfma_f32_16x16x32_bf16 v[104:107], v[88:91], v[168:171], 0
	v_mfma_f32_16x16x32_bf16 v[84:87], v[64:67], v[184:187], 0
	v_mfma_f32_16x16x32_bf16 v[80:83], v[88:91], v[184:187], 0
	v_mfma_f32_16x16x32_bf16 v[176:179], v[72:75], v[156:159], v[176:179]
	v_mfma_f32_16x16x32_bf16 v[172:175], v[96:99], v[156:159], v[172:175]
	v_mfma_f32_16x16x32_bf16 v[136:139], v[72:75], v[164:167], v[136:139]
	v_mfma_f32_16x16x32_bf16 v[132:135], v[96:99], v[164:167], v[132:135]
	v_mfma_f32_16x16x32_bf16 v[112:115], v[72:75], v[180:183], v[112:115]
	v_mfma_f32_16x16x32_bf16 v[104:107], v[96:99], v[180:183], v[104:107]
	v_mfma_f32_16x16x32_bf16 v[84:87], v[72:75], v[188:191], v[84:87]
	v_mfma_f32_16x16x32_bf16 v[80:83], v[96:99], v[188:191], v[80:83]
	v_mfma_f32_16x16x32_bf16 v[148:151], v[108:111], v[152:155], 0
	v_mfma_f32_16x16x32_bf16 v[144:147], v[128:131], v[152:155], 0
	v_mfma_f32_16x16x32_bf16 v[124:127], v[108:111], v[160:163], 0
	v_mfma_f32_16x16x32_bf16 v[120:123], v[128:131], v[160:163], 0
	v_mfma_f32_16x16x32_bf16 v[100:103], v[108:111], v[168:171], 0
	v_mfma_f32_16x16x32_bf16 v[92:95], v[128:131], v[168:171], 0
	v_mfma_f32_16x16x32_bf16 v[76:79], v[108:111], v[184:187], 0
	v_mfma_f32_16x16x32_bf16 v[68:71], v[128:131], v[184:187], 0
	v_mfma_f32_16x16x32_bf16 v[148:151], v[116:119], v[156:159], v[148:151]
	v_mfma_f32_16x16x32_bf16 v[144:147], v[140:143], v[156:159], v[144:147]
	v_mfma_f32_16x16x32_bf16 v[124:127], v[116:119], v[164:167], v[124:127]
	v_mfma_f32_16x16x32_bf16 v[120:123], v[140:143], v[164:167], v[120:123]
	v_mfma_f32_16x16x32_bf16 v[100:103], v[116:119], v[180:183], v[100:103]
	v_mfma_f32_16x16x32_bf16 v[92:95], v[140:143], v[180:183], v[92:95]
	v_mfma_f32_16x16x32_bf16 v[76:79], v[116:119], v[188:191], v[76:79]
	v_mfma_f32_16x16x32_bf16 v[68:71], v[140:143], v[188:191], v[68:71]
	s_barrier
	s_add_i32 s74, s75, s2
	v_lshl_add_u64 v[192:193], s[90:91], 0, v[216:217]
	s_mov_b32 m0, s74
	ds_read_b128 v[152:155], v240 offset:16384
	ds_read_b128 v[156:159], v240 offset:17408
	ds_read_b128 v[160:163], v240 offset:18432
	ds_read_b128 v[164:167], v240 offset:19456
	ds_read_b128 v[168:171], v240 offset:20480
	ds_read_b128 v[180:183], v240 offset:21504
	ds_read_b128 v[184:187], v240 offset:22528
	ds_read_b128 v[188:191], v240 offset:23552
	global_load_lds_dwordx4 v[192:193], off
	s_add_i32 m0, s74, 0x2000
	s_add_u32 s74, s90, 0x80000
	v_lshl_add_u64 v[194:195], s[90:91], 0, v[228:229]
	s_addc_u32 s75, s91, 0
	s_add_i32 s67, s67, s2
	global_load_lds_dwordx4 v[194:195], off
	v_lshl_add_u64 v[196:197], s[74:75], 0, v[216:217]
	s_mov_b32 m0, s67
	v_lshl_add_u64 v[198:199], s[92:93], 0, v[226:227]
	global_load_lds_dwordx4 v[196:197], off
	v_lshl_add_u64 v[196:197], s[74:75], 0, v[228:229]
	s_add_i32 m0, s67, 0x2000
	s_nop 0
	global_load_lds_dwordx4 v[196:197], off
	v_lshl_add_u64 v[196:197], s[92:93], 0, v[224:225]
	s_mov_b32 m0, s28
	s_nop 0
	global_load_lds_dwordx4 v[196:197], off
	s_mov_b32 m0, s29
	s_nop 0
	global_load_lds_dwordx4 v[198:199], off
	s_waitcnt vmcnt(8)
	s_waitcnt lgkmcnt(0)
	s_barrier
	s_waitcnt lgkmcnt(0)
	v_mfma_f32_16x16x32_bf16 v[60:63], v[64:67], v[152:155], 0
	v_mfma_f32_16x16x32_bf16 v[56:59], v[88:91], v[152:155], 0
	v_mfma_f32_16x16x32_bf16 v[44:47], v[64:67], v[160:163], 0
	v_mfma_f32_16x16x32_bf16 v[40:43], v[88:91], v[160:163], 0
	v_mfma_f32_16x16x32_bf16 v[28:31], v[64:67], v[168:171], 0
	v_mfma_f32_16x16x32_bf16 v[24:27], v[88:91], v[168:171], 0
	v_mfma_f32_16x16x32_bf16 v[12:15], v[64:67], v[184:187], 0
	v_mfma_f32_16x16x32_bf16 v[8:11], v[88:91], v[184:187], 0
	v_mfma_f32_16x16x32_bf16 v[60:63], v[72:75], v[156:159], v[60:63]
	v_mfma_f32_16x16x32_bf16 v[56:59], v[96:99], v[156:159], v[56:59]
	v_mfma_f32_16x16x32_bf16 v[44:47], v[72:75], v[164:167], v[44:47]
	v_mfma_f32_16x16x32_bf16 v[40:43], v[96:99], v[164:167], v[40:43]
	v_mfma_f32_16x16x32_bf16 v[28:31], v[72:75], v[180:183], v[28:31]
	v_mfma_f32_16x16x32_bf16 v[24:27], v[96:99], v[180:183], v[24:27]
	v_mfma_f32_16x16x32_bf16 v[12:15], v[72:75], v[188:191], v[12:15]
	v_mfma_f32_16x16x32_bf16 v[8:11], v[96:99], v[188:191], v[8:11]
	v_mfma_f32_16x16x32_bf16 v[52:55], v[108:111], v[152:155], 0
	v_mfma_f32_16x16x32_bf16 v[48:51], v[128:131], v[152:155], 0
	v_mfma_f32_16x16x32_bf16 v[36:39], v[108:111], v[160:163], 0
	v_mfma_f32_16x16x32_bf16 v[32:35], v[128:131], v[160:163], 0
	v_mfma_f32_16x16x32_bf16 v[20:23], v[108:111], v[168:171], 0
	v_mfma_f32_16x16x32_bf16 v[16:19], v[128:131], v[168:171], 0
	v_mfma_f32_16x16x32_bf16 v[4:7], v[108:111], v[184:187], 0
	v_mfma_f32_16x16x32_bf16 v[0:3], v[128:131], v[184:187], 0
	v_mfma_f32_16x16x32_bf16 v[52:55], v[116:119], v[156:159], v[52:55]
	v_mfma_f32_16x16x32_bf16 v[48:51], v[140:143], v[156:159], v[48:51]
	v_mfma_f32_16x16x32_bf16 v[36:39], v[116:119], v[164:167], v[36:39]
	v_mfma_f32_16x16x32_bf16 v[32:35], v[140:143], v[164:167], v[32:35]
	v_mfma_f32_16x16x32_bf16 v[20:23], v[116:119], v[180:183], v[20:23]
	v_mfma_f32_16x16x32_bf16 v[16:19], v[140:143], v[180:183], v[16:19]
	v_mfma_f32_16x16x32_bf16 v[4:7], v[116:119], v[188:191], v[4:7]
	v_mfma_f32_16x16x32_bf16 v[0:3], v[140:143], v[188:191], v[0:3]
	s_barrier
	s_add_i32 s67, 0, 0x18000
	s_add_i32 s3, 0, 0x1c000
	v_add_u32_e32 v96, s67, v238
	v_add_u32_e32 v140, s3, v238
	ds_read_b128 v[64:67], v96
	ds_read_b128 v[72:75], v96 offset:1024
	ds_read_b128 v[88:91], v96 offset:2048
	ds_read_b128 v[96:99], v96 offset:3072
	ds_read_b128 v[108:111], v140
	ds_read_b128 v[116:119], v140 offset:1024
	ds_read_b128 v[128:131], v140 offset:2048
	ds_read_b128 v[140:143], v140 offset:3072
	s_add_u32 s74, s92, 0x80000
	s_addc_u32 s75, s93, 0
	s_mov_b32 m0, s34
	v_lshl_add_u64 v[200:201], s[74:75], 0, v[224:225]
	ds_read_b128 v[152:155], v240 offset:32768
	ds_read_b128 v[156:159], v240 offset:33792
	ds_read_b128 v[160:163], v240 offset:34816
	ds_read_b128 v[164:167], v240 offset:35840
	ds_read_b128 v[168:171], v240 offset:36864
	ds_read_b128 v[180:183], v240 offset:37888
	ds_read_b128 v[184:187], v240 offset:38912
	ds_read_b128 v[188:191], v240 offset:39936
	global_load_lds_dwordx4 v[200:201], off
	v_lshl_add_u64 v[200:201], s[74:75], 0, v[226:227]
	s_mov_b32 m0, s35
	s_nop 0
	global_load_lds_dwordx4 v[200:201], off
	s_waitcnt vmcnt(8)
	s_waitcnt lgkmcnt(0)
	s_barrier
	s_waitcnt lgkmcnt(0)
	v_mfma_f32_16x16x32_bf16 v[176:179], v[64:67], v[152:155], v[176:179]
	v_mfma_f32_16x16x32_bf16 v[172:175], v[88:91], v[152:155], v[172:175]
	v_mfma_f32_16x16x32_bf16 v[136:139], v[64:67], v[160:163], v[136:139]
	v_mfma_f32_16x16x32_bf16 v[132:135], v[88:91], v[160:163], v[132:135]
	v_mfma_f32_16x16x32_bf16 v[112:115], v[64:67], v[168:171], v[112:115]
	v_mfma_f32_16x16x32_bf16 v[104:107], v[88:91], v[168:171], v[104:107]
	v_mfma_f32_16x16x32_bf16 v[84:87], v[64:67], v[184:187], v[84:87]
	v_mfma_f32_16x16x32_bf16 v[80:83], v[88:91], v[184:187], v[80:83]
	v_mfma_f32_16x16x32_bf16 v[176:179], v[72:75], v[156:159], v[176:179]
	v_mfma_f32_16x16x32_bf16 v[172:175], v[96:99], v[156:159], v[172:175]
	v_mfma_f32_16x16x32_bf16 v[136:139], v[72:75], v[164:167], v[136:139]
	v_mfma_f32_16x16x32_bf16 v[132:135], v[96:99], v[164:167], v[132:135]
	v_mfma_f32_16x16x32_bf16 v[112:115], v[72:75], v[180:183], v[112:115]
	v_mfma_f32_16x16x32_bf16 v[104:107], v[96:99], v[180:183], v[104:107]
	v_mfma_f32_16x16x32_bf16 v[84:87], v[72:75], v[188:191], v[84:87]
	v_mfma_f32_16x16x32_bf16 v[80:83], v[96:99], v[188:191], v[80:83]
	v_mfma_f32_16x16x32_bf16 v[148:151], v[108:111], v[152:155], v[148:151]
	v_mfma_f32_16x16x32_bf16 v[144:147], v[128:131], v[152:155], v[144:147]
	v_mfma_f32_16x16x32_bf16 v[124:127], v[108:111], v[160:163], v[124:127]
	v_mfma_f32_16x16x32_bf16 v[120:123], v[128:131], v[160:163], v[120:123]
	v_mfma_f32_16x16x32_bf16 v[100:103], v[108:111], v[168:171], v[100:103]
	v_mfma_f32_16x16x32_bf16 v[92:95], v[128:131], v[168:171], v[92:95]
	v_mfma_f32_16x16x32_bf16 v[76:79], v[108:111], v[184:187], v[76:79]
	v_mfma_f32_16x16x32_bf16 v[68:71], v[128:131], v[184:187], v[68:71]
	v_mfma_f32_16x16x32_bf16 v[148:151], v[116:119], v[156:159], v[148:151]
	v_mfma_f32_16x16x32_bf16 v[144:147], v[140:143], v[156:159], v[144:147]
	v_mfma_f32_16x16x32_bf16 v[124:127], v[116:119], v[164:167], v[124:127]
	v_mfma_f32_16x16x32_bf16 v[120:123], v[140:143], v[164:167], v[120:123]
	v_mfma_f32_16x16x32_bf16 v[100:103], v[116:119], v[180:183], v[100:103]
	v_mfma_f32_16x16x32_bf16 v[92:95], v[140:143], v[180:183], v[92:95]
	v_mfma_f32_16x16x32_bf16 v[76:79], v[116:119], v[188:191], v[76:79]
	v_mfma_f32_16x16x32_bf16 v[68:71], v[140:143], v[188:191], v[68:71]
	s_barrier
	s_add_i32 s67, s67, s2
	v_lshl_add_u64 v[192:193], v[192:193], 0, s[30:31]
	s_mov_b32 m0, s67
	ds_read_b128 v[152:155], v240 offset:49152
	ds_read_b128 v[156:159], v240 offset:50176
	ds_read_b128 v[160:163], v240 offset:51200
	ds_read_b128 v[164:167], v240 offset:52224
	ds_read_b128 v[168:171], v240 offset:53248
	ds_read_b128 v[180:183], v240 offset:54272
	ds_read_b128 v[184:187], v240 offset:55296
	ds_read_b128 v[188:191], v240 offset:56320
	global_load_lds_dwordx4 v[192:193], off
	s_add_i32 m0, s67, 0x2000
	s_add_u32 s74, s90, 0x80080
	v_lshl_add_u64 v[192:193], v[194:195], 0, s[30:31]
	s_addc_u32 s75, s91, 0
	s_add_i32 s3, s3, s2
	global_load_lds_dwordx4 v[192:193], off
	v_lshl_add_u64 v[192:193], s[74:75], 0, v[216:217]
	s_mov_b32 m0, s3
	s_nop 0
	global_load_lds_dwordx4 v[192:193], off
	v_lshl_add_u64 v[192:193], s[74:75], 0, v[228:229]
	s_add_i32 m0, s3, 0x2000
	s_nop 0
	global_load_lds_dwordx4 v[192:193], off
	v_lshl_add_u64 v[192:193], v[196:197], 0, s[30:31]
	s_mov_b32 m0, s60
	s_nop 0
	global_load_lds_dwordx4 v[192:193], off
	v_lshl_add_u64 v[192:193], v[198:199], 0, s[30:31]
	s_mov_b32 m0, s61
	s_nop 0
	global_load_lds_dwordx4 v[192:193], off
	s_waitcnt vmcnt(8)
	s_waitcnt lgkmcnt(0)
	s_barrier
	s_waitcnt lgkmcnt(0)
	v_mfma_f32_16x16x32_bf16 v[60:63], v[64:67], v[152:155], v[60:63]
	v_mfma_f32_16x16x32_bf16 v[56:59], v[88:91], v[152:155], v[56:59]
	v_mfma_f32_16x16x32_bf16 v[44:47], v[64:67], v[160:163], v[44:47]
	v_mfma_f32_16x16x32_bf16 v[40:43], v[88:91], v[160:163], v[40:43]
	v_mfma_f32_16x16x32_bf16 v[28:31], v[64:67], v[168:171], v[28:31]
	v_mfma_f32_16x16x32_bf16 v[24:27], v[88:91], v[168:171], v[24:27]
	v_mfma_f32_16x16x32_bf16 v[12:15], v[64:67], v[184:187], v[12:15]
	v_mfma_f32_16x16x32_bf16 v[8:11], v[88:91], v[184:187], v[8:11]
	v_mfma_f32_16x16x32_bf16 v[60:63], v[72:75], v[156:159], v[60:63]
	v_mfma_f32_16x16x32_bf16 v[56:59], v[96:99], v[156:159], v[56:59]
	v_mfma_f32_16x16x32_bf16 v[44:47], v[72:75], v[164:167], v[44:47]
	v_mfma_f32_16x16x32_bf16 v[40:43], v[96:99], v[164:167], v[40:43]
	v_mfma_f32_16x16x32_bf16 v[28:31], v[72:75], v[180:183], v[28:31]
	v_mfma_f32_16x16x32_bf16 v[24:27], v[96:99], v[180:183], v[24:27]
	v_mfma_f32_16x16x32_bf16 v[12:15], v[72:75], v[188:191], v[12:15]
	v_mfma_f32_16x16x32_bf16 v[8:11], v[96:99], v[188:191], v[8:11]
	v_mfma_f32_16x16x32_bf16 v[52:55], v[108:111], v[152:155], v[52:55]
	v_mfma_f32_16x16x32_bf16 v[48:51], v[128:131], v[152:155], v[48:51]
	v_mfma_f32_16x16x32_bf16 v[36:39], v[108:111], v[160:163], v[36:39]
	v_mfma_f32_16x16x32_bf16 v[32:35], v[128:131], v[160:163], v[32:35]
	v_mfma_f32_16x16x32_bf16 v[20:23], v[108:111], v[168:171], v[20:23]
	v_mfma_f32_16x16x32_bf16 v[16:19], v[128:131], v[168:171], v[16:19]
	v_mfma_f32_16x16x32_bf16 v[4:7], v[108:111], v[184:187], v[4:7]
	v_mfma_f32_16x16x32_bf16 v[0:3], v[128:131], v[184:187], v[0:3]
	v_mfma_f32_16x16x32_bf16 v[52:55], v[116:119], v[156:159], v[52:55]
	v_mfma_f32_16x16x32_bf16 v[48:51], v[140:143], v[156:159], v[48:51]
	v_mfma_f32_16x16x32_bf16 v[36:39], v[116:119], v[164:167], v[36:39]
	v_mfma_f32_16x16x32_bf16 v[32:35], v[140:143], v[164:167], v[32:35]
	v_mfma_f32_16x16x32_bf16 v[20:23], v[116:119], v[180:183], v[20:23]
	v_mfma_f32_16x16x32_bf16 v[16:19], v[140:143], v[180:183], v[16:19]
	v_mfma_f32_16x16x32_bf16 v[4:7], v[116:119], v[188:191], v[4:7]
	v_mfma_f32_16x16x32_bf16 v[0:3], v[140:143], v[188:191], v[0:3]
	s_barrier
	s_add_i32 s71, s71, 2
	s_add_u32 s88, s88, 0x100
	s_addc_u32 s89, s89, 0
	s_add_u32 s87, s87, 0x100
	s_addc_u32 vcc_hi, vcc_hi, 0
.LBB0_965:
	s_add_u32 s67, s88, 0xfff80080
	s_addc_u32 s74, s89, -1
	s_add_i32 s75, 0, 0x10000
	s_cmp_eq_u32 s71, 28
	s_cselect_b32 s93, s79, s74
	s_cselect_b32 s92, s96, s67
	s_cselect_b32 s91, s77, vcc_hi
	s_cselect_b32 s90, vcc_lo, s87
	s_add_i32 s67, 0, 0x14000
	v_add_u32_e32 v96, s75, v238
	v_add_u32_e32 v140, s67, v238
	ds_read_b128 v[64:67], v96
	ds_read_b128 v[72:75], v96 offset:1024
	ds_read_b128 v[88:91], v96 offset:2048
	ds_read_b128 v[96:99], v96 offset:3072
	ds_read_b128 v[108:111], v140
	ds_read_b128 v[116:119], v140 offset:1024
	ds_read_b128 v[128:131], v140 offset:2048
	ds_read_b128 v[140:143], v140 offset:3072
	v_lshl_add_u64 v[192:193], s[88:89], 0, v[230:231]
	s_add_i32 m0, s28, 0xc000
	ds_read_b128 v[152:155], v240
	ds_read_b128 v[156:159], v240 offset:1024
	ds_read_b128 v[160:163], v240 offset:2048
	ds_read_b128 v[164:167], v240 offset:3072
	ds_read_b128 v[168:171], v240 offset:4096
	ds_read_b128 v[180:183], v240 offset:5120
	ds_read_b128 v[184:187], v240 offset:6144
	ds_read_b128 v[188:191], v240 offset:7168
	global_load_lds_dwordx4 v[192:193], off
	v_lshl_add_u64 v[192:193], s[88:89], 0, v[232:233]
	s_add_i32 m0, s28, 0xe000
	s_nop 0
	global_load_lds_dwordx4 v[192:193], off
	s_waitcnt vmcnt(8)
	s_waitcnt lgkmcnt(0)
	s_barrier
	s_waitcnt lgkmcnt(0)
	v_mfma_f32_16x16x32_bf16 v[176:179], v[64:67], v[152:155], v[176:179]
	v_mfma_f32_16x16x32_bf16 v[172:175], v[88:91], v[152:155], v[172:175]
	v_mfma_f32_16x16x32_bf16 v[136:139], v[64:67], v[160:163], v[136:139]
	v_mfma_f32_16x16x32_bf16 v[132:135], v[88:91], v[160:163], v[132:135]
	v_mfma_f32_16x16x32_bf16 v[112:115], v[64:67], v[168:171], v[112:115]
	v_mfma_f32_16x16x32_bf16 v[104:107], v[88:91], v[168:171], v[104:107]
	v_mfma_f32_16x16x32_bf16 v[84:87], v[64:67], v[184:187], v[84:87]
	v_mfma_f32_16x16x32_bf16 v[80:83], v[88:91], v[184:187], v[80:83]
	v_mfma_f32_16x16x32_bf16 v[176:179], v[72:75], v[156:159], v[176:179]
	v_mfma_f32_16x16x32_bf16 v[172:175], v[96:99], v[156:159], v[172:175]
	v_mfma_f32_16x16x32_bf16 v[136:139], v[72:75], v[164:167], v[136:139]
	v_mfma_f32_16x16x32_bf16 v[132:135], v[96:99], v[164:167], v[132:135]
	v_mfma_f32_16x16x32_bf16 v[112:115], v[72:75], v[180:183], v[112:115]
	v_mfma_f32_16x16x32_bf16 v[104:107], v[96:99], v[180:183], v[104:107]
	v_mfma_f32_16x16x32_bf16 v[84:87], v[72:75], v[188:191], v[84:87]
	v_mfma_f32_16x16x32_bf16 v[80:83], v[96:99], v[188:191], v[80:83]
	v_mfma_f32_16x16x32_bf16 v[148:151], v[108:111], v[152:155], v[148:151]
	v_mfma_f32_16x16x32_bf16 v[144:147], v[128:131], v[152:155], v[144:147]
	v_mfma_f32_16x16x32_bf16 v[124:127], v[108:111], v[160:163], v[124:127]
	v_mfma_f32_16x16x32_bf16 v[120:123], v[128:131], v[160:163], v[120:123]
	v_mfma_f32_16x16x32_bf16 v[100:103], v[108:111], v[168:171], v[100:103]
	v_mfma_f32_16x16x32_bf16 v[92:95], v[128:131], v[168:171], v[92:95]
	v_mfma_f32_16x16x32_bf16 v[76:79], v[108:111], v[184:187], v[76:79]
	v_mfma_f32_16x16x32_bf16 v[68:71], v[128:131], v[184:187], v[68:71]
	v_mfma_f32_16x16x32_bf16 v[148:151], v[116:119], v[156:159], v[148:151]
	v_mfma_f32_16x16x32_bf16 v[144:147], v[140:143], v[156:159], v[144:147]
	v_mfma_f32_16x16x32_bf16 v[124:127], v[116:119], v[164:167], v[124:127]
	v_mfma_f32_16x16x32_bf16 v[120:123], v[140:143], v[164:167], v[120:123]
	v_mfma_f32_16x16x32_bf16 v[100:103], v[116:119], v[180:183], v[100:103]
	v_mfma_f32_16x16x32_bf16 v[92:95], v[140:143], v[180:183], v[92:95]
	v_mfma_f32_16x16x32_bf16 v[76:79], v[116:119], v[188:191], v[76:79]
	v_mfma_f32_16x16x32_bf16 v[68:71], v[140:143], v[188:191], v[68:71]
	s_barrier
	s_add_i32 s74, s75, s2
	v_lshl_add_u64 v[192:193], s[90:91], 0, v[216:217]
	s_mov_b32 m0, s74
	ds_read_b128 v[152:155], v240 offset:16384
	ds_read_b128 v[156:159], v240 offset:17408
	ds_read_b128 v[160:163], v240 offset:18432
	ds_read_b128 v[164:167], v240 offset:19456
	ds_read_b128 v[168:171], v240 offset:20480
	ds_read_b128 v[180:183], v240 offset:21504
	ds_read_b128 v[184:187], v240 offset:22528
	ds_read_b128 v[188:191], v240 offset:23552
	global_load_lds_dwordx4 v[192:193], off
	s_add_i32 m0, s74, 0x2000
	s_add_u32 s74, s90, 0x80000
	v_lshl_add_u64 v[194:195], s[90:91], 0, v[228:229]
	s_addc_u32 s75, s91, 0
	s_add_i32 s67, s67, s2
	global_load_lds_dwordx4 v[194:195], off
	v_lshl_add_u64 v[196:197], s[74:75], 0, v[216:217]
	s_mov_b32 m0, s67
	v_lshl_add_u64 v[198:199], s[92:93], 0, v[226:227]
	global_load_lds_dwordx4 v[196:197], off
	v_lshl_add_u64 v[196:197], s[74:75], 0, v[228:229]
	s_add_i32 m0, s67, 0x2000
	s_nop 0
	global_load_lds_dwordx4 v[196:197], off
	v_lshl_add_u64 v[196:197], s[92:93], 0, v[224:225]
	s_mov_b32 m0, s28
	s_nop 0
	global_load_lds_dwordx4 v[196:197], off
	s_mov_b32 m0, s29
	s_nop 0
	global_load_lds_dwordx4 v[198:199], off
	s_waitcnt vmcnt(8)
	s_waitcnt lgkmcnt(0)
	s_barrier
	s_waitcnt lgkmcnt(0)
	v_mfma_f32_16x16x32_bf16 v[60:63], v[64:67], v[152:155], v[60:63]
	v_mfma_f32_16x16x32_bf16 v[56:59], v[88:91], v[152:155], v[56:59]
	v_mfma_f32_16x16x32_bf16 v[44:47], v[64:67], v[160:163], v[44:47]
	v_mfma_f32_16x16x32_bf16 v[40:43], v[88:91], v[160:163], v[40:43]
	v_mfma_f32_16x16x32_bf16 v[28:31], v[64:67], v[168:171], v[28:31]
	v_mfma_f32_16x16x32_bf16 v[24:27], v[88:91], v[168:171], v[24:27]
	v_mfma_f32_16x16x32_bf16 v[12:15], v[64:67], v[184:187], v[12:15]
	v_mfma_f32_16x16x32_bf16 v[8:11], v[88:91], v[184:187], v[8:11]
	v_mfma_f32_16x16x32_bf16 v[60:63], v[72:75], v[156:159], v[60:63]
	v_mfma_f32_16x16x32_bf16 v[56:59], v[96:99], v[156:159], v[56:59]
	v_mfma_f32_16x16x32_bf16 v[44:47], v[72:75], v[164:167], v[44:47]
	v_mfma_f32_16x16x32_bf16 v[40:43], v[96:99], v[164:167], v[40:43]
	v_mfma_f32_16x16x32_bf16 v[28:31], v[72:75], v[180:183], v[28:31]
	v_mfma_f32_16x16x32_bf16 v[24:27], v[96:99], v[180:183], v[24:27]
	v_mfma_f32_16x16x32_bf16 v[12:15], v[72:75], v[188:191], v[12:15]
	v_mfma_f32_16x16x32_bf16 v[8:11], v[96:99], v[188:191], v[8:11]
	v_mfma_f32_16x16x32_bf16 v[52:55], v[108:111], v[152:155], v[52:55]
	v_mfma_f32_16x16x32_bf16 v[48:51], v[128:131], v[152:155], v[48:51]
	v_mfma_f32_16x16x32_bf16 v[36:39], v[108:111], v[160:163], v[36:39]
	v_mfma_f32_16x16x32_bf16 v[32:35], v[128:131], v[160:163], v[32:35]
	v_mfma_f32_16x16x32_bf16 v[20:23], v[108:111], v[168:171], v[20:23]
	v_mfma_f32_16x16x32_bf16 v[16:19], v[128:131], v[168:171], v[16:19]
	v_mfma_f32_16x16x32_bf16 v[4:7], v[108:111], v[184:187], v[4:7]
	v_mfma_f32_16x16x32_bf16 v[0:3], v[128:131], v[184:187], v[0:3]
	v_mfma_f32_16x16x32_bf16 v[52:55], v[116:119], v[156:159], v[52:55]
	v_mfma_f32_16x16x32_bf16 v[48:51], v[140:143], v[156:159], v[48:51]
	v_mfma_f32_16x16x32_bf16 v[36:39], v[116:119], v[164:167], v[36:39]
	v_mfma_f32_16x16x32_bf16 v[32:35], v[140:143], v[164:167], v[32:35]
	v_mfma_f32_16x16x32_bf16 v[20:23], v[116:119], v[180:183], v[20:23]
	v_mfma_f32_16x16x32_bf16 v[16:19], v[140:143], v[180:183], v[16:19]
	v_mfma_f32_16x16x32_bf16 v[4:7], v[116:119], v[188:191], v[4:7]
	v_mfma_f32_16x16x32_bf16 v[0:3], v[140:143], v[188:191], v[0:3]
	s_barrier
	s_add_i32 s67, 0, 0x18000
	s_add_i32 s3, 0, 0x1c000
	v_add_u32_e32 v96, s67, v238
	v_add_u32_e32 v140, s3, v238
	ds_read_b128 v[64:67], v96
	ds_read_b128 v[72:75], v96 offset:1024
	ds_read_b128 v[88:91], v96 offset:2048
	ds_read_b128 v[96:99], v96 offset:3072
	ds_read_b128 v[108:111], v140
	ds_read_b128 v[116:119], v140 offset:1024
	ds_read_b128 v[128:131], v140 offset:2048
	ds_read_b128 v[140:143], v140 offset:3072
	s_add_u32 s74, s92, 0x80000
	s_addc_u32 s75, s93, 0
	s_mov_b32 m0, s34
	v_lshl_add_u64 v[200:201], s[74:75], 0, v[224:225]
	ds_read_b128 v[152:155], v240 offset:32768
	ds_read_b128 v[156:159], v240 offset:33792
	ds_read_b128 v[160:163], v240 offset:34816
	ds_read_b128 v[164:167], v240 offset:35840
	ds_read_b128 v[168:171], v240 offset:36864
	ds_read_b128 v[180:183], v240 offset:37888
	ds_read_b128 v[184:187], v240 offset:38912
	ds_read_b128 v[188:191], v240 offset:39936
	global_load_lds_dwordx4 v[200:201], off
	v_lshl_add_u64 v[200:201], s[74:75], 0, v[226:227]
	s_mov_b32 m0, s35
	s_nop 0
	global_load_lds_dwordx4 v[200:201], off
	s_waitcnt vmcnt(8)
	s_waitcnt lgkmcnt(0)
	s_barrier
	s_waitcnt lgkmcnt(0)
	v_mfma_f32_16x16x32_bf16 v[176:179], v[64:67], v[152:155], v[176:179]
	v_mfma_f32_16x16x32_bf16 v[172:175], v[88:91], v[152:155], v[172:175]
	v_mfma_f32_16x16x32_bf16 v[136:139], v[64:67], v[160:163], v[136:139]
	v_mfma_f32_16x16x32_bf16 v[132:135], v[88:91], v[160:163], v[132:135]
	v_mfma_f32_16x16x32_bf16 v[112:115], v[64:67], v[168:171], v[112:115]
	v_mfma_f32_16x16x32_bf16 v[104:107], v[88:91], v[168:171], v[104:107]
	v_mfma_f32_16x16x32_bf16 v[84:87], v[64:67], v[184:187], v[84:87]
	v_mfma_f32_16x16x32_bf16 v[80:83], v[88:91], v[184:187], v[80:83]
	v_mfma_f32_16x16x32_bf16 v[176:179], v[72:75], v[156:159], v[176:179]
	v_mfma_f32_16x16x32_bf16 v[172:175], v[96:99], v[156:159], v[172:175]
	v_mfma_f32_16x16x32_bf16 v[136:139], v[72:75], v[164:167], v[136:139]
	v_mfma_f32_16x16x32_bf16 v[132:135], v[96:99], v[164:167], v[132:135]
	v_mfma_f32_16x16x32_bf16 v[112:115], v[72:75], v[180:183], v[112:115]
	v_mfma_f32_16x16x32_bf16 v[104:107], v[96:99], v[180:183], v[104:107]
	v_mfma_f32_16x16x32_bf16 v[84:87], v[72:75], v[188:191], v[84:87]
	v_mfma_f32_16x16x32_bf16 v[80:83], v[96:99], v[188:191], v[80:83]
	v_mfma_f32_16x16x32_bf16 v[148:151], v[108:111], v[152:155], v[148:151]
	v_mfma_f32_16x16x32_bf16 v[144:147], v[128:131], v[152:155], v[144:147]
	v_mfma_f32_16x16x32_bf16 v[124:127], v[108:111], v[160:163], v[124:127]
	v_mfma_f32_16x16x32_bf16 v[120:123], v[128:131], v[160:163], v[120:123]
	v_mfma_f32_16x16x32_bf16 v[100:103], v[108:111], v[168:171], v[100:103]
	v_mfma_f32_16x16x32_bf16 v[92:95], v[128:131], v[168:171], v[92:95]
	v_mfma_f32_16x16x32_bf16 v[76:79], v[108:111], v[184:187], v[76:79]
	v_mfma_f32_16x16x32_bf16 v[68:71], v[128:131], v[184:187], v[68:71]
	v_mfma_f32_16x16x32_bf16 v[148:151], v[116:119], v[156:159], v[148:151]
	v_mfma_f32_16x16x32_bf16 v[144:147], v[140:143], v[156:159], v[144:147]
	v_mfma_f32_16x16x32_bf16 v[124:127], v[116:119], v[164:167], v[124:127]
	v_mfma_f32_16x16x32_bf16 v[120:123], v[140:143], v[164:167], v[120:123]
	v_mfma_f32_16x16x32_bf16 v[100:103], v[116:119], v[180:183], v[100:103]
	v_mfma_f32_16x16x32_bf16 v[92:95], v[140:143], v[180:183], v[92:95]
	v_mfma_f32_16x16x32_bf16 v[76:79], v[116:119], v[188:191], v[76:79]
	v_mfma_f32_16x16x32_bf16 v[68:71], v[140:143], v[188:191], v[68:71]
	s_barrier
	s_add_i32 s67, s67, s2
	v_lshl_add_u64 v[192:193], v[192:193], 0, s[30:31]
	s_mov_b32 m0, s67
	ds_read_b128 v[152:155], v240 offset:49152
	ds_read_b128 v[156:159], v240 offset:50176
	ds_read_b128 v[160:163], v240 offset:51200
	ds_read_b128 v[164:167], v240 offset:52224
	ds_read_b128 v[168:171], v240 offset:53248
	ds_read_b128 v[180:183], v240 offset:54272
	ds_read_b128 v[184:187], v240 offset:55296
	ds_read_b128 v[188:191], v240 offset:56320
	global_load_lds_dwordx4 v[192:193], off
	s_add_i32 m0, s67, 0x2000
	s_add_u32 s74, s90, 0x80080
	v_lshl_add_u64 v[192:193], v[194:195], 0, s[30:31]
	s_addc_u32 s75, s91, 0
	s_add_i32 s3, s3, s2
	global_load_lds_dwordx4 v[192:193], off
	v_lshl_add_u64 v[192:193], s[74:75], 0, v[216:217]
	s_mov_b32 m0, s3
	s_nop 0
	global_load_lds_dwordx4 v[192:193], off
	v_lshl_add_u64 v[192:193], s[74:75], 0, v[228:229]
	s_add_i32 m0, s3, 0x2000
	s_nop 0
	global_load_lds_dwordx4 v[192:193], off
	v_lshl_add_u64 v[192:193], v[196:197], 0, s[30:31]
	s_mov_b32 m0, s60
	s_nop 0
	global_load_lds_dwordx4 v[192:193], off
	v_lshl_add_u64 v[192:193], v[198:199], 0, s[30:31]
	s_mov_b32 m0, s61
	s_nop 0
	global_load_lds_dwordx4 v[192:193], off
	s_waitcnt vmcnt(8)
	s_waitcnt lgkmcnt(0)
	s_barrier
	s_waitcnt lgkmcnt(0)
	v_mfma_f32_16x16x32_bf16 v[60:63], v[64:67], v[152:155], v[60:63]
	v_mfma_f32_16x16x32_bf16 v[56:59], v[88:91], v[152:155], v[56:59]
	v_mfma_f32_16x16x32_bf16 v[44:47], v[64:67], v[160:163], v[44:47]
	v_mfma_f32_16x16x32_bf16 v[40:43], v[88:91], v[160:163], v[40:43]
	v_mfma_f32_16x16x32_bf16 v[28:31], v[64:67], v[168:171], v[28:31]
	v_mfma_f32_16x16x32_bf16 v[24:27], v[88:91], v[168:171], v[24:27]
	v_mfma_f32_16x16x32_bf16 v[12:15], v[64:67], v[184:187], v[12:15]
	v_mfma_f32_16x16x32_bf16 v[8:11], v[88:91], v[184:187], v[8:11]
	v_mfma_f32_16x16x32_bf16 v[60:63], v[72:75], v[156:159], v[60:63]
	v_mfma_f32_16x16x32_bf16 v[56:59], v[96:99], v[156:159], v[56:59]
	v_mfma_f32_16x16x32_bf16 v[44:47], v[72:75], v[164:167], v[44:47]
	v_mfma_f32_16x16x32_bf16 v[40:43], v[96:99], v[164:167], v[40:43]
	v_mfma_f32_16x16x32_bf16 v[28:31], v[72:75], v[180:183], v[28:31]
	v_mfma_f32_16x16x32_bf16 v[24:27], v[96:99], v[180:183], v[24:27]
	v_mfma_f32_16x16x32_bf16 v[12:15], v[72:75], v[188:191], v[12:15]
	v_mfma_f32_16x16x32_bf16 v[8:11], v[96:99], v[188:191], v[8:11]
	v_mfma_f32_16x16x32_bf16 v[52:55], v[108:111], v[152:155], v[52:55]
	v_mfma_f32_16x16x32_bf16 v[48:51], v[128:131], v[152:155], v[48:51]
	v_mfma_f32_16x16x32_bf16 v[36:39], v[108:111], v[160:163], v[36:39]
	v_mfma_f32_16x16x32_bf16 v[32:35], v[128:131], v[160:163], v[32:35]
	v_mfma_f32_16x16x32_bf16 v[20:23], v[108:111], v[168:171], v[20:23]
	v_mfma_f32_16x16x32_bf16 v[16:19], v[128:131], v[168:171], v[16:19]
	v_mfma_f32_16x16x32_bf16 v[4:7], v[108:111], v[184:187], v[4:7]
	v_mfma_f32_16x16x32_bf16 v[0:3], v[128:131], v[184:187], v[0:3]
	v_mfma_f32_16x16x32_bf16 v[52:55], v[116:119], v[156:159], v[52:55]
	v_mfma_f32_16x16x32_bf16 v[48:51], v[140:143], v[156:159], v[48:51]
	v_mfma_f32_16x16x32_bf16 v[36:39], v[116:119], v[164:167], v[36:39]
	v_mfma_f32_16x16x32_bf16 v[32:35], v[140:143], v[164:167], v[32:35]
	v_mfma_f32_16x16x32_bf16 v[20:23], v[116:119], v[180:183], v[20:23]
	v_mfma_f32_16x16x32_bf16 v[16:19], v[140:143], v[180:183], v[16:19]
	v_mfma_f32_16x16x32_bf16 v[4:7], v[116:119], v[188:191], v[4:7]
	v_mfma_f32_16x16x32_bf16 v[0:3], v[140:143], v[188:191], v[0:3]
	s_barrier
	s_add_i32 s71, s71, 2
	s_add_u32 s88, s88, 0x100
	s_addc_u32 s89, s89, 0
	s_add_u32 s87, s87, 0x100
	s_addc_u32 vcc_hi, vcc_hi, 0
	s_cmp_gt_u32 s71, 29
	s_cbranch_scc0 .LBB0_965
	s_and_b64 vcc, exec, s[22:23]
	s_cbranch_vccz .LBB0_968
	s_barrier

.LBB0_1189:
	s_ashr_i32 s75, s74, 31
	s_lshl_b64 s[72:73], s[74:75], 20
	s_add_u32 s76, s2, s72
	s_addc_u32 s77, s3, s73
	s_and_b64 s[72:73], s[4:5], exec
	s_cselect_b32 s71, s77, s83
	s_cselect_b32 s72, s76, s82
	s_ashr_i32 s23, s22, 31
	s_lshl_b64 s[78:79], s[22:23], 20
	s_add_u32 s78, s14, s78
	s_addc_u32 s79, s15, s79
	s_and_b64 s[86:87], s[4:5], exec
	s_cselect_b32 s23, s79, s85
	s_cselect_b32 s73, s78, s84
	s_add_u32 s82, s82, 0x80080
	s_addc_u32 s83, s83, 0
	s_add_u32 s75, s84, 0x100
	s_addc_u32 s81, s85, 0
	s_mov_b32 s88, -2
	s_add_u32 s67, s82, 0xfff80080
	s_addc_u32 s84, s83, -1
	s_add_i32 s89, 0, 0x10000
	s_cmp_eq_u32 s88, 28
	s_cselect_b32 s87, s71, s84
	s_cselect_b32 s86, s72, s67
	s_cselect_b32 s85, s23, s81
	s_cselect_b32 s84, s73, s75
	s_add_i32 s67, 0, 0x14000
	v_add_u32_e32 v76, s89, v192
	v_add_u32_e32 v156, s67, v192
	ds_read_b128 v[64:67], v76
	ds_read_b128 v[68:71], v76 offset:1024
	ds_read_b128 v[72:75], v76 offset:2048
	ds_read_b128 v[76:79], v76 offset:3072
	ds_read_b128 v[80:83], v156
	ds_read_b128 v[116:119], v156 offset:1024
	ds_read_b128 v[152:155], v156 offset:2048
	ds_read_b128 v[156:159], v156 offset:3072
	v_lshl_add_u64 v[190:191], s[82:83], 0, v[186:187]
	s_add_i32 m0, s28, 0xc000
	ds_read_b128 v[160:163], v193
	ds_read_b128 v[164:167], v193 offset:1024
	ds_read_b128 v[168:171], v193 offset:2048
	ds_read_b128 v[172:175], v193 offset:3072
	ds_read_b128 v[194:197], v193 offset:4096
	ds_read_b128 v[198:201], v193 offset:5120
	ds_read_b128 v[202:205], v193 offset:6144
	ds_read_b128 v[206:209], v193 offset:7168
	global_load_lds_dwordx4 v[190:191], off
	v_lshl_add_u64 v[190:191], s[82:83], 0, v[188:189]
	s_add_i32 m0, s28, 0xe000
	s_nop 0
	global_load_lds_dwordx4 v[190:191], off
	s_waitcnt vmcnt(8)
	s_waitcnt lgkmcnt(0)
	s_barrier
	s_waitcnt lgkmcnt(0)
	v_mfma_f32_16x16x32_bf16 v[148:151], v[64:67], v[160:163], 0
	v_mfma_f32_16x16x32_bf16 v[144:147], v[72:75], v[160:163], 0
	v_mfma_f32_16x16x32_bf16 v[132:135], v[64:67], v[168:171], 0
	v_mfma_f32_16x16x32_bf16 v[128:131], v[72:75], v[168:171], 0
	v_mfma_f32_16x16x32_bf16 v[112:115], v[64:67], v[194:197], 0
	v_mfma_f32_16x16x32_bf16 v[108:111], v[72:75], v[194:197], 0
	v_mfma_f32_16x16x32_bf16 v[96:99], v[64:67], v[202:205], 0
	v_mfma_f32_16x16x32_bf16 v[92:95], v[72:75], v[202:205], 0
	v_mfma_f32_16x16x32_bf16 v[148:151], v[68:71], v[164:167], v[148:151]
	v_mfma_f32_16x16x32_bf16 v[144:147], v[76:79], v[164:167], v[144:147]
	v_mfma_f32_16x16x32_bf16 v[132:135], v[68:71], v[172:175], v[132:135]
	v_mfma_f32_16x16x32_bf16 v[128:131], v[76:79], v[172:175], v[128:131]
	v_mfma_f32_16x16x32_bf16 v[112:115], v[68:71], v[198:201], v[112:115]
	v_mfma_f32_16x16x32_bf16 v[108:111], v[76:79], v[198:201], v[108:111]
	v_mfma_f32_16x16x32_bf16 v[96:99], v[68:71], v[206:209], v[96:99]
	v_mfma_f32_16x16x32_bf16 v[92:95], v[76:79], v[206:209], v[92:95]
	v_mfma_f32_16x16x32_bf16 v[140:143], v[80:83], v[160:163], 0
	v_mfma_f32_16x16x32_bf16 v[136:139], v[152:155], v[160:163], 0
	v_mfma_f32_16x16x32_bf16 v[124:127], v[80:83], v[168:171], 0
	v_mfma_f32_16x16x32_bf16 v[120:123], v[152:155], v[168:171], 0
	v_mfma_f32_16x16x32_bf16 v[104:107], v[80:83], v[194:197], 0
	v_mfma_f32_16x16x32_bf16 v[100:103], v[152:155], v[194:197], 0
	v_mfma_f32_16x16x32_bf16 v[88:91], v[80:83], v[202:205], 0
	v_mfma_f32_16x16x32_bf16 v[84:87], v[152:155], v[202:205], 0
	v_mfma_f32_16x16x32_bf16 v[140:143], v[116:119], v[164:167], v[140:143]
	v_mfma_f32_16x16x32_bf16 v[136:139], v[156:159], v[164:167], v[136:139]
	v_mfma_f32_16x16x32_bf16 v[124:127], v[116:119], v[172:175], v[124:127]
	v_mfma_f32_16x16x32_bf16 v[120:123], v[156:159], v[172:175], v[120:123]
	v_mfma_f32_16x16x32_bf16 v[104:107], v[116:119], v[198:201], v[104:107]
	v_mfma_f32_16x16x32_bf16 v[100:103], v[156:159], v[198:201], v[100:103]
	v_mfma_f32_16x16x32_bf16 v[88:91], v[116:119], v[206:209], v[88:91]
	v_mfma_f32_16x16x32_bf16 v[84:87], v[156:159], v[206:209], v[84:87]
	s_barrier
	s_add_i32 s89, s89, s24
	v_lshl_add_u64 v[190:191], s[84:85], 0, v[180:181]
	s_mov_b32 m0, s89
	ds_read_b128 v[160:163], v193 offset:16384
	ds_read_b128 v[164:167], v193 offset:17408
	ds_read_b128 v[168:171], v193 offset:18432
	ds_read_b128 v[172:175], v193 offset:19456
	ds_read_b128 v[194:197], v193 offset:20480
	ds_read_b128 v[198:201], v193 offset:21504
	ds_read_b128 v[202:205], v193 offset:22528
	ds_read_b128 v[206:209], v193 offset:23552
	global_load_lds_dwordx4 v[190:191], off
	s_add_i32 m0, s89, 0x2000
	s_add_u32 s90, s84, 0x80000
	v_lshl_add_u64 v[210:211], s[84:85], 0, v[176:177]
	s_addc_u32 s91, s85, 0
	s_add_i32 s67, s67, s24
	global_load_lds_dwordx4 v[210:211], off
	v_lshl_add_u64 v[212:213], s[90:91], 0, v[180:181]
	s_mov_b32 m0, s67
	v_lshl_add_u64 v[214:215], s[86:87], 0, v[178:179]
	global_load_lds_dwordx4 v[212:213], off
	v_lshl_add_u64 v[212:213], s[90:91], 0, v[176:177]
	s_add_i32 m0, s67, 0x2000
	s_nop 0
	global_load_lds_dwordx4 v[212:213], off
	v_lshl_add_u64 v[212:213], s[86:87], 0, v[182:183]
	s_mov_b32 m0, s28
	s_nop 0
	global_load_lds_dwordx4 v[212:213], off
	s_mov_b32 m0, s29
	s_nop 0
	global_load_lds_dwordx4 v[214:215], off
	s_waitcnt vmcnt(8)
	s_waitcnt lgkmcnt(0)
	s_barrier
	s_waitcnt lgkmcnt(0)
	v_mfma_f32_16x16x32_bf16 v[60:63], v[64:67], v[160:163], 0
	v_mfma_f32_16x16x32_bf16 v[56:59], v[72:75], v[160:163], 0
	v_mfma_f32_16x16x32_bf16 v[44:47], v[64:67], v[168:171], 0
	v_mfma_f32_16x16x32_bf16 v[40:43], v[72:75], v[168:171], 0
	v_mfma_f32_16x16x32_bf16 v[28:31], v[64:67], v[194:197], 0
	v_mfma_f32_16x16x32_bf16 v[24:27], v[72:75], v[194:197], 0
	v_mfma_f32_16x16x32_bf16 v[12:15], v[64:67], v[202:205], 0
	v_mfma_f32_16x16x32_bf16 v[8:11], v[72:75], v[202:205], 0
	v_mfma_f32_16x16x32_bf16 v[60:63], v[68:71], v[164:167], v[60:63]
	v_mfma_f32_16x16x32_bf16 v[56:59], v[76:79], v[164:167], v[56:59]
	v_mfma_f32_16x16x32_bf16 v[44:47], v[68:71], v[172:175], v[44:47]
	v_mfma_f32_16x16x32_bf16 v[40:43], v[76:79], v[172:175], v[40:43]
	v_mfma_f32_16x16x32_bf16 v[28:31], v[68:71], v[198:201], v[28:31]
	v_mfma_f32_16x16x32_bf16 v[24:27], v[76:79], v[198:201], v[24:27]
	v_mfma_f32_16x16x32_bf16 v[12:15], v[68:71], v[206:209], v[12:15]
	v_mfma_f32_16x16x32_bf16 v[8:11], v[76:79], v[206:209], v[8:11]
	v_mfma_f32_16x16x32_bf16 v[52:55], v[80:83], v[160:163], 0
	v_mfma_f32_16x16x32_bf16 v[48:51], v[152:155], v[160:163], 0
	v_mfma_f32_16x16x32_bf16 v[36:39], v[80:83], v[168:171], 0
	v_mfma_f32_16x16x32_bf16 v[32:35], v[152:155], v[168:171], 0
	v_mfma_f32_16x16x32_bf16 v[20:23], v[80:83], v[194:197], 0
	v_mfma_f32_16x16x32_bf16 v[16:19], v[152:155], v[194:197], 0
	v_mfma_f32_16x16x32_bf16 v[4:7], v[80:83], v[202:205], 0
	v_mfma_f32_16x16x32_bf16 v[0:3], v[152:155], v[202:205], 0
	v_mfma_f32_16x16x32_bf16 v[52:55], v[116:119], v[164:167], v[52:55]
	v_mfma_f32_16x16x32_bf16 v[48:51], v[156:159], v[164:167], v[48:51]
	v_mfma_f32_16x16x32_bf16 v[36:39], v[116:119], v[172:175], v[36:39]
	v_mfma_f32_16x16x32_bf16 v[32:35], v[156:159], v[172:175], v[32:35]
	v_mfma_f32_16x16x32_bf16 v[20:23], v[116:119], v[198:201], v[20:23]
	v_mfma_f32_16x16x32_bf16 v[16:19], v[156:159], v[198:201], v[16:19]
	v_mfma_f32_16x16x32_bf16 v[4:7], v[116:119], v[206:209], v[4:7]
	v_mfma_f32_16x16x32_bf16 v[0:3], v[156:159], v[206:209], v[0:3]
	s_barrier
	s_add_i32 s67, 0, 0x18000
	s_add_i32 s89, 0, 0x1c000
	v_add_u32_e32 v76, s67, v192
	v_add_u32_e32 v156, s89, v192
	ds_read_b128 v[64:67], v76
	ds_read_b128 v[68:71], v76 offset:1024
	ds_read_b128 v[72:75], v76 offset:2048
	ds_read_b128 v[76:79], v76 offset:3072
	ds_read_b128 v[80:83], v156
	ds_read_b128 v[116:119], v156 offset:1024
	ds_read_b128 v[152:155], v156 offset:2048
	ds_read_b128 v[156:159], v156 offset:3072
	s_add_u32 s86, s86, 0x80000
	s_addc_u32 s87, s87, 0
	s_mov_b32 m0, s34
	v_lshl_add_u64 v[218:219], s[86:87], 0, v[182:183]
	ds_read_b128 v[160:163], v193 offset:32768
	ds_read_b128 v[164:167], v193 offset:33792
	ds_read_b128 v[168:171], v193 offset:34816
	ds_read_b128 v[172:175], v193 offset:35840
	ds_read_b128 v[194:197], v193 offset:36864
	ds_read_b128 v[198:201], v193 offset:37888
	ds_read_b128 v[202:205], v193 offset:38912
	ds_read_b128 v[206:209], v193 offset:39936
	global_load_lds_dwordx4 v[218:219], off
	v_lshl_add_u64 v[218:219], s[86:87], 0, v[178:179]
	s_mov_b32 m0, s35
	s_nop 0
	global_load_lds_dwordx4 v[218:219], off
	s_waitcnt vmcnt(8)
	s_waitcnt lgkmcnt(0)
	s_barrier
	s_waitcnt lgkmcnt(0)
	v_mfma_f32_16x16x32_bf16 v[148:151], v[64:67], v[160:163], v[148:151]
	v_mfma_f32_16x16x32_bf16 v[144:147], v[72:75], v[160:163], v[144:147]
	v_mfma_f32_16x16x32_bf16 v[132:135], v[64:67], v[168:171], v[132:135]
	v_mfma_f32_16x16x32_bf16 v[128:131], v[72:75], v[168:171], v[128:131]
	v_mfma_f32_16x16x32_bf16 v[112:115], v[64:67], v[194:197], v[112:115]
	v_mfma_f32_16x16x32_bf16 v[108:111], v[72:75], v[194:197], v[108:111]
	v_mfma_f32_16x16x32_bf16 v[96:99], v[64:67], v[202:205], v[96:99]
	v_mfma_f32_16x16x32_bf16 v[92:95], v[72:75], v[202:205], v[92:95]
	v_mfma_f32_16x16x32_bf16 v[148:151], v[68:71], v[164:167], v[148:151]
	v_mfma_f32_16x16x32_bf16 v[144:147], v[76:79], v[164:167], v[144:147]
	v_mfma_f32_16x16x32_bf16 v[132:135], v[68:71], v[172:175], v[132:135]
	v_mfma_f32_16x16x32_bf16 v[128:131], v[76:79], v[172:175], v[128:131]
	v_mfma_f32_16x16x32_bf16 v[112:115], v[68:71], v[198:201], v[112:115]
	v_mfma_f32_16x16x32_bf16 v[108:111], v[76:79], v[198:201], v[108:111]
	v_mfma_f32_16x16x32_bf16 v[96:99], v[68:71], v[206:209], v[96:99]
	v_mfma_f32_16x16x32_bf16 v[92:95], v[76:79], v[206:209], v[92:95]
	v_mfma_f32_16x16x32_bf16 v[140:143], v[80:83], v[160:163], v[140:143]
	v_mfma_f32_16x16x32_bf16 v[136:139], v[152:155], v[160:163], v[136:139]
	v_mfma_f32_16x16x32_bf16 v[124:127], v[80:83], v[168:171], v[124:127]
	v_mfma_f32_16x16x32_bf16 v[120:123], v[152:155], v[168:171], v[120:123]
	v_mfma_f32_16x16x32_bf16 v[104:107], v[80:83], v[194:197], v[104:107]
	v_mfma_f32_16x16x32_bf16 v[100:103], v[152:155], v[194:197], v[100:103]
	v_mfma_f32_16x16x32_bf16 v[88:91], v[80:83], v[202:205], v[88:91]
	v_mfma_f32_16x16x32_bf16 v[84:87], v[152:155], v[202:205], v[84:87]
	v_mfma_f32_16x16x32_bf16 v[140:143], v[116:119], v[164:167], v[140:143]
	v_mfma_f32_16x16x32_bf16 v[136:139], v[156:159], v[164:167], v[136:139]
	v_mfma_f32_16x16x32_bf16 v[124:127], v[116:119], v[172:175], v[124:127]
	v_mfma_f32_16x16x32_bf16 v[120:123], v[156:159], v[172:175], v[120:123]
	v_mfma_f32_16x16x32_bf16 v[104:107], v[116:119], v[198:201], v[104:107]
	v_mfma_f32_16x16x32_bf16 v[100:103], v[156:159], v[198:201], v[100:103]
	v_mfma_f32_16x16x32_bf16 v[88:91], v[116:119], v[206:209], v[88:91]
	v_mfma_f32_16x16x32_bf16 v[84:87], v[156:159], v[206:209], v[84:87]
	s_barrier
	s_add_i32 s67, s67, s24
	v_lshl_add_u64 v[190:191], v[190:191], 0, s[30:31]
	s_mov_b32 m0, s67
	ds_read_b128 v[160:163], v193 offset:49152
	ds_read_b128 v[164:167], v193 offset:50176
	ds_read_b128 v[168:171], v193 offset:51200
	ds_read_b128 v[172:175], v193 offset:52224
	ds_read_b128 v[194:197], v193 offset:53248
	ds_read_b128 v[198:201], v193 offset:54272
	ds_read_b128 v[202:205], v193 offset:55296
	ds_read_b128 v[206:209], v193 offset:56320
	global_load_lds_dwordx4 v[190:191], off
	s_add_i32 m0, s67, 0x2000
	s_add_u32 s84, s84, 0x80080
	v_lshl_add_u64 v[190:191], v[210:211], 0, s[30:31]
	s_addc_u32 s85, s85, 0
	s_add_i32 s67, s89, s24
	global_load_lds_dwordx4 v[190:191], off
	v_lshl_add_u64 v[190:191], s[84:85], 0, v[180:181]
	s_mov_b32 m0, s67
	s_nop 0
	global_load_lds_dwordx4 v[190:191], off
	v_lshl_add_u64 v[190:191], s[84:85], 0, v[176:177]
	s_add_i32 m0, s67, 0x2000
	s_nop 0
	global_load_lds_dwordx4 v[190:191], off
	v_lshl_add_u64 v[190:191], v[212:213], 0, s[30:31]
	s_mov_b32 m0, s53
	s_nop 0
	global_load_lds_dwordx4 v[190:191], off
	v_lshl_add_u64 v[190:191], v[214:215], 0, s[30:31]
	s_mov_b32 m0, s54
	s_nop 0
	global_load_lds_dwordx4 v[190:191], off
	s_waitcnt vmcnt(8)
	s_waitcnt lgkmcnt(0)
	s_barrier
	s_waitcnt lgkmcnt(0)
	v_mfma_f32_16x16x32_bf16 v[60:63], v[64:67], v[160:163], v[60:63]
	v_mfma_f32_16x16x32_bf16 v[56:59], v[72:75], v[160:163], v[56:59]
	v_mfma_f32_16x16x32_bf16 v[44:47], v[64:67], v[168:171], v[44:47]
	v_mfma_f32_16x16x32_bf16 v[40:43], v[72:75], v[168:171], v[40:43]
	v_mfma_f32_16x16x32_bf16 v[28:31], v[64:67], v[194:197], v[28:31]
	v_mfma_f32_16x16x32_bf16 v[24:27], v[72:75], v[194:197], v[24:27]
	v_mfma_f32_16x16x32_bf16 v[12:15], v[64:67], v[202:205], v[12:15]
	v_mfma_f32_16x16x32_bf16 v[8:11], v[72:75], v[202:205], v[8:11]
	v_mfma_f32_16x16x32_bf16 v[60:63], v[68:71], v[164:167], v[60:63]
	v_mfma_f32_16x16x32_bf16 v[56:59], v[76:79], v[164:167], v[56:59]
	v_mfma_f32_16x16x32_bf16 v[44:47], v[68:71], v[172:175], v[44:47]
	v_mfma_f32_16x16x32_bf16 v[40:43], v[76:79], v[172:175], v[40:43]
	v_mfma_f32_16x16x32_bf16 v[28:31], v[68:71], v[198:201], v[28:31]
	v_mfma_f32_16x16x32_bf16 v[24:27], v[76:79], v[198:201], v[24:27]
	v_mfma_f32_16x16x32_bf16 v[12:15], v[68:71], v[206:209], v[12:15]
	v_mfma_f32_16x16x32_bf16 v[8:11], v[76:79], v[206:209], v[8:11]
	v_mfma_f32_16x16x32_bf16 v[52:55], v[80:83], v[160:163], v[52:55]
	v_mfma_f32_16x16x32_bf16 v[48:51], v[152:155], v[160:163], v[48:51]
	v_mfma_f32_16x16x32_bf16 v[36:39], v[80:83], v[168:171], v[36:39]
	v_mfma_f32_16x16x32_bf16 v[32:35], v[152:155], v[168:171], v[32:35]
	v_mfma_f32_16x16x32_bf16 v[20:23], v[80:83], v[194:197], v[20:23]
	v_mfma_f32_16x16x32_bf16 v[16:19], v[152:155], v[194:197], v[16:19]
	v_mfma_f32_16x16x32_bf16 v[4:7], v[80:83], v[202:205], v[4:7]
	v_mfma_f32_16x16x32_bf16 v[0:3], v[152:155], v[202:205], v[0:3]
	v_mfma_f32_16x16x32_bf16 v[52:55], v[116:119], v[164:167], v[52:55]
	v_mfma_f32_16x16x32_bf16 v[48:51], v[156:159], v[164:167], v[48:51]
	v_mfma_f32_16x16x32_bf16 v[36:39], v[116:119], v[172:175], v[36:39]
	v_mfma_f32_16x16x32_bf16 v[32:35], v[156:159], v[172:175], v[32:35]
	v_mfma_f32_16x16x32_bf16 v[20:23], v[116:119], v[198:201], v[20:23]
	v_mfma_f32_16x16x32_bf16 v[16:19], v[156:159], v[198:201], v[16:19]
	v_mfma_f32_16x16x32_bf16 v[4:7], v[116:119], v[206:209], v[4:7]
	v_mfma_f32_16x16x32_bf16 v[0:3], v[156:159], v[206:209], v[0:3]
	s_barrier
	s_add_i32 s88, s88, 2
	s_add_u32 s82, s82, 0x100
	s_addc_u32 s83, s83, 0
	s_add_u32 s75, s75, 0x100
	s_addc_u32 s81, s81, 0
.LBB0_1190:
	s_add_u32 s67, s82, 0xfff80080
	s_addc_u32 s84, s83, -1
	s_add_i32 s89, 0, 0x10000
	s_cmp_eq_u32 s88, 28
	s_cselect_b32 s87, s71, s84
	s_cselect_b32 s86, s72, s67
	s_cselect_b32 s85, s23, s81
	s_cselect_b32 s84, s73, s75
	s_add_i32 s67, 0, 0x14000
	v_add_u32_e32 v76, s89, v192
	v_add_u32_e32 v156, s67, v192
	ds_read_b128 v[64:67], v76
	ds_read_b128 v[68:71], v76 offset:1024
	ds_read_b128 v[72:75], v76 offset:2048
	ds_read_b128 v[76:79], v76 offset:3072
	ds_read_b128 v[80:83], v156
	ds_read_b128 v[116:119], v156 offset:1024
	ds_read_b128 v[152:155], v156 offset:2048
	ds_read_b128 v[156:159], v156 offset:3072
	v_lshl_add_u64 v[190:191], s[82:83], 0, v[186:187]
	s_add_i32 m0, s28, 0xc000
	ds_read_b128 v[160:163], v193
	ds_read_b128 v[164:167], v193 offset:1024
	ds_read_b128 v[168:171], v193 offset:2048
	ds_read_b128 v[172:175], v193 offset:3072
	ds_read_b128 v[194:197], v193 offset:4096
	ds_read_b128 v[198:201], v193 offset:5120
	ds_read_b128 v[202:205], v193 offset:6144
	ds_read_b128 v[206:209], v193 offset:7168
	global_load_lds_dwordx4 v[190:191], off
	v_lshl_add_u64 v[190:191], s[82:83], 0, v[188:189]
	s_add_i32 m0, s28, 0xe000
	s_nop 0
	global_load_lds_dwordx4 v[190:191], off
	s_waitcnt vmcnt(8)
	s_waitcnt lgkmcnt(0)
	s_barrier
	s_waitcnt lgkmcnt(0)
	v_mfma_f32_16x16x32_bf16 v[148:151], v[64:67], v[160:163], v[148:151]
	v_mfma_f32_16x16x32_bf16 v[144:147], v[72:75], v[160:163], v[144:147]
	v_mfma_f32_16x16x32_bf16 v[132:135], v[64:67], v[168:171], v[132:135]
	v_mfma_f32_16x16x32_bf16 v[128:131], v[72:75], v[168:171], v[128:131]
	v_mfma_f32_16x16x32_bf16 v[112:115], v[64:67], v[194:197], v[112:115]
	v_mfma_f32_16x16x32_bf16 v[108:111], v[72:75], v[194:197], v[108:111]
	v_mfma_f32_16x16x32_bf16 v[96:99], v[64:67], v[202:205], v[96:99]
	v_mfma_f32_16x16x32_bf16 v[92:95], v[72:75], v[202:205], v[92:95]
	v_mfma_f32_16x16x32_bf16 v[148:151], v[68:71], v[164:167], v[148:151]
	v_mfma_f32_16x16x32_bf16 v[144:147], v[76:79], v[164:167], v[144:147]
	v_mfma_f32_16x16x32_bf16 v[132:135], v[68:71], v[172:175], v[132:135]
	v_mfma_f32_16x16x32_bf16 v[128:131], v[76:79], v[172:175], v[128:131]
	v_mfma_f32_16x16x32_bf16 v[112:115], v[68:71], v[198:201], v[112:115]
	v_mfma_f32_16x16x32_bf16 v[108:111], v[76:79], v[198:201], v[108:111]
	v_mfma_f32_16x16x32_bf16 v[96:99], v[68:71], v[206:209], v[96:99]
	v_mfma_f32_16x16x32_bf16 v[92:95], v[76:79], v[206:209], v[92:95]
	v_mfma_f32_16x16x32_bf16 v[140:143], v[80:83], v[160:163], v[140:143]
	v_mfma_f32_16x16x32_bf16 v[136:139], v[152:155], v[160:163], v[136:139]
	v_mfma_f32_16x16x32_bf16 v[124:127], v[80:83], v[168:171], v[124:127]
	v_mfma_f32_16x16x32_bf16 v[120:123], v[152:155], v[168:171], v[120:123]
	v_mfma_f32_16x16x32_bf16 v[104:107], v[80:83], v[194:197], v[104:107]
	v_mfma_f32_16x16x32_bf16 v[100:103], v[152:155], v[194:197], v[100:103]
	v_mfma_f32_16x16x32_bf16 v[88:91], v[80:83], v[202:205], v[88:91]
	v_mfma_f32_16x16x32_bf16 v[84:87], v[152:155], v[202:205], v[84:87]
	v_mfma_f32_16x16x32_bf16 v[140:143], v[116:119], v[164:167], v[140:143]
	v_mfma_f32_16x16x32_bf16 v[136:139], v[156:159], v[164:167], v[136:139]
	v_mfma_f32_16x16x32_bf16 v[124:127], v[116:119], v[172:175], v[124:127]
	v_mfma_f32_16x16x32_bf16 v[120:123], v[156:159], v[172:175], v[120:123]
	v_mfma_f32_16x16x32_bf16 v[104:107], v[116:119], v[198:201], v[104:107]
	v_mfma_f32_16x16x32_bf16 v[100:103], v[156:159], v[198:201], v[100:103]
	v_mfma_f32_16x16x32_bf16 v[88:91], v[116:119], v[206:209], v[88:91]
	v_mfma_f32_16x16x32_bf16 v[84:87], v[156:159], v[206:209], v[84:87]
	s_barrier
	s_add_i32 s89, s89, s24
	v_lshl_add_u64 v[190:191], s[84:85], 0, v[180:181]
	s_mov_b32 m0, s89
	ds_read_b128 v[160:163], v193 offset:16384
	ds_read_b128 v[164:167], v193 offset:17408
	ds_read_b128 v[168:171], v193 offset:18432
	ds_read_b128 v[172:175], v193 offset:19456
	ds_read_b128 v[194:197], v193 offset:20480
	ds_read_b128 v[198:201], v193 offset:21504
	ds_read_b128 v[202:205], v193 offset:22528
	ds_read_b128 v[206:209], v193 offset:23552
	global_load_lds_dwordx4 v[190:191], off
	s_add_i32 m0, s89, 0x2000
	s_add_u32 s90, s84, 0x80000
	v_lshl_add_u64 v[210:211], s[84:85], 0, v[176:177]
	s_addc_u32 s91, s85, 0
	s_add_i32 s67, s67, s24
	global_load_lds_dwordx4 v[210:211], off
	v_lshl_add_u64 v[212:213], s[90:91], 0, v[180:181]
	s_mov_b32 m0, s67
	v_lshl_add_u64 v[214:215], s[86:87], 0, v[178:179]
	global_load_lds_dwordx4 v[212:213], off
	v_lshl_add_u64 v[212:213], s[90:91], 0, v[176:177]
	s_add_i32 m0, s67, 0x2000
	s_nop 0
	global_load_lds_dwordx4 v[212:213], off
	v_lshl_add_u64 v[212:213], s[86:87], 0, v[182:183]
	s_mov_b32 m0, s28
	s_nop 0
	global_load_lds_dwordx4 v[212:213], off
	s_mov_b32 m0, s29
	s_nop 0
	global_load_lds_dwordx4 v[214:215], off
	s_waitcnt vmcnt(8)
	s_waitcnt lgkmcnt(0)
	s_barrier
	s_waitcnt lgkmcnt(0)
	v_mfma_f32_16x16x32_bf16 v[60:63], v[64:67], v[160:163], v[60:63]
	v_mfma_f32_16x16x32_bf16 v[56:59], v[72:75], v[160:163], v[56:59]
	v_mfma_f32_16x16x32_bf16 v[44:47], v[64:67], v[168:171], v[44:47]
	v_mfma_f32_16x16x32_bf16 v[40:43], v[72:75], v[168:171], v[40:43]
	v_mfma_f32_16x16x32_bf16 v[28:31], v[64:67], v[194:197], v[28:31]
	v_mfma_f32_16x16x32_bf16 v[24:27], v[72:75], v[194:197], v[24:27]
	v_mfma_f32_16x16x32_bf16 v[12:15], v[64:67], v[202:205], v[12:15]
	v_mfma_f32_16x16x32_bf16 v[8:11], v[72:75], v[202:205], v[8:11]
	v_mfma_f32_16x16x32_bf16 v[60:63], v[68:71], v[164:167], v[60:63]
	v_mfma_f32_16x16x32_bf16 v[56:59], v[76:79], v[164:167], v[56:59]
	v_mfma_f32_16x16x32_bf16 v[44:47], v[68:71], v[172:175], v[44:47]
	v_mfma_f32_16x16x32_bf16 v[40:43], v[76:79], v[172:175], v[40:43]
	v_mfma_f32_16x16x32_bf16 v[28:31], v[68:71], v[198:201], v[28:31]
	v_mfma_f32_16x16x32_bf16 v[24:27], v[76:79], v[198:201], v[24:27]
	v_mfma_f32_16x16x32_bf16 v[12:15], v[68:71], v[206:209], v[12:15]
	v_mfma_f32_16x16x32_bf16 v[8:11], v[76:79], v[206:209], v[8:11]
	v_mfma_f32_16x16x32_bf16 v[52:55], v[80:83], v[160:163], v[52:55]
	v_mfma_f32_16x16x32_bf16 v[48:51], v[152:155], v[160:163], v[48:51]
	v_mfma_f32_16x16x32_bf16 v[36:39], v[80:83], v[168:171], v[36:39]
	v_mfma_f32_16x16x32_bf16 v[32:35], v[152:155], v[168:171], v[32:35]
	v_mfma_f32_16x16x32_bf16 v[20:23], v[80:83], v[194:197], v[20:23]
	v_mfma_f32_16x16x32_bf16 v[16:19], v[152:155], v[194:197], v[16:19]
	v_mfma_f32_16x16x32_bf16 v[4:7], v[80:83], v[202:205], v[4:7]
	v_mfma_f32_16x16x32_bf16 v[0:3], v[152:155], v[202:205], v[0:3]
	v_mfma_f32_16x16x32_bf16 v[52:55], v[116:119], v[164:167], v[52:55]
	v_mfma_f32_16x16x32_bf16 v[48:51], v[156:159], v[164:167], v[48:51]
	v_mfma_f32_16x16x32_bf16 v[36:39], v[116:119], v[172:175], v[36:39]
	v_mfma_f32_16x16x32_bf16 v[32:35], v[156:159], v[172:175], v[32:35]
	v_mfma_f32_16x16x32_bf16 v[20:23], v[116:119], v[198:201], v[20:23]
	v_mfma_f32_16x16x32_bf16 v[16:19], v[156:159], v[198:201], v[16:19]
	v_mfma_f32_16x16x32_bf16 v[4:7], v[116:119], v[206:209], v[4:7]
	v_mfma_f32_16x16x32_bf16 v[0:3], v[156:159], v[206:209], v[0:3]
	s_barrier
	s_add_i32 s67, 0, 0x18000
	s_add_i32 s89, 0, 0x1c000
	v_add_u32_e32 v76, s67, v192
	v_add_u32_e32 v156, s89, v192
	ds_read_b128 v[64:67], v76
	ds_read_b128 v[68:71], v76 offset:1024
	ds_read_b128 v[72:75], v76 offset:2048
	ds_read_b128 v[76:79], v76 offset:3072
	ds_read_b128 v[80:83], v156
	ds_read_b128 v[116:119], v156 offset:1024
	ds_read_b128 v[152:155], v156 offset:2048
	ds_read_b128 v[156:159], v156 offset:3072
	s_add_u32 s86, s86, 0x80000
	s_addc_u32 s87, s87, 0
	s_mov_b32 m0, s34
	v_lshl_add_u64 v[218:219], s[86:87], 0, v[182:183]
	ds_read_b128 v[160:163], v193 offset:32768
	ds_read_b128 v[164:167], v193 offset:33792
	ds_read_b128 v[168:171], v193 offset:34816
	ds_read_b128 v[172:175], v193 offset:35840
	ds_read_b128 v[194:197], v193 offset:36864
	ds_read_b128 v[198:201], v193 offset:37888
	ds_read_b128 v[202:205], v193 offset:38912
	ds_read_b128 v[206:209], v193 offset:39936
	global_load_lds_dwordx4 v[218:219], off
	v_lshl_add_u64 v[218:219], s[86:87], 0, v[178:179]
	s_mov_b32 m0, s35
	s_nop 0
	global_load_lds_dwordx4 v[218:219], off
	s_waitcnt vmcnt(8)
	s_waitcnt lgkmcnt(0)
	s_barrier
	s_waitcnt lgkmcnt(0)
	v_mfma_f32_16x16x32_bf16 v[148:151], v[64:67], v[160:163], v[148:151]
	v_mfma_f32_16x16x32_bf16 v[144:147], v[72:75], v[160:163], v[144:147]
	v_mfma_f32_16x16x32_bf16 v[132:135], v[64:67], v[168:171], v[132:135]
	v_mfma_f32_16x16x32_bf16 v[128:131], v[72:75], v[168:171], v[128:131]
	v_mfma_f32_16x16x32_bf16 v[112:115], v[64:67], v[194:197], v[112:115]
	v_mfma_f32_16x16x32_bf16 v[108:111], v[72:75], v[194:197], v[108:111]
	v_mfma_f32_16x16x32_bf16 v[96:99], v[64:67], v[202:205], v[96:99]
	v_mfma_f32_16x16x32_bf16 v[92:95], v[72:75], v[202:205], v[92:95]
	v_mfma_f32_16x16x32_bf16 v[148:151], v[68:71], v[164:167], v[148:151]
	v_mfma_f32_16x16x32_bf16 v[144:147], v[76:79], v[164:167], v[144:147]
	v_mfma_f32_16x16x32_bf16 v[132:135], v[68:71], v[172:175], v[132:135]
	v_mfma_f32_16x16x32_bf16 v[128:131], v[76:79], v[172:175], v[128:131]
	v_mfma_f32_16x16x32_bf16 v[112:115], v[68:71], v[198:201], v[112:115]
	v_mfma_f32_16x16x32_bf16 v[108:111], v[76:79], v[198:201], v[108:111]
	v_mfma_f32_16x16x32_bf16 v[96:99], v[68:71], v[206:209], v[96:99]
	v_mfma_f32_16x16x32_bf16 v[92:95], v[76:79], v[206:209], v[92:95]
	v_mfma_f32_16x16x32_bf16 v[140:143], v[80:83], v[160:163], v[140:143]
	v_mfma_f32_16x16x32_bf16 v[136:139], v[152:155], v[160:163], v[136:139]
	v_mfma_f32_16x16x32_bf16 v[124:127], v[80:83], v[168:171], v[124:127]
	v_mfma_f32_16x16x32_bf16 v[120:123], v[152:155], v[168:171], v[120:123]
	v_mfma_f32_16x16x32_bf16 v[104:107], v[80:83], v[194:197], v[104:107]
	v_mfma_f32_16x16x32_bf16 v[100:103], v[152:155], v[194:197], v[100:103]
	v_mfma_f32_16x16x32_bf16 v[88:91], v[80:83], v[202:205], v[88:91]
	v_mfma_f32_16x16x32_bf16 v[84:87], v[152:155], v[202:205], v[84:87]
	v_mfma_f32_16x16x32_bf16 v[140:143], v[116:119], v[164:167], v[140:143]
	v_mfma_f32_16x16x32_bf16 v[136:139], v[156:159], v[164:167], v[136:139]
	v_mfma_f32_16x16x32_bf16 v[124:127], v[116:119], v[172:175], v[124:127]
	v_mfma_f32_16x16x32_bf16 v[120:123], v[156:159], v[172:175], v[120:123]
	v_mfma_f32_16x16x32_bf16 v[104:107], v[116:119], v[198:201], v[104:107]
	v_mfma_f32_16x16x32_bf16 v[100:103], v[156:159], v[198:201], v[100:103]
	v_mfma_f32_16x16x32_bf16 v[88:91], v[116:119], v[206:209], v[88:91]
	v_mfma_f32_16x16x32_bf16 v[84:87], v[156:159], v[206:209], v[84:87]
	s_barrier
	s_add_i32 s67, s67, s24
	v_lshl_add_u64 v[190:191], v[190:191], 0, s[30:31]
	s_mov_b32 m0, s67
	ds_read_b128 v[160:163], v193 offset:49152
	ds_read_b128 v[164:167], v193 offset:50176
	ds_read_b128 v[168:171], v193 offset:51200
	ds_read_b128 v[172:175], v193 offset:52224
	ds_read_b128 v[194:197], v193 offset:53248
	ds_read_b128 v[198:201], v193 offset:54272
	ds_read_b128 v[202:205], v193 offset:55296
	ds_read_b128 v[206:209], v193 offset:56320
	global_load_lds_dwordx4 v[190:191], off
	s_add_i32 m0, s67, 0x2000
	s_add_u32 s84, s84, 0x80080
	v_lshl_add_u64 v[190:191], v[210:211], 0, s[30:31]
	s_addc_u32 s85, s85, 0
	s_add_i32 s67, s89, s24
	global_load_lds_dwordx4 v[190:191], off
	v_lshl_add_u64 v[190:191], s[84:85], 0, v[180:181]
	s_mov_b32 m0, s67
	s_nop 0
	global_load_lds_dwordx4 v[190:191], off
	v_lshl_add_u64 v[190:191], s[84:85], 0, v[176:177]
	s_add_i32 m0, s67, 0x2000
	s_nop 0
	global_load_lds_dwordx4 v[190:191], off
	v_lshl_add_u64 v[190:191], v[212:213], 0, s[30:31]
	s_mov_b32 m0, s53
	s_nop 0
	global_load_lds_dwordx4 v[190:191], off
	v_lshl_add_u64 v[190:191], v[214:215], 0, s[30:31]
	s_mov_b32 m0, s54
	s_nop 0
	global_load_lds_dwordx4 v[190:191], off
	s_waitcnt vmcnt(8)
	s_waitcnt lgkmcnt(0)
	s_barrier
	s_waitcnt lgkmcnt(0)
	v_mfma_f32_16x16x32_bf16 v[60:63], v[64:67], v[160:163], v[60:63]
	v_mfma_f32_16x16x32_bf16 v[56:59], v[72:75], v[160:163], v[56:59]
	v_mfma_f32_16x16x32_bf16 v[44:47], v[64:67], v[168:171], v[44:47]
	v_mfma_f32_16x16x32_bf16 v[40:43], v[72:75], v[168:171], v[40:43]
	v_mfma_f32_16x16x32_bf16 v[28:31], v[64:67], v[194:197], v[28:31]
	v_mfma_f32_16x16x32_bf16 v[24:27], v[72:75], v[194:197], v[24:27]
	v_mfma_f32_16x16x32_bf16 v[12:15], v[64:67], v[202:205], v[12:15]
	v_mfma_f32_16x16x32_bf16 v[8:11], v[72:75], v[202:205], v[8:11]
	v_mfma_f32_16x16x32_bf16 v[60:63], v[68:71], v[164:167], v[60:63]
	v_mfma_f32_16x16x32_bf16 v[56:59], v[76:79], v[164:167], v[56:59]
	v_mfma_f32_16x16x32_bf16 v[44:47], v[68:71], v[172:175], v[44:47]
	v_mfma_f32_16x16x32_bf16 v[40:43], v[76:79], v[172:175], v[40:43]
	v_mfma_f32_16x16x32_bf16 v[28:31], v[68:71], v[198:201], v[28:31]
	v_mfma_f32_16x16x32_bf16 v[24:27], v[76:79], v[198:201], v[24:27]
	v_mfma_f32_16x16x32_bf16 v[12:15], v[68:71], v[206:209], v[12:15]
	v_mfma_f32_16x16x32_bf16 v[8:11], v[76:79], v[206:209], v[8:11]
	v_mfma_f32_16x16x32_bf16 v[52:55], v[80:83], v[160:163], v[52:55]
	v_mfma_f32_16x16x32_bf16 v[48:51], v[152:155], v[160:163], v[48:51]
	v_mfma_f32_16x16x32_bf16 v[36:39], v[80:83], v[168:171], v[36:39]
	v_mfma_f32_16x16x32_bf16 v[32:35], v[152:155], v[168:171], v[32:35]
	v_mfma_f32_16x16x32_bf16 v[20:23], v[80:83], v[194:197], v[20:23]
	v_mfma_f32_16x16x32_bf16 v[16:19], v[152:155], v[194:197], v[16:19]
	v_mfma_f32_16x16x32_bf16 v[4:7], v[80:83], v[202:205], v[4:7]
	v_mfma_f32_16x16x32_bf16 v[0:3], v[152:155], v[202:205], v[0:3]
	v_mfma_f32_16x16x32_bf16 v[52:55], v[116:119], v[164:167], v[52:55]
	v_mfma_f32_16x16x32_bf16 v[48:51], v[156:159], v[164:167], v[48:51]
	v_mfma_f32_16x16x32_bf16 v[36:39], v[116:119], v[172:175], v[36:39]
	v_mfma_f32_16x16x32_bf16 v[32:35], v[156:159], v[172:175], v[32:35]
	v_mfma_f32_16x16x32_bf16 v[20:23], v[116:119], v[198:201], v[20:23]
	v_mfma_f32_16x16x32_bf16 v[16:19], v[156:159], v[198:201], v[16:19]
	v_mfma_f32_16x16x32_bf16 v[4:7], v[116:119], v[206:209], v[4:7]
	v_mfma_f32_16x16x32_bf16 v[0:3], v[156:159], v[206:209], v[0:3]
	s_barrier
	s_add_i32 s88, s88, 2
	s_add_u32 s82, s82, 0x100
	s_addc_u32 s83, s83, 0
	s_add_u32 s75, s75, 0x100
	s_addc_u32 s81, s81, 0
	s_cmp_gt_u32 s88, 29
	s_cbranch_scc0 .LBB0_1190
	s_and_b64 vcc, exec, s[18:19]
	s_cbranch_vccz .LBB0_1193
	s_barrier

.LBB0_1289:
	s_lshl_b32 s80, s96, 8
	s_ashr_i32 s81, s80, 31
	s_lshl_b64 s[86:87], s[80:81], 2
	s_add_u32 s84, s84, s86
	s_addc_u32 s85, s85, s87
	s_add_i32 m0, s94, s41
	s_add_u32 s81, s82, 0x100
	global_load_lds_dwordx4 v239, s[84:85]
	s_addc_u32 s96, s83, 0
	s_mov_b32 vcc_lo, -2
	s_add_u32 s82, s78, 0x100
	s_addc_u32 s83, s79, 0
	s_add_i32 s94, 0, 0x10000
	s_cmpk_eq_i32 vcc_lo, 0x54
	s_cselect_b32 s87, s75, s83
	s_cselect_b32 s86, s74, s82
	s_cselect_b32 s85, s77, s96
	s_cselect_b32 s84, s76, s81
	s_add_i32 vcc_hi, 0, 0x14000
	v_add_u32_e32 v96, s94, v238
	v_add_u32_e32 v140, vcc_hi, v238
	ds_read_b128 v[64:67], v96
	ds_read_b128 v[72:75], v96 offset:1024
	ds_read_b128 v[88:91], v96 offset:2048
	ds_read_b128 v[96:99], v96 offset:3072
	ds_read_b128 v[108:111], v140
	ds_read_b128 v[116:119], v140 offset:1024
	ds_read_b128 v[128:131], v140 offset:2048
	ds_read_b128 v[140:143], v140 offset:3072
	v_lshl_add_u64 v[192:193], s[78:79], 0, v[230:231]
	s_add_i32 m0, s29, 0xc000
	ds_read_b128 v[152:155], v240
	ds_read_b128 v[156:159], v240 offset:1024
	ds_read_b128 v[160:163], v240 offset:2048
	ds_read_b128 v[164:167], v240 offset:3072
	ds_read_b128 v[168:171], v240 offset:4096
	ds_read_b128 v[180:183], v240 offset:5120
	ds_read_b128 v[184:187], v240 offset:6144
	ds_read_b128 v[188:191], v240 offset:7168
	global_load_lds_dwordx4 v[192:193], off
	v_lshl_add_u64 v[192:193], s[78:79], 0, v[232:233]
	s_add_i32 m0, s29, 0xe000
	s_nop 0
	global_load_lds_dwordx4 v[192:193], off
	s_waitcnt vmcnt(8)
	s_waitcnt lgkmcnt(0)
	s_barrier
	s_waitcnt lgkmcnt(0)
	v_mfma_f32_16x16x32_bf16 v[176:179], v[64:67], v[152:155], 0
	v_mfma_f32_16x16x32_bf16 v[172:175], v[88:91], v[152:155], 0
	v_mfma_f32_16x16x32_bf16 v[136:139], v[64:67], v[160:163], 0
	v_mfma_f32_16x16x32_bf16 v[132:135], v[88:91], v[160:163], 0
	v_mfma_f32_16x16x32_bf16 v[112:115], v[64:67], v[168:171], 0
	v_mfma_f32_16x16x32_bf16 v[104:107], v[88:91], v[168:171], 0
	v_mfma_f32_16x16x32_bf16 v[84:87], v[64:67], v[184:187], 0
	v_mfma_f32_16x16x32_bf16 v[80:83], v[88:91], v[184:187], 0
	v_mfma_f32_16x16x32_bf16 v[176:179], v[72:75], v[156:159], v[176:179]
	v_mfma_f32_16x16x32_bf16 v[172:175], v[96:99], v[156:159], v[172:175]
	v_mfma_f32_16x16x32_bf16 v[136:139], v[72:75], v[164:167], v[136:139]
	v_mfma_f32_16x16x32_bf16 v[132:135], v[96:99], v[164:167], v[132:135]
	v_mfma_f32_16x16x32_bf16 v[112:115], v[72:75], v[180:183], v[112:115]
	v_mfma_f32_16x16x32_bf16 v[104:107], v[96:99], v[180:183], v[104:107]
	v_mfma_f32_16x16x32_bf16 v[84:87], v[72:75], v[188:191], v[84:87]
	v_mfma_f32_16x16x32_bf16 v[80:83], v[96:99], v[188:191], v[80:83]
	v_mfma_f32_16x16x32_bf16 v[148:151], v[108:111], v[152:155], 0
	v_mfma_f32_16x16x32_bf16 v[144:147], v[128:131], v[152:155], 0
	v_mfma_f32_16x16x32_bf16 v[124:127], v[108:111], v[160:163], 0
	v_mfma_f32_16x16x32_bf16 v[120:123], v[128:131], v[160:163], 0
	v_mfma_f32_16x16x32_bf16 v[100:103], v[108:111], v[168:171], 0
	v_mfma_f32_16x16x32_bf16 v[92:95], v[128:131], v[168:171], 0
	v_mfma_f32_16x16x32_bf16 v[76:79], v[108:111], v[184:187], 0
	v_mfma_f32_16x16x32_bf16 v[68:71], v[128:131], v[184:187], 0
	v_mfma_f32_16x16x32_bf16 v[148:151], v[116:119], v[156:159], v[148:151]
	v_mfma_f32_16x16x32_bf16 v[144:147], v[140:143], v[156:159], v[144:147]
	v_mfma_f32_16x16x32_bf16 v[124:127], v[116:119], v[164:167], v[124:127]
	v_mfma_f32_16x16x32_bf16 v[120:123], v[140:143], v[164:167], v[120:123]
	v_mfma_f32_16x16x32_bf16 v[100:103], v[116:119], v[180:183], v[100:103]
	v_mfma_f32_16x16x32_bf16 v[92:95], v[140:143], v[180:183], v[92:95]
	v_mfma_f32_16x16x32_bf16 v[76:79], v[116:119], v[188:191], v[76:79]
	v_mfma_f32_16x16x32_bf16 v[68:71], v[140:143], v[188:191], v[68:71]
	s_barrier
	s_add_i32 s78, s94, s2
	v_lshl_add_u64 v[192:193], s[84:85], 0, v[216:217]
	s_mov_b32 m0, s78
	ds_read_b128 v[152:155], v240 offset:16384
	ds_read_b128 v[156:159], v240 offset:17408
	ds_read_b128 v[160:163], v240 offset:18432
	ds_read_b128 v[164:167], v240 offset:19456
	ds_read_b128 v[168:171], v240 offset:20480
	ds_read_b128 v[180:183], v240 offset:21504
	ds_read_b128 v[184:187], v240 offset:22528
	ds_read_b128 v[188:191], v240 offset:23552
	global_load_lds_dwordx4 v[192:193], off
	s_add_i32 m0, s78, 0x2000
	s_add_u32 s78, s84, 0x160000
	v_lshl_add_u64 v[194:195], s[84:85], 0, v[228:229]
	s_addc_u32 s79, s85, 0
	s_add_i32 s94, vcc_hi, s2
	global_load_lds_dwordx4 v[194:195], off
	v_lshl_add_u64 v[196:197], s[78:79], 0, v[216:217]
	s_mov_b32 m0, s94
	v_lshl_add_u64 v[198:199], s[86:87], 0, v[226:227]
	global_load_lds_dwordx4 v[196:197], off
	v_lshl_add_u64 v[196:197], s[78:79], 0, v[228:229]
	s_add_i32 m0, s94, 0x2000
	s_nop 0
	global_load_lds_dwordx4 v[196:197], off
	v_lshl_add_u64 v[196:197], s[86:87], 0, v[224:225]
	s_mov_b32 m0, s29
	s_nop 0
	global_load_lds_dwordx4 v[196:197], off
	s_mov_b32 m0, s34
	s_nop 0
	global_load_lds_dwordx4 v[198:199], off
	s_waitcnt vmcnt(8)
	s_waitcnt lgkmcnt(0)
	s_barrier
	s_waitcnt lgkmcnt(0)
	v_mfma_f32_16x16x32_bf16 v[60:63], v[64:67], v[152:155], 0
	v_mfma_f32_16x16x32_bf16 v[56:59], v[88:91], v[152:155], 0
	v_mfma_f32_16x16x32_bf16 v[44:47], v[64:67], v[160:163], 0
	v_mfma_f32_16x16x32_bf16 v[40:43], v[88:91], v[160:163], 0
	v_mfma_f32_16x16x32_bf16 v[28:31], v[64:67], v[168:171], 0
	v_mfma_f32_16x16x32_bf16 v[24:27], v[88:91], v[168:171], 0
	v_mfma_f32_16x16x32_bf16 v[12:15], v[64:67], v[184:187], 0
	v_mfma_f32_16x16x32_bf16 v[8:11], v[88:91], v[184:187], 0
	v_mfma_f32_16x16x32_bf16 v[60:63], v[72:75], v[156:159], v[60:63]
	v_mfma_f32_16x16x32_bf16 v[56:59], v[96:99], v[156:159], v[56:59]
	v_mfma_f32_16x16x32_bf16 v[44:47], v[72:75], v[164:167], v[44:47]
	v_mfma_f32_16x16x32_bf16 v[40:43], v[96:99], v[164:167], v[40:43]
	v_mfma_f32_16x16x32_bf16 v[28:31], v[72:75], v[180:183], v[28:31]
	v_mfma_f32_16x16x32_bf16 v[24:27], v[96:99], v[180:183], v[24:27]
	v_mfma_f32_16x16x32_bf16 v[12:15], v[72:75], v[188:191], v[12:15]
	v_mfma_f32_16x16x32_bf16 v[8:11], v[96:99], v[188:191], v[8:11]
	v_mfma_f32_16x16x32_bf16 v[52:55], v[108:111], v[152:155], 0
	v_mfma_f32_16x16x32_bf16 v[48:51], v[128:131], v[152:155], 0
	v_mfma_f32_16x16x32_bf16 v[36:39], v[108:111], v[160:163], 0
	v_mfma_f32_16x16x32_bf16 v[32:35], v[128:131], v[160:163], 0
	v_mfma_f32_16x16x32_bf16 v[20:23], v[108:111], v[168:171], 0
	v_mfma_f32_16x16x32_bf16 v[16:19], v[128:131], v[168:171], 0
	v_mfma_f32_16x16x32_bf16 v[4:7], v[108:111], v[184:187], 0
	v_mfma_f32_16x16x32_bf16 v[0:3], v[128:131], v[184:187], 0
	v_mfma_f32_16x16x32_bf16 v[52:55], v[116:119], v[156:159], v[52:55]
	v_mfma_f32_16x16x32_bf16 v[48:51], v[140:143], v[156:159], v[48:51]
	v_mfma_f32_16x16x32_bf16 v[36:39], v[116:119], v[164:167], v[36:39]
	v_mfma_f32_16x16x32_bf16 v[32:35], v[140:143], v[164:167], v[32:35]
	v_mfma_f32_16x16x32_bf16 v[20:23], v[116:119], v[180:183], v[20:23]
	v_mfma_f32_16x16x32_bf16 v[16:19], v[140:143], v[180:183], v[16:19]
	v_mfma_f32_16x16x32_bf16 v[4:7], v[116:119], v[188:191], v[4:7]
	v_mfma_f32_16x16x32_bf16 v[0:3], v[140:143], v[188:191], v[0:3]
	s_barrier
	s_add_i32 s94, 0, 0x18000
	s_add_i32 vcc_hi, 0, 0x1c000
	v_add_u32_e32 v96, s94, v238
	v_add_u32_e32 v140, vcc_hi, v238
	ds_read_b128 v[64:67], v96
	ds_read_b128 v[72:75], v96 offset:1024
	ds_read_b128 v[88:91], v96 offset:2048
	ds_read_b128 v[96:99], v96 offset:3072
	ds_read_b128 v[108:111], v140
	ds_read_b128 v[116:119], v140 offset:1024
	ds_read_b128 v[128:131], v140 offset:2048
	ds_read_b128 v[140:143], v140 offset:3072
	s_add_u32 s78, s86, 0x160000
	s_addc_u32 s79, s87, 0
	s_mov_b32 m0, s35
	v_lshl_add_u64 v[200:201], s[78:79], 0, v[224:225]
	ds_read_b128 v[152:155], v240 offset:32768
	ds_read_b128 v[156:159], v240 offset:33792
	ds_read_b128 v[160:163], v240 offset:34816
	ds_read_b128 v[164:167], v240 offset:35840
	ds_read_b128 v[168:171], v240 offset:36864
	ds_read_b128 v[180:183], v240 offset:37888
	ds_read_b128 v[184:187], v240 offset:38912
	ds_read_b128 v[188:191], v240 offset:39936
	global_load_lds_dwordx4 v[200:201], off
	v_lshl_add_u64 v[200:201], s[78:79], 0, v[226:227]
	s_mov_b32 m0, s38
	s_nop 0
	global_load_lds_dwordx4 v[200:201], off
	s_waitcnt vmcnt(8)
	s_waitcnt lgkmcnt(0)
	s_barrier
	s_waitcnt lgkmcnt(0)
	v_mfma_f32_16x16x32_bf16 v[176:179], v[64:67], v[152:155], v[176:179]
	v_mfma_f32_16x16x32_bf16 v[172:175], v[88:91], v[152:155], v[172:175]
	v_mfma_f32_16x16x32_bf16 v[136:139], v[64:67], v[160:163], v[136:139]
	v_mfma_f32_16x16x32_bf16 v[132:135], v[88:91], v[160:163], v[132:135]
	v_mfma_f32_16x16x32_bf16 v[112:115], v[64:67], v[168:171], v[112:115]
	v_mfma_f32_16x16x32_bf16 v[104:107], v[88:91], v[168:171], v[104:107]
	v_mfma_f32_16x16x32_bf16 v[84:87], v[64:67], v[184:187], v[84:87]
	v_mfma_f32_16x16x32_bf16 v[80:83], v[88:91], v[184:187], v[80:83]
	v_mfma_f32_16x16x32_bf16 v[176:179], v[72:75], v[156:159], v[176:179]
	v_mfma_f32_16x16x32_bf16 v[172:175], v[96:99], v[156:159], v[172:175]
	v_mfma_f32_16x16x32_bf16 v[136:139], v[72:75], v[164:167], v[136:139]
	v_mfma_f32_16x16x32_bf16 v[132:135], v[96:99], v[164:167], v[132:135]
	v_mfma_f32_16x16x32_bf16 v[112:115], v[72:75], v[180:183], v[112:115]
	v_mfma_f32_16x16x32_bf16 v[104:107], v[96:99], v[180:183], v[104:107]
	v_mfma_f32_16x16x32_bf16 v[84:87], v[72:75], v[188:191], v[84:87]
	v_mfma_f32_16x16x32_bf16 v[80:83], v[96:99], v[188:191], v[80:83]
	v_mfma_f32_16x16x32_bf16 v[148:151], v[108:111], v[152:155], v[148:151]
	v_mfma_f32_16x16x32_bf16 v[144:147], v[128:131], v[152:155], v[144:147]
	v_mfma_f32_16x16x32_bf16 v[124:127], v[108:111], v[160:163], v[124:127]
	v_mfma_f32_16x16x32_bf16 v[120:123], v[128:131], v[160:163], v[120:123]
	v_mfma_f32_16x16x32_bf16 v[100:103], v[108:111], v[168:171], v[100:103]
	v_mfma_f32_16x16x32_bf16 v[92:95], v[128:131], v[168:171], v[92:95]
	v_mfma_f32_16x16x32_bf16 v[76:79], v[108:111], v[184:187], v[76:79]
	v_mfma_f32_16x16x32_bf16 v[68:71], v[128:131], v[184:187], v[68:71]
	v_mfma_f32_16x16x32_bf16 v[148:151], v[116:119], v[156:159], v[148:151]
	v_mfma_f32_16x16x32_bf16 v[144:147], v[140:143], v[156:159], v[144:147]
	v_mfma_f32_16x16x32_bf16 v[124:127], v[116:119], v[164:167], v[124:127]
	v_mfma_f32_16x16x32_bf16 v[120:123], v[140:143], v[164:167], v[120:123]
	v_mfma_f32_16x16x32_bf16 v[100:103], v[116:119], v[180:183], v[100:103]
	v_mfma_f32_16x16x32_bf16 v[92:95], v[140:143], v[180:183], v[92:95]
	v_mfma_f32_16x16x32_bf16 v[76:79], v[116:119], v[188:191], v[76:79]
	v_mfma_f32_16x16x32_bf16 v[68:71], v[140:143], v[188:191], v[68:71]
	s_barrier
	s_add_i32 s78, s94, s2
	v_lshl_add_u64 v[192:193], v[192:193], 0, s[30:31]
	s_mov_b32 m0, s78
	ds_read_b128 v[152:155], v240 offset:49152
	ds_read_b128 v[156:159], v240 offset:50176
	ds_read_b128 v[160:163], v240 offset:51200
	ds_read_b128 v[164:167], v240 offset:52224
	ds_read_b128 v[168:171], v240 offset:53248
	ds_read_b128 v[180:183], v240 offset:54272
	ds_read_b128 v[184:187], v240 offset:55296
	ds_read_b128 v[188:191], v240 offset:56320
	global_load_lds_dwordx4 v[192:193], off
	s_add_i32 m0, s78, 0x2000
	s_add_u32 s78, s84, 0x160080
	v_lshl_add_u64 v[192:193], v[194:195], 0, s[30:31]
	s_addc_u32 s79, s85, 0
	s_add_i32 s84, vcc_hi, s2
	global_load_lds_dwordx4 v[192:193], off
	v_lshl_add_u64 v[192:193], s[78:79], 0, v[216:217]
	s_mov_b32 m0, s84
	s_nop 0
	global_load_lds_dwordx4 v[192:193], off
	v_lshl_add_u64 v[192:193], s[78:79], 0, v[228:229]
	s_add_i32 m0, s84, 0x2000
	s_nop 0
	global_load_lds_dwordx4 v[192:193], off
	v_lshl_add_u64 v[192:193], v[196:197], 0, s[30:31]
	s_mov_b32 m0, s60
	s_nop 0
	global_load_lds_dwordx4 v[192:193], off
	v_lshl_add_u64 v[192:193], v[198:199], 0, s[30:31]
	s_mov_b32 m0, s61
	s_nop 0
	global_load_lds_dwordx4 v[192:193], off
	s_waitcnt vmcnt(8)
	s_waitcnt lgkmcnt(0)
	s_barrier
	s_waitcnt lgkmcnt(0)
	v_mfma_f32_16x16x32_bf16 v[60:63], v[64:67], v[152:155], v[60:63]
	v_mfma_f32_16x16x32_bf16 v[56:59], v[88:91], v[152:155], v[56:59]
	v_mfma_f32_16x16x32_bf16 v[44:47], v[64:67], v[160:163], v[44:47]
	v_mfma_f32_16x16x32_bf16 v[40:43], v[88:91], v[160:163], v[40:43]
	v_mfma_f32_16x16x32_bf16 v[28:31], v[64:67], v[168:171], v[28:31]
	v_mfma_f32_16x16x32_bf16 v[24:27], v[88:91], v[168:171], v[24:27]
	v_mfma_f32_16x16x32_bf16 v[12:15], v[64:67], v[184:187], v[12:15]
	v_mfma_f32_16x16x32_bf16 v[8:11], v[88:91], v[184:187], v[8:11]
	v_mfma_f32_16x16x32_bf16 v[60:63], v[72:75], v[156:159], v[60:63]
	v_mfma_f32_16x16x32_bf16 v[56:59], v[96:99], v[156:159], v[56:59]
	v_mfma_f32_16x16x32_bf16 v[44:47], v[72:75], v[164:167], v[44:47]
	v_mfma_f32_16x16x32_bf16 v[40:43], v[96:99], v[164:167], v[40:43]
	v_mfma_f32_16x16x32_bf16 v[28:31], v[72:75], v[180:183], v[28:31]
	v_mfma_f32_16x16x32_bf16 v[24:27], v[96:99], v[180:183], v[24:27]
	v_mfma_f32_16x16x32_bf16 v[12:15], v[72:75], v[188:191], v[12:15]
	v_mfma_f32_16x16x32_bf16 v[8:11], v[96:99], v[188:191], v[8:11]
	v_mfma_f32_16x16x32_bf16 v[52:55], v[108:111], v[152:155], v[52:55]
	v_mfma_f32_16x16x32_bf16 v[48:51], v[128:131], v[152:155], v[48:51]
	v_mfma_f32_16x16x32_bf16 v[36:39], v[108:111], v[160:163], v[36:39]
	v_mfma_f32_16x16x32_bf16 v[32:35], v[128:131], v[160:163], v[32:35]
	v_mfma_f32_16x16x32_bf16 v[20:23], v[108:111], v[168:171], v[20:23]
	v_mfma_f32_16x16x32_bf16 v[16:19], v[128:131], v[168:171], v[16:19]
	v_mfma_f32_16x16x32_bf16 v[4:7], v[108:111], v[184:187], v[4:7]
	v_mfma_f32_16x16x32_bf16 v[0:3], v[128:131], v[184:187], v[0:3]
	v_mfma_f32_16x16x32_bf16 v[52:55], v[116:119], v[156:159], v[52:55]
	v_mfma_f32_16x16x32_bf16 v[48:51], v[140:143], v[156:159], v[48:51]
	v_mfma_f32_16x16x32_bf16 v[36:39], v[116:119], v[164:167], v[36:39]
	v_mfma_f32_16x16x32_bf16 v[32:35], v[140:143], v[164:167], v[32:35]
	v_mfma_f32_16x16x32_bf16 v[20:23], v[116:119], v[180:183], v[20:23]
	v_mfma_f32_16x16x32_bf16 v[16:19], v[140:143], v[180:183], v[16:19]
	v_mfma_f32_16x16x32_bf16 v[4:7], v[116:119], v[188:191], v[4:7]
	v_mfma_f32_16x16x32_bf16 v[0:3], v[140:143], v[188:191], v[0:3]
	s_barrier
	s_add_i32 vcc_lo, vcc_lo, 2
	s_add_u32 s81, s81, 0x100
	s_addc_u32 s96, s96, 0
	s_mov_b64 s[78:79], s[82:83]
.LBB0_1290:
	s_add_u32 s82, s78, 0x100
	s_addc_u32 s83, s79, 0
	s_add_i32 s94, 0, 0x10000
	s_cmpk_eq_i32 vcc_lo, 0x54
	s_cselect_b32 s87, s75, s83
	s_cselect_b32 s86, s74, s82
	s_cselect_b32 s85, s77, s96
	s_cselect_b32 s84, s76, s81
	s_add_i32 vcc_hi, 0, 0x14000
	v_add_u32_e32 v96, s94, v238
	v_add_u32_e32 v140, vcc_hi, v238
	ds_read_b128 v[64:67], v96
	ds_read_b128 v[72:75], v96 offset:1024
	ds_read_b128 v[88:91], v96 offset:2048
	ds_read_b128 v[96:99], v96 offset:3072
	ds_read_b128 v[108:111], v140
	ds_read_b128 v[116:119], v140 offset:1024
	ds_read_b128 v[128:131], v140 offset:2048
	ds_read_b128 v[140:143], v140 offset:3072
	v_lshl_add_u64 v[192:193], s[78:79], 0, v[230:231]
	s_add_i32 m0, s29, 0xc000
	ds_read_b128 v[152:155], v240
	ds_read_b128 v[156:159], v240 offset:1024
	ds_read_b128 v[160:163], v240 offset:2048
	ds_read_b128 v[164:167], v240 offset:3072
	ds_read_b128 v[168:171], v240 offset:4096
	ds_read_b128 v[180:183], v240 offset:5120
	ds_read_b128 v[184:187], v240 offset:6144
	ds_read_b128 v[188:191], v240 offset:7168
	global_load_lds_dwordx4 v[192:193], off
	v_lshl_add_u64 v[192:193], s[78:79], 0, v[232:233]
	s_add_i32 m0, s29, 0xe000
	s_nop 0
	global_load_lds_dwordx4 v[192:193], off
	s_waitcnt vmcnt(8)
	s_waitcnt lgkmcnt(0)
	s_barrier
	s_waitcnt lgkmcnt(0)
	v_mfma_f32_16x16x32_bf16 v[176:179], v[64:67], v[152:155], v[176:179]
	v_mfma_f32_16x16x32_bf16 v[172:175], v[88:91], v[152:155], v[172:175]
	v_mfma_f32_16x16x32_bf16 v[136:139], v[64:67], v[160:163], v[136:139]
	v_mfma_f32_16x16x32_bf16 v[132:135], v[88:91], v[160:163], v[132:135]
	v_mfma_f32_16x16x32_bf16 v[112:115], v[64:67], v[168:171], v[112:115]
	v_mfma_f32_16x16x32_bf16 v[104:107], v[88:91], v[168:171], v[104:107]
	v_mfma_f32_16x16x32_bf16 v[84:87], v[64:67], v[184:187], v[84:87]
	v_mfma_f32_16x16x32_bf16 v[80:83], v[88:91], v[184:187], v[80:83]
	v_mfma_f32_16x16x32_bf16 v[176:179], v[72:75], v[156:159], v[176:179]
	v_mfma_f32_16x16x32_bf16 v[172:175], v[96:99], v[156:159], v[172:175]
	v_mfma_f32_16x16x32_bf16 v[136:139], v[72:75], v[164:167], v[136:139]
	v_mfma_f32_16x16x32_bf16 v[132:135], v[96:99], v[164:167], v[132:135]
	v_mfma_f32_16x16x32_bf16 v[112:115], v[72:75], v[180:183], v[112:115]
	v_mfma_f32_16x16x32_bf16 v[104:107], v[96:99], v[180:183], v[104:107]
	v_mfma_f32_16x16x32_bf16 v[84:87], v[72:75], v[188:191], v[84:87]
	v_mfma_f32_16x16x32_bf16 v[80:83], v[96:99], v[188:191], v[80:83]
	v_mfma_f32_16x16x32_bf16 v[148:151], v[108:111], v[152:155], v[148:151]
	v_mfma_f32_16x16x32_bf16 v[144:147], v[128:131], v[152:155], v[144:147]
	v_mfma_f32_16x16x32_bf16 v[124:127], v[108:111], v[160:163], v[124:127]
	v_mfma_f32_16x16x32_bf16 v[120:123], v[128:131], v[160:163], v[120:123]
	v_mfma_f32_16x16x32_bf16 v[100:103], v[108:111], v[168:171], v[100:103]
	v_mfma_f32_16x16x32_bf16 v[92:95], v[128:131], v[168:171], v[92:95]
	v_mfma_f32_16x16x32_bf16 v[76:79], v[108:111], v[184:187], v[76:79]
	v_mfma_f32_16x16x32_bf16 v[68:71], v[128:131], v[184:187], v[68:71]
	v_mfma_f32_16x16x32_bf16 v[148:151], v[116:119], v[156:159], v[148:151]
	v_mfma_f32_16x16x32_bf16 v[144:147], v[140:143], v[156:159], v[144:147]
	v_mfma_f32_16x16x32_bf16 v[124:127], v[116:119], v[164:167], v[124:127]
	v_mfma_f32_16x16x32_bf16 v[120:123], v[140:143], v[164:167], v[120:123]
	v_mfma_f32_16x16x32_bf16 v[100:103], v[116:119], v[180:183], v[100:103]
	v_mfma_f32_16x16x32_bf16 v[92:95], v[140:143], v[180:183], v[92:95]
	v_mfma_f32_16x16x32_bf16 v[76:79], v[116:119], v[188:191], v[76:79]
	v_mfma_f32_16x16x32_bf16 v[68:71], v[140:143], v[188:191], v[68:71]
	s_barrier
	s_add_i32 s78, s94, s2
	v_lshl_add_u64 v[192:193], s[84:85], 0, v[216:217]
	s_mov_b32 m0, s78
	ds_read_b128 v[152:155], v240 offset:16384
	ds_read_b128 v[156:159], v240 offset:17408
	ds_read_b128 v[160:163], v240 offset:18432
	ds_read_b128 v[164:167], v240 offset:19456
	ds_read_b128 v[168:171], v240 offset:20480
	ds_read_b128 v[180:183], v240 offset:21504
	ds_read_b128 v[184:187], v240 offset:22528
	ds_read_b128 v[188:191], v240 offset:23552
	global_load_lds_dwordx4 v[192:193], off
	s_add_i32 m0, s78, 0x2000
	s_add_u32 s78, s84, 0x160000
	v_lshl_add_u64 v[194:195], s[84:85], 0, v[228:229]
	s_addc_u32 s79, s85, 0
	s_add_i32 s94, vcc_hi, s2
	global_load_lds_dwordx4 v[194:195], off
	v_lshl_add_u64 v[196:197], s[78:79], 0, v[216:217]
	s_mov_b32 m0, s94
	v_lshl_add_u64 v[198:199], s[86:87], 0, v[226:227]
	global_load_lds_dwordx4 v[196:197], off
	v_lshl_add_u64 v[196:197], s[78:79], 0, v[228:229]
	s_add_i32 m0, s94, 0x2000
	s_nop 0
	global_load_lds_dwordx4 v[196:197], off
	v_lshl_add_u64 v[196:197], s[86:87], 0, v[224:225]
	s_mov_b32 m0, s29
	s_nop 0
	global_load_lds_dwordx4 v[196:197], off
	s_mov_b32 m0, s34
	s_nop 0
	global_load_lds_dwordx4 v[198:199], off
	s_waitcnt vmcnt(8)
	s_waitcnt lgkmcnt(0)
	s_barrier
	s_waitcnt lgkmcnt(0)
	v_mfma_f32_16x16x32_bf16 v[60:63], v[64:67], v[152:155], v[60:63]
	v_mfma_f32_16x16x32_bf16 v[56:59], v[88:91], v[152:155], v[56:59]
	v_mfma_f32_16x16x32_bf16 v[44:47], v[64:67], v[160:163], v[44:47]
	v_mfma_f32_16x16x32_bf16 v[40:43], v[88:91], v[160:163], v[40:43]
	v_mfma_f32_16x16x32_bf16 v[28:31], v[64:67], v[168:171], v[28:31]
	v_mfma_f32_16x16x32_bf16 v[24:27], v[88:91], v[168:171], v[24:27]
	v_mfma_f32_16x16x32_bf16 v[12:15], v[64:67], v[184:187], v[12:15]
	v_mfma_f32_16x16x32_bf16 v[8:11], v[88:91], v[184:187], v[8:11]
	v_mfma_f32_16x16x32_bf16 v[60:63], v[72:75], v[156:159], v[60:63]
	v_mfma_f32_16x16x32_bf16 v[56:59], v[96:99], v[156:159], v[56:59]
	v_mfma_f32_16x16x32_bf16 v[44:47], v[72:75], v[164:167], v[44:47]
	v_mfma_f32_16x16x32_bf16 v[40:43], v[96:99], v[164:167], v[40:43]
	v_mfma_f32_16x16x32_bf16 v[28:31], v[72:75], v[180:183], v[28:31]
	v_mfma_f32_16x16x32_bf16 v[24:27], v[96:99], v[180:183], v[24:27]
	v_mfma_f32_16x16x32_bf16 v[12:15], v[72:75], v[188:191], v[12:15]
	v_mfma_f32_16x16x32_bf16 v[8:11], v[96:99], v[188:191], v[8:11]
	v_mfma_f32_16x16x32_bf16 v[52:55], v[108:111], v[152:155], v[52:55]
	v_mfma_f32_16x16x32_bf16 v[48:51], v[128:131], v[152:155], v[48:51]
	v_mfma_f32_16x16x32_bf16 v[36:39], v[108:111], v[160:163], v[36:39]
	v_mfma_f32_16x16x32_bf16 v[32:35], v[128:131], v[160:163], v[32:35]
	v_mfma_f32_16x16x32_bf16 v[20:23], v[108:111], v[168:171], v[20:23]
	v_mfma_f32_16x16x32_bf16 v[16:19], v[128:131], v[168:171], v[16:19]
	v_mfma_f32_16x16x32_bf16 v[4:7], v[108:111], v[184:187], v[4:7]
	v_mfma_f32_16x16x32_bf16 v[0:3], v[128:131], v[184:187], v[0:3]
	v_mfma_f32_16x16x32_bf16 v[52:55], v[116:119], v[156:159], v[52:55]
	v_mfma_f32_16x16x32_bf16 v[48:51], v[140:143], v[156:159], v[48:51]
	v_mfma_f32_16x16x32_bf16 v[36:39], v[116:119], v[164:167], v[36:39]
	v_mfma_f32_16x16x32_bf16 v[32:35], v[140:143], v[164:167], v[32:35]
	v_mfma_f32_16x16x32_bf16 v[20:23], v[116:119], v[180:183], v[20:23]
	v_mfma_f32_16x16x32_bf16 v[16:19], v[140:143], v[180:183], v[16:19]
	v_mfma_f32_16x16x32_bf16 v[4:7], v[116:119], v[188:191], v[4:7]
	v_mfma_f32_16x16x32_bf16 v[0:3], v[140:143], v[188:191], v[0:3]
	s_barrier
	s_add_i32 s94, 0, 0x18000
	s_add_i32 vcc_hi, 0, 0x1c000
	v_add_u32_e32 v96, s94, v238
	v_add_u32_e32 v140, vcc_hi, v238
	ds_read_b128 v[64:67], v96
	ds_read_b128 v[72:75], v96 offset:1024
	ds_read_b128 v[88:91], v96 offset:2048
	ds_read_b128 v[96:99], v96 offset:3072
	ds_read_b128 v[108:111], v140
	ds_read_b128 v[116:119], v140 offset:1024
	ds_read_b128 v[128:131], v140 offset:2048
	ds_read_b128 v[140:143], v140 offset:3072
	s_add_u32 s78, s86, 0x160000
	s_addc_u32 s79, s87, 0
	s_mov_b32 m0, s35
	v_lshl_add_u64 v[200:201], s[78:79], 0, v[224:225]
	ds_read_b128 v[152:155], v240 offset:32768
	ds_read_b128 v[156:159], v240 offset:33792
	ds_read_b128 v[160:163], v240 offset:34816
	ds_read_b128 v[164:167], v240 offset:35840
	ds_read_b128 v[168:171], v240 offset:36864
	ds_read_b128 v[180:183], v240 offset:37888
	ds_read_b128 v[184:187], v240 offset:38912
	ds_read_b128 v[188:191], v240 offset:39936
	global_load_lds_dwordx4 v[200:201], off
	v_lshl_add_u64 v[200:201], s[78:79], 0, v[226:227]
	s_mov_b32 m0, s38
	s_nop 0
	global_load_lds_dwordx4 v[200:201], off
	s_waitcnt vmcnt(8)
	s_waitcnt lgkmcnt(0)
	s_barrier
	s_waitcnt lgkmcnt(0)
	v_mfma_f32_16x16x32_bf16 v[176:179], v[64:67], v[152:155], v[176:179]
	v_mfma_f32_16x16x32_bf16 v[172:175], v[88:91], v[152:155], v[172:175]
	v_mfma_f32_16x16x32_bf16 v[136:139], v[64:67], v[160:163], v[136:139]
	v_mfma_f32_16x16x32_bf16 v[132:135], v[88:91], v[160:163], v[132:135]
	v_mfma_f32_16x16x32_bf16 v[112:115], v[64:67], v[168:171], v[112:115]
	v_mfma_f32_16x16x32_bf16 v[104:107], v[88:91], v[168:171], v[104:107]
	v_mfma_f32_16x16x32_bf16 v[84:87], v[64:67], v[184:187], v[84:87]
	v_mfma_f32_16x16x32_bf16 v[80:83], v[88:91], v[184:187], v[80:83]
	v_mfma_f32_16x16x32_bf16 v[176:179], v[72:75], v[156:159], v[176:179]
	v_mfma_f32_16x16x32_bf16 v[172:175], v[96:99], v[156:159], v[172:175]
	v_mfma_f32_16x16x32_bf16 v[136:139], v[72:75], v[164:167], v[136:139]
	v_mfma_f32_16x16x32_bf16 v[132:135], v[96:99], v[164:167], v[132:135]
	v_mfma_f32_16x16x32_bf16 v[112:115], v[72:75], v[180:183], v[112:115]
	v_mfma_f32_16x16x32_bf16 v[104:107], v[96:99], v[180:183], v[104:107]
	v_mfma_f32_16x16x32_bf16 v[84:87], v[72:75], v[188:191], v[84:87]
	v_mfma_f32_16x16x32_bf16 v[80:83], v[96:99], v[188:191], v[80:83]
	v_mfma_f32_16x16x32_bf16 v[148:151], v[108:111], v[152:155], v[148:151]
	v_mfma_f32_16x16x32_bf16 v[144:147], v[128:131], v[152:155], v[144:147]
	v_mfma_f32_16x16x32_bf16 v[124:127], v[108:111], v[160:163], v[124:127]
	v_mfma_f32_16x16x32_bf16 v[120:123], v[128:131], v[160:163], v[120:123]
	v_mfma_f32_16x16x32_bf16 v[100:103], v[108:111], v[168:171], v[100:103]
	v_mfma_f32_16x16x32_bf16 v[92:95], v[128:131], v[168:171], v[92:95]
	v_mfma_f32_16x16x32_bf16 v[76:79], v[108:111], v[184:187], v[76:79]
	v_mfma_f32_16x16x32_bf16 v[68:71], v[128:131], v[184:187], v[68:71]
	v_mfma_f32_16x16x32_bf16 v[148:151], v[116:119], v[156:159], v[148:151]
	v_mfma_f32_16x16x32_bf16 v[144:147], v[140:143], v[156:159], v[144:147]
	v_mfma_f32_16x16x32_bf16 v[124:127], v[116:119], v[164:167], v[124:127]
	v_mfma_f32_16x16x32_bf16 v[120:123], v[140:143], v[164:167], v[120:123]
	v_mfma_f32_16x16x32_bf16 v[100:103], v[116:119], v[180:183], v[100:103]
	v_mfma_f32_16x16x32_bf16 v[92:95], v[140:143], v[180:183], v[92:95]
	v_mfma_f32_16x16x32_bf16 v[76:79], v[116:119], v[188:191], v[76:79]
	v_mfma_f32_16x16x32_bf16 v[68:71], v[140:143], v[188:191], v[68:71]
	s_barrier
	s_add_i32 s78, s94, s2
	v_lshl_add_u64 v[192:193], v[192:193], 0, s[30:31]
	s_mov_b32 m0, s78
	ds_read_b128 v[152:155], v240 offset:49152
	ds_read_b128 v[156:159], v240 offset:50176
	ds_read_b128 v[160:163], v240 offset:51200
	ds_read_b128 v[164:167], v240 offset:52224
	ds_read_b128 v[168:171], v240 offset:53248
	ds_read_b128 v[180:183], v240 offset:54272
	ds_read_b128 v[184:187], v240 offset:55296
	ds_read_b128 v[188:191], v240 offset:56320
	global_load_lds_dwordx4 v[192:193], off
	s_add_i32 m0, s78, 0x2000
	s_add_u32 s78, s84, 0x160080
	v_lshl_add_u64 v[192:193], v[194:195], 0, s[30:31]
	s_addc_u32 s79, s85, 0
	s_add_i32 s84, vcc_hi, s2
	global_load_lds_dwordx4 v[192:193], off
	v_lshl_add_u64 v[192:193], s[78:79], 0, v[216:217]
	s_mov_b32 m0, s84
	s_nop 0
	global_load_lds_dwordx4 v[192:193], off
	v_lshl_add_u64 v[192:193], s[78:79], 0, v[228:229]
	s_add_i32 m0, s84, 0x2000
	s_nop 0
	global_load_lds_dwordx4 v[192:193], off
	v_lshl_add_u64 v[192:193], v[196:197], 0, s[30:31]
	s_mov_b32 m0, s60
	s_nop 0
	global_load_lds_dwordx4 v[192:193], off
	v_lshl_add_u64 v[192:193], v[198:199], 0, s[30:31]
	s_mov_b32 m0, s61
	s_nop 0
	global_load_lds_dwordx4 v[192:193], off
	s_waitcnt vmcnt(8)
	s_waitcnt lgkmcnt(0)
	s_barrier
	s_waitcnt lgkmcnt(0)
	v_mfma_f32_16x16x32_bf16 v[60:63], v[64:67], v[152:155], v[60:63]
	v_mfma_f32_16x16x32_bf16 v[56:59], v[88:91], v[152:155], v[56:59]
	v_mfma_f32_16x16x32_bf16 v[44:47], v[64:67], v[160:163], v[44:47]
	v_mfma_f32_16x16x32_bf16 v[40:43], v[88:91], v[160:163], v[40:43]
	v_mfma_f32_16x16x32_bf16 v[28:31], v[64:67], v[168:171], v[28:31]
	v_mfma_f32_16x16x32_bf16 v[24:27], v[88:91], v[168:171], v[24:27]
	v_mfma_f32_16x16x32_bf16 v[12:15], v[64:67], v[184:187], v[12:15]
	v_mfma_f32_16x16x32_bf16 v[8:11], v[88:91], v[184:187], v[8:11]
	v_mfma_f32_16x16x32_bf16 v[60:63], v[72:75], v[156:159], v[60:63]
	v_mfma_f32_16x16x32_bf16 v[56:59], v[96:99], v[156:159], v[56:59]
	v_mfma_f32_16x16x32_bf16 v[44:47], v[72:75], v[164:167], v[44:47]
	v_mfma_f32_16x16x32_bf16 v[40:43], v[96:99], v[164:167], v[40:43]
	v_mfma_f32_16x16x32_bf16 v[28:31], v[72:75], v[180:183], v[28:31]
	v_mfma_f32_16x16x32_bf16 v[24:27], v[96:99], v[180:183], v[24:27]
	v_mfma_f32_16x16x32_bf16 v[12:15], v[72:75], v[188:191], v[12:15]
	v_mfma_f32_16x16x32_bf16 v[8:11], v[96:99], v[188:191], v[8:11]
	v_mfma_f32_16x16x32_bf16 v[52:55], v[108:111], v[152:155], v[52:55]
	v_mfma_f32_16x16x32_bf16 v[48:51], v[128:131], v[152:155], v[48:51]
	v_mfma_f32_16x16x32_bf16 v[36:39], v[108:111], v[160:163], v[36:39]
	v_mfma_f32_16x16x32_bf16 v[32:35], v[128:131], v[160:163], v[32:35]
	v_mfma_f32_16x16x32_bf16 v[20:23], v[108:111], v[168:171], v[20:23]
	v_mfma_f32_16x16x32_bf16 v[16:19], v[128:131], v[168:171], v[16:19]
	v_mfma_f32_16x16x32_bf16 v[4:7], v[108:111], v[184:187], v[4:7]
	v_mfma_f32_16x16x32_bf16 v[0:3], v[128:131], v[184:187], v[0:3]
	v_mfma_f32_16x16x32_bf16 v[52:55], v[116:119], v[156:159], v[52:55]
	v_mfma_f32_16x16x32_bf16 v[48:51], v[140:143], v[156:159], v[48:51]
	v_mfma_f32_16x16x32_bf16 v[36:39], v[116:119], v[164:167], v[36:39]
	v_mfma_f32_16x16x32_bf16 v[32:35], v[140:143], v[164:167], v[32:35]
	v_mfma_f32_16x16x32_bf16 v[20:23], v[116:119], v[180:183], v[20:23]
	v_mfma_f32_16x16x32_bf16 v[16:19], v[140:143], v[180:183], v[16:19]
	v_mfma_f32_16x16x32_bf16 v[4:7], v[116:119], v[188:191], v[4:7]
	v_mfma_f32_16x16x32_bf16 v[0:3], v[140:143], v[188:191], v[0:3]
	s_barrier
	s_add_i32 vcc_lo, vcc_lo, 2
	s_add_u32 s81, s81, 0x100
	s_addc_u32 s96, s96, 0
	s_cmpk_gt_u32 vcc_lo, 0x55
	s_mov_b64 s[78:79], s[82:83]
	s_cbranch_scc0 .LBB0_1290
	s_and_b64 vcc, exec, s[70:71]
	s_cbranch_vccz .LBB0_1293
	s_barrier
